# v39 + all seven GEMM K-loops: LDS-DMA in SGPR-base form (no 64-bit address VALU), B-fragment ds_reads with immediate offsets (no VALU in load segments)
# speedup vs baseline: 1.0242x; 1.0079x over previous
.LBB0_495:
	s_ashr_i32 s13, s12, 31
	s_lshl_b64 s[14:15], s[12:13], 19
	v_readlane_b32 s16, v244, 44
	v_readlane_b32 s17, v244, 45
	s_add_u32 s14, s16, s14
	s_addc_u32 s15, s17, s15
	s_and_b64 s[40:41], s[6:7], exec
	s_cselect_b32 s13, s15, s57
	s_cselect_b32 s81, s14, s56
	s_ashr_i32 s11, s10, 31
	s_lshl_b64 s[40:41], s[10:11], 19
	s_add_u32 s40, s38, s40
	s_addc_u32 s41, s39, s41
	s_and_b64 s[42:43], s[6:7], exec
	s_cselect_b32 s11, s41, s59
	s_cselect_b32 s82, s40, s58
	s_lshl_b32 s42, s80, 10
	s_lshl_b32 s60, s12, 8
	s_add_i32 s83, s42, 0
	s_ashr_i32 s61, s60, 31
	s_add_i32 s83, s83, 0x20800
	s_add_u32 s56, s56, 0x40080
	s_addc_u32 s57, s57, 0
	s_add_u32 s84, s58, 0x100
	v_add_u32_e32 v245, 0x10000, v156
	v_add_u32_e32 v246, 0x10000, v157
	s_mov_b32 s100, 1
	s_addc_u32 s85, s59, 0
	s_mov_b32 s86, -2
	v_lshl_add_u64 v[148:149], s[60:61], 2, v[132:133]
	s_branch .LBB0_497
.LBB0_496:
	s_cmp_lg_u32 s100, 0
	s_cbranch_scc1 .Lpeel_0
	ds_read_b128 v[150:153], v245
	ds_read_b128 v[162:165], v246
	ds_read_b128 v[166:169], v245 offset:2048
	ds_read_b128 v[170:173], v246 offset:2048
	ds_read_b128 v[174:177], v245 offset:16384
	ds_read_b128 v[178:181], v246 offset:16384
	ds_read_b128 v[182:185], v245 offset:18432
	ds_read_b128 v[186:189], v246 offset:18432
	s_add_u32 s44, s56, 0xfffc0080
	s_addc_u32 s45, s57, -1
	s_and_b64 s[42:43], s[58:59], exec
	s_cselect_b32 s61, s13, s45
	s_cselect_b32 s60, s81, s44
	s_cselect_b32 s59, s11, s85
	s_cselect_b32 s58, s82, s84
	s_add_i32 m0, s62, 0xc000
	ds_read_b128 v[190:193], v158
	ds_read_b128 v[194:197], v158 offset:2048
	ds_read_b128 v[198:201], v159
	ds_read_b128 v[202:205], v159 offset:2048
	ds_read_b128 v[206:209], v158 offset:4096
	ds_read_b128 v[210:213], v158 offset:6144
	ds_read_b128 v[214:217], v159 offset:4096
	ds_read_b128 v[218:221], v159 offset:6144
	global_load_lds_dwordx4 v140, s[56:57]
	s_add_i32 m0, s62, 0xe000
	s_nop 0
	global_load_lds_dwordx4 v142, s[56:57]
	s_waitcnt vmcnt(8)
	s_waitcnt lgkmcnt(0)
	s_barrier
	s_setprio 1
	s_waitcnt lgkmcnt(0)
	v_mfma_f32_16x16x32_bf16 v[126:129], v[150:153], v[190:193], v[126:129]
	v_mfma_f32_16x16x32_bf16 v[118:121], v[166:169], v[190:193], v[118:121]
	v_mfma_f32_16x16x32_bf16 v[110:113], v[150:153], v[194:197], v[110:113]
	v_mfma_f32_16x16x32_bf16 v[102:105], v[166:169], v[194:197], v[102:105]
	v_mfma_f32_16x16x32_bf16 v[94:97], v[150:153], v[206:209], v[94:97]
	v_mfma_f32_16x16x32_bf16 v[86:89], v[166:169], v[206:209], v[86:89]
	v_mfma_f32_16x16x32_bf16 v[78:81], v[150:153], v[210:213], v[78:81]
	v_mfma_f32_16x16x32_bf16 v[70:73], v[166:169], v[210:213], v[70:73]
	v_mfma_f32_16x16x32_bf16 v[126:129], v[162:165], v[198:201], v[126:129]
	v_mfma_f32_16x16x32_bf16 v[118:121], v[170:173], v[198:201], v[118:121]
	v_mfma_f32_16x16x32_bf16 v[110:113], v[162:165], v[202:205], v[110:113]
	v_mfma_f32_16x16x32_bf16 v[102:105], v[170:173], v[202:205], v[102:105]
	v_mfma_f32_16x16x32_bf16 v[94:97], v[162:165], v[214:217], v[94:97]
	v_mfma_f32_16x16x32_bf16 v[86:89], v[170:173], v[214:217], v[86:89]
	v_mfma_f32_16x16x32_bf16 v[78:81], v[162:165], v[218:221], v[78:81]
	v_mfma_f32_16x16x32_bf16 v[70:73], v[170:173], v[218:221], v[70:73]
	s_setprio 0
	s_setprio 1
	v_mfma_f32_16x16x32_bf16 v[122:125], v[174:177], v[190:193], v[122:125]
	v_mfma_f32_16x16x32_bf16 v[114:117], v[182:185], v[190:193], v[114:117]
	v_mfma_f32_16x16x32_bf16 v[106:109], v[174:177], v[194:197], v[106:109]
	v_mfma_f32_16x16x32_bf16 v[98:101], v[182:185], v[194:197], v[98:101]
	v_mfma_f32_16x16x32_bf16 v[90:93], v[174:177], v[206:209], v[90:93]
	v_mfma_f32_16x16x32_bf16 v[82:85], v[182:185], v[206:209], v[82:85]
	v_mfma_f32_16x16x32_bf16 v[74:77], v[174:177], v[210:213], v[74:77]
	v_mfma_f32_16x16x32_bf16 v[66:69], v[182:185], v[210:213], v[66:69]
	v_mfma_f32_16x16x32_bf16 v[122:125], v[178:181], v[198:201], v[122:125]
	v_mfma_f32_16x16x32_bf16 v[114:117], v[186:189], v[198:201], v[114:117]
	v_mfma_f32_16x16x32_bf16 v[106:109], v[178:181], v[202:205], v[106:109]
	v_mfma_f32_16x16x32_bf16 v[98:101], v[186:189], v[202:205], v[98:101]
	v_mfma_f32_16x16x32_bf16 v[90:93], v[178:181], v[214:217], v[90:93]
	v_mfma_f32_16x16x32_bf16 v[82:85], v[186:189], v[214:217], v[82:85]
	v_mfma_f32_16x16x32_bf16 v[74:77], v[178:181], v[218:221], v[74:77]
	v_mfma_f32_16x16x32_bf16 v[66:69], v[186:189], v[218:221], v[66:69]
	s_setprio 0
	s_barrier
	s_add_i32 s42, s72, s55
	s_mov_b32 m0, s42
	ds_read_b128 v[190:193], v158 offset:16384
	ds_read_b128 v[194:197], v158 offset:18432
	ds_read_b128 v[198:201], v159 offset:16384
	ds_read_b128 v[202:205], v159 offset:18432
	ds_read_b128 v[206:209], v158 offset:20480
	ds_read_b128 v[210:213], v158 offset:22528
	ds_read_b128 v[214:217], v159 offset:20480
	ds_read_b128 v[218:221], v159 offset:22528
	global_load_lds_dwordx4 v130, s[58:59]
	s_add_i32 m0, s42, 0x2000
	s_add_u32 s42, s58, 0x40000
	s_addc_u32 s43, s59, 0
	s_add_i32 s44, s74, s55
	global_load_lds_dwordx4 v138, s[58:59]
	s_mov_b32 m0, s44
	s_nop 0
	global_load_lds_dwordx4 v130, s[42:43]
	s_add_i32 m0, s44, 0x2000
	s_nop 0
	global_load_lds_dwordx4 v138, s[42:43]
	s_mov_b32 m0, s62
	s_nop 0
	global_load_lds_dwordx4 v134, s[60:61]
	s_mov_b32 m0, s63
	s_nop 0
	global_load_lds_dwordx4 v136, s[60:61]
	s_waitcnt vmcnt(8)
	s_waitcnt lgkmcnt(0)
	s_barrier
	s_setprio 1
	s_waitcnt lgkmcnt(0)
	v_mfma_f32_16x16x32_bf16 v[62:65], v[150:153], v[190:193], v[62:65]
	v_mfma_f32_16x16x32_bf16 v[54:57], v[166:169], v[190:193], v[54:57]
	v_mfma_f32_16x16x32_bf16 v[46:49], v[150:153], v[194:197], v[46:49]
	v_mfma_f32_16x16x32_bf16 v[38:41], v[166:169], v[194:197], v[38:41]
	v_mfma_f32_16x16x32_bf16 v[30:33], v[150:153], v[206:209], v[30:33]
	v_mfma_f32_16x16x32_bf16 v[22:25], v[166:169], v[206:209], v[22:25]
	v_mfma_f32_16x16x32_bf16 v[14:17], v[150:153], v[210:213], v[14:17]
	v_mfma_f32_16x16x32_bf16 v[6:9], v[166:169], v[210:213], v[6:9]
	v_mfma_f32_16x16x32_bf16 v[62:65], v[162:165], v[198:201], v[62:65]
	v_mfma_f32_16x16x32_bf16 v[54:57], v[170:173], v[198:201], v[54:57]
	v_mfma_f32_16x16x32_bf16 v[46:49], v[162:165], v[202:205], v[46:49]
	v_mfma_f32_16x16x32_bf16 v[38:41], v[170:173], v[202:205], v[38:41]
	v_mfma_f32_16x16x32_bf16 v[30:33], v[162:165], v[214:217], v[30:33]
	v_mfma_f32_16x16x32_bf16 v[22:25], v[170:173], v[214:217], v[22:25]
	v_mfma_f32_16x16x32_bf16 v[14:17], v[162:165], v[218:221], v[14:17]
	v_mfma_f32_16x16x32_bf16 v[6:9], v[170:173], v[218:221], v[6:9]
	s_setprio 0
	s_setprio 1
	v_mfma_f32_16x16x32_bf16 v[58:61], v[174:177], v[190:193], v[58:61]
	v_mfma_f32_16x16x32_bf16 v[50:53], v[182:185], v[190:193], v[50:53]
	v_mfma_f32_16x16x32_bf16 v[42:45], v[174:177], v[194:197], v[42:45]
	v_mfma_f32_16x16x32_bf16 v[34:37], v[182:185], v[194:197], v[34:37]
	v_mfma_f32_16x16x32_bf16 v[26:29], v[174:177], v[206:209], v[26:29]
	v_mfma_f32_16x16x32_bf16 v[18:21], v[182:185], v[206:209], v[18:21]
	v_mfma_f32_16x16x32_bf16 v[10:13], v[174:177], v[210:213], v[10:13]
	v_mfma_f32_16x16x32_bf16 v[2:5], v[182:185], v[210:213], v[2:5]
	v_mfma_f32_16x16x32_bf16 v[58:61], v[178:181], v[198:201], v[58:61]
	v_mfma_f32_16x16x32_bf16 v[50:53], v[186:189], v[198:201], v[50:53]
	v_mfma_f32_16x16x32_bf16 v[42:45], v[178:181], v[202:205], v[42:45]
	v_mfma_f32_16x16x32_bf16 v[34:37], v[186:189], v[202:205], v[34:37]
	v_mfma_f32_16x16x32_bf16 v[26:29], v[178:181], v[214:217], v[26:29]
	v_mfma_f32_16x16x32_bf16 v[18:21], v[186:189], v[214:217], v[18:21]
	v_mfma_f32_16x16x32_bf16 v[10:13], v[178:181], v[218:221], v[10:13]
	v_mfma_f32_16x16x32_bf16 v[2:5], v[186:189], v[218:221], v[2:5]
	s_setprio 0
	s_barrier
	s_add_i32 s44, 0, 0x18000
	ds_read_b128 v[150:153], v245 offset:32768
	ds_read_b128 v[162:165], v246 offset:32768
	s_add_i32 s45, 0, 0x1c000
	ds_read_b128 v[166:169], v245 offset:34816
	ds_read_b128 v[170:173], v246 offset:34816
	ds_read_b128 v[174:177], v245 offset:49152
	ds_read_b128 v[178:181], v246 offset:49152
	ds_read_b128 v[182:185], v245 offset:51200
	ds_read_b128 v[186:189], v246 offset:51200
	s_add_u32 s42, s60, 0x40000
	s_addc_u32 s43, s61, 0
	s_mov_b32 m0, s64
	ds_read_b128 v[190:193], v158 offset:32768
	ds_read_b128 v[194:197], v158 offset:34816
	ds_read_b128 v[198:201], v159 offset:32768
	ds_read_b128 v[202:205], v159 offset:34816
	ds_read_b128 v[206:209], v158 offset:36864
	ds_read_b128 v[210:213], v158 offset:38912
	ds_read_b128 v[214:217], v159 offset:36864
	ds_read_b128 v[218:221], v159 offset:38912
	global_load_lds_dwordx4 v134, s[42:43]
	s_mov_b32 m0, s65
	s_nop 0
	global_load_lds_dwordx4 v136, s[42:43]
	s_waitcnt vmcnt(8)
	s_waitcnt lgkmcnt(0)
	s_barrier
	s_setprio 1
	s_waitcnt lgkmcnt(0)
	v_mfma_f32_16x16x32_bf16 v[126:129], v[150:153], v[190:193], v[126:129]
	v_mfma_f32_16x16x32_bf16 v[118:121], v[166:169], v[190:193], v[118:121]
	v_mfma_f32_16x16x32_bf16 v[110:113], v[150:153], v[194:197], v[110:113]
	v_mfma_f32_16x16x32_bf16 v[102:105], v[166:169], v[194:197], v[102:105]
	v_mfma_f32_16x16x32_bf16 v[94:97], v[150:153], v[206:209], v[94:97]
	v_mfma_f32_16x16x32_bf16 v[86:89], v[166:169], v[206:209], v[86:89]
	v_mfma_f32_16x16x32_bf16 v[78:81], v[150:153], v[210:213], v[78:81]
	v_mfma_f32_16x16x32_bf16 v[70:73], v[166:169], v[210:213], v[70:73]
	v_mfma_f32_16x16x32_bf16 v[126:129], v[162:165], v[198:201], v[126:129]
	v_mfma_f32_16x16x32_bf16 v[118:121], v[170:173], v[198:201], v[118:121]
	v_mfma_f32_16x16x32_bf16 v[110:113], v[162:165], v[202:205], v[110:113]
	v_mfma_f32_16x16x32_bf16 v[102:105], v[170:173], v[202:205], v[102:105]
	v_mfma_f32_16x16x32_bf16 v[94:97], v[162:165], v[214:217], v[94:97]
	v_mfma_f32_16x16x32_bf16 v[86:89], v[170:173], v[214:217], v[86:89]
	v_mfma_f32_16x16x32_bf16 v[78:81], v[162:165], v[218:221], v[78:81]
	v_mfma_f32_16x16x32_bf16 v[70:73], v[170:173], v[218:221], v[70:73]
	s_setprio 0
	s_setprio 1
	v_mfma_f32_16x16x32_bf16 v[122:125], v[174:177], v[190:193], v[122:125]
	v_mfma_f32_16x16x32_bf16 v[114:117], v[182:185], v[190:193], v[114:117]
	v_mfma_f32_16x16x32_bf16 v[106:109], v[174:177], v[194:197], v[106:109]
	v_mfma_f32_16x16x32_bf16 v[98:101], v[182:185], v[194:197], v[98:101]
	v_mfma_f32_16x16x32_bf16 v[90:93], v[174:177], v[206:209], v[90:93]
	v_mfma_f32_16x16x32_bf16 v[82:85], v[182:185], v[206:209], v[82:85]
	v_mfma_f32_16x16x32_bf16 v[74:77], v[174:177], v[210:213], v[74:77]
	v_mfma_f32_16x16x32_bf16 v[66:69], v[182:185], v[210:213], v[66:69]
	v_mfma_f32_16x16x32_bf16 v[122:125], v[178:181], v[198:201], v[122:125]
	v_mfma_f32_16x16x32_bf16 v[114:117], v[186:189], v[198:201], v[114:117]
	v_mfma_f32_16x16x32_bf16 v[106:109], v[178:181], v[202:205], v[106:109]
	v_mfma_f32_16x16x32_bf16 v[98:101], v[186:189], v[202:205], v[98:101]
	v_mfma_f32_16x16x32_bf16 v[90:93], v[178:181], v[214:217], v[90:93]
	v_mfma_f32_16x16x32_bf16 v[82:85], v[186:189], v[214:217], v[82:85]
	v_mfma_f32_16x16x32_bf16 v[74:77], v[178:181], v[218:221], v[74:77]
	v_mfma_f32_16x16x32_bf16 v[66:69], v[186:189], v[218:221], v[66:69]
	s_setprio 0
	s_barrier
	s_add_i32 s42, s44, s55
	s_add_i32 m0, s42, 0xffffff80
	ds_read_b128 v[190:193], v158 offset:49152
	ds_read_b128 v[194:197], v158 offset:51200
	ds_read_b128 v[198:201], v159 offset:49152
	ds_read_b128 v[202:205], v159 offset:51200
	ds_read_b128 v[206:209], v158 offset:53248
	ds_read_b128 v[210:213], v158 offset:55296
	ds_read_b128 v[214:217], v159 offset:53248
	ds_read_b128 v[218:221], v159 offset:55296
	global_load_lds_dwordx4 v130, s[58:59] offset:128
	s_add_i32 m0, s42, 0x1f80
	s_add_u32 s42, s58, 0x40080
	s_addc_u32 s43, s59, 0
	s_add_i32 s44, s45, s55
	global_load_lds_dwordx4 v138, s[58:59] offset:128
	s_mov_b32 m0, s44
	s_nop 0
	global_load_lds_dwordx4 v130, s[42:43]
	s_add_i32 m0, s44, 0x2000
	s_nop 0
	global_load_lds_dwordx4 v138, s[42:43]
	s_add_i32 m0, s69, 0xffffff80
	s_nop 0
	global_load_lds_dwordx4 v134, s[60:61] offset:128
	s_add_i32 m0, s70, 0xffffff80
	s_nop 0
	global_load_lds_dwordx4 v136, s[60:61] offset:128
	s_waitcnt vmcnt(8)
	s_waitcnt lgkmcnt(0)
	s_barrier
	s_setprio 1
	s_waitcnt lgkmcnt(0)
	v_mfma_f32_16x16x32_bf16 v[62:65], v[150:153], v[190:193], v[62:65]
	v_mfma_f32_16x16x32_bf16 v[54:57], v[166:169], v[190:193], v[54:57]
	v_mfma_f32_16x16x32_bf16 v[46:49], v[150:153], v[194:197], v[46:49]
	v_mfma_f32_16x16x32_bf16 v[38:41], v[166:169], v[194:197], v[38:41]
	v_mfma_f32_16x16x32_bf16 v[30:33], v[150:153], v[206:209], v[30:33]
	v_mfma_f32_16x16x32_bf16 v[22:25], v[166:169], v[206:209], v[22:25]
	v_mfma_f32_16x16x32_bf16 v[14:17], v[150:153], v[210:213], v[14:17]
	v_mfma_f32_16x16x32_bf16 v[6:9], v[166:169], v[210:213], v[6:9]
	v_mfma_f32_16x16x32_bf16 v[62:65], v[162:165], v[198:201], v[62:65]
	v_mfma_f32_16x16x32_bf16 v[54:57], v[170:173], v[198:201], v[54:57]
	v_mfma_f32_16x16x32_bf16 v[46:49], v[162:165], v[202:205], v[46:49]
	v_mfma_f32_16x16x32_bf16 v[38:41], v[170:173], v[202:205], v[38:41]
	v_mfma_f32_16x16x32_bf16 v[30:33], v[162:165], v[214:217], v[30:33]
	v_mfma_f32_16x16x32_bf16 v[22:25], v[170:173], v[214:217], v[22:25]
	v_mfma_f32_16x16x32_bf16 v[14:17], v[162:165], v[218:221], v[14:17]
	v_mfma_f32_16x16x32_bf16 v[6:9], v[170:173], v[218:221], v[6:9]
	s_setprio 0
	s_setprio 1
	v_mfma_f32_16x16x32_bf16 v[58:61], v[174:177], v[190:193], v[58:61]
	v_mfma_f32_16x16x32_bf16 v[50:53], v[182:185], v[190:193], v[50:53]
	v_mfma_f32_16x16x32_bf16 v[42:45], v[174:177], v[194:197], v[42:45]
	v_mfma_f32_16x16x32_bf16 v[34:37], v[182:185], v[194:197], v[34:37]
	v_mfma_f32_16x16x32_bf16 v[26:29], v[174:177], v[206:209], v[26:29]
	v_mfma_f32_16x16x32_bf16 v[18:21], v[182:185], v[206:209], v[18:21]
	v_mfma_f32_16x16x32_bf16 v[10:13], v[174:177], v[210:213], v[10:13]
	v_mfma_f32_16x16x32_bf16 v[2:5], v[182:185], v[210:213], v[2:5]
	v_mfma_f32_16x16x32_bf16 v[58:61], v[178:181], v[198:201], v[58:61]
	v_mfma_f32_16x16x32_bf16 v[50:53], v[186:189], v[198:201], v[50:53]
	v_mfma_f32_16x16x32_bf16 v[42:45], v[178:181], v[202:205], v[42:45]
	v_mfma_f32_16x16x32_bf16 v[34:37], v[186:189], v[202:205], v[34:37]
	v_mfma_f32_16x16x32_bf16 v[26:29], v[178:181], v[214:217], v[26:29]
	v_mfma_f32_16x16x32_bf16 v[18:21], v[186:189], v[214:217], v[18:21]
	v_mfma_f32_16x16x32_bf16 v[10:13], v[178:181], v[218:221], v[10:13]
	v_mfma_f32_16x16x32_bf16 v[2:5], v[186:189], v[218:221], v[2:5]
	s_setprio 0
	s_barrier
	s_add_i32 s86, s86, 2
	s_add_u32 s56, s56, 0x100
	s_addc_u32 s57, s57, 0
	s_add_u32 s84, s84, 0x100
	s_addc_u32 s85, s85, 0
	s_cmp_gt_u32 s86, 13
	s_cbranch_scc1 .LBB0_500

.Lpeel_0:
	s_mov_b32 s100, 0
	ds_read_b128 v[150:153], v245
	ds_read_b128 v[162:165], v246
	ds_read_b128 v[166:169], v245 offset:2048
	ds_read_b128 v[170:173], v246 offset:2048
	ds_read_b128 v[174:177], v245 offset:16384
	ds_read_b128 v[178:181], v246 offset:16384
	ds_read_b128 v[182:185], v245 offset:18432
	ds_read_b128 v[186:189], v246 offset:18432
	s_add_u32 s44, s56, 0xfffc0080
	s_addc_u32 s45, s57, -1
	s_and_b64 s[42:43], s[58:59], exec
	s_cselect_b32 s61, s13, s45
	s_cselect_b32 s60, s81, s44
	s_cselect_b32 s59, s11, s85
	s_cselect_b32 s58, s82, s84
	s_add_i32 m0, s62, 0xc000
	ds_read_b128 v[190:193], v158
	ds_read_b128 v[194:197], v158 offset:2048
	ds_read_b128 v[198:201], v159
	ds_read_b128 v[202:205], v159 offset:2048
	ds_read_b128 v[206:209], v158 offset:4096
	ds_read_b128 v[210:213], v158 offset:6144
	ds_read_b128 v[214:217], v159 offset:4096
	ds_read_b128 v[218:221], v159 offset:6144
	global_load_lds_dwordx4 v140, s[56:57]
	s_add_i32 m0, s62, 0xe000
	s_nop 0
	global_load_lds_dwordx4 v142, s[56:57]
	s_waitcnt vmcnt(8)
	s_waitcnt lgkmcnt(0)
	s_barrier
	s_setprio 1
	s_waitcnt lgkmcnt(0)
	v_mfma_f32_16x16x32_bf16 v[126:129], v[150:153], v[190:193], 0
	v_mfma_f32_16x16x32_bf16 v[118:121], v[166:169], v[190:193], 0
	v_mfma_f32_16x16x32_bf16 v[110:113], v[150:153], v[194:197], 0
	v_mfma_f32_16x16x32_bf16 v[102:105], v[166:169], v[194:197], 0
	v_mfma_f32_16x16x32_bf16 v[94:97], v[150:153], v[206:209], 0
	v_mfma_f32_16x16x32_bf16 v[86:89], v[166:169], v[206:209], 0
	v_mfma_f32_16x16x32_bf16 v[78:81], v[150:153], v[210:213], 0
	v_mfma_f32_16x16x32_bf16 v[70:73], v[166:169], v[210:213], 0
	v_mfma_f32_16x16x32_bf16 v[126:129], v[162:165], v[198:201], v[126:129]
	v_mfma_f32_16x16x32_bf16 v[118:121], v[170:173], v[198:201], v[118:121]
	v_mfma_f32_16x16x32_bf16 v[110:113], v[162:165], v[202:205], v[110:113]
	v_mfma_f32_16x16x32_bf16 v[102:105], v[170:173], v[202:205], v[102:105]
	v_mfma_f32_16x16x32_bf16 v[94:97], v[162:165], v[214:217], v[94:97]
	v_mfma_f32_16x16x32_bf16 v[86:89], v[170:173], v[214:217], v[86:89]
	v_mfma_f32_16x16x32_bf16 v[78:81], v[162:165], v[218:221], v[78:81]
	v_mfma_f32_16x16x32_bf16 v[70:73], v[170:173], v[218:221], v[70:73]
	s_setprio 0
	s_setprio 1
	v_mfma_f32_16x16x32_bf16 v[122:125], v[174:177], v[190:193], 0
	v_mfma_f32_16x16x32_bf16 v[114:117], v[182:185], v[190:193], 0
	v_mfma_f32_16x16x32_bf16 v[106:109], v[174:177], v[194:197], 0
	v_mfma_f32_16x16x32_bf16 v[98:101], v[182:185], v[194:197], 0
	v_mfma_f32_16x16x32_bf16 v[90:93], v[174:177], v[206:209], 0
	v_mfma_f32_16x16x32_bf16 v[82:85], v[182:185], v[206:209], 0
	v_mfma_f32_16x16x32_bf16 v[74:77], v[174:177], v[210:213], 0
	v_mfma_f32_16x16x32_bf16 v[66:69], v[182:185], v[210:213], 0
	v_mfma_f32_16x16x32_bf16 v[122:125], v[178:181], v[198:201], v[122:125]
	v_mfma_f32_16x16x32_bf16 v[114:117], v[186:189], v[198:201], v[114:117]
	v_mfma_f32_16x16x32_bf16 v[106:109], v[178:181], v[202:205], v[106:109]
	v_mfma_f32_16x16x32_bf16 v[98:101], v[186:189], v[202:205], v[98:101]
	v_mfma_f32_16x16x32_bf16 v[90:93], v[178:181], v[214:217], v[90:93]
	v_mfma_f32_16x16x32_bf16 v[82:85], v[186:189], v[214:217], v[82:85]
	v_mfma_f32_16x16x32_bf16 v[74:77], v[178:181], v[218:221], v[74:77]
	v_mfma_f32_16x16x32_bf16 v[66:69], v[186:189], v[218:221], v[66:69]
	s_setprio 0
	s_barrier
	s_add_i32 s42, s72, s55
	s_mov_b32 m0, s42
	ds_read_b128 v[190:193], v158 offset:16384
	ds_read_b128 v[194:197], v158 offset:18432
	ds_read_b128 v[198:201], v159 offset:16384
	ds_read_b128 v[202:205], v159 offset:18432
	ds_read_b128 v[206:209], v158 offset:20480
	ds_read_b128 v[210:213], v158 offset:22528
	ds_read_b128 v[214:217], v159 offset:20480
	ds_read_b128 v[218:221], v159 offset:22528
	global_load_lds_dwordx4 v130, s[58:59]
	s_add_i32 m0, s42, 0x2000
	s_add_u32 s42, s58, 0x40000
	s_addc_u32 s43, s59, 0
	s_add_i32 s44, s74, s55
	global_load_lds_dwordx4 v138, s[58:59]
	s_mov_b32 m0, s44
	s_nop 0
	global_load_lds_dwordx4 v130, s[42:43]
	s_add_i32 m0, s44, 0x2000
	s_nop 0
	global_load_lds_dwordx4 v138, s[42:43]
	s_mov_b32 m0, s62
	s_nop 0
	global_load_lds_dwordx4 v134, s[60:61]
	s_mov_b32 m0, s63
	s_nop 0
	global_load_lds_dwordx4 v136, s[60:61]
	s_waitcnt vmcnt(8)
	s_waitcnt lgkmcnt(0)
	s_barrier
	s_setprio 1
	s_waitcnt lgkmcnt(0)
	v_mfma_f32_16x16x32_bf16 v[62:65], v[150:153], v[190:193], 0
	v_mfma_f32_16x16x32_bf16 v[54:57], v[166:169], v[190:193], 0
	v_mfma_f32_16x16x32_bf16 v[46:49], v[150:153], v[194:197], 0
	v_mfma_f32_16x16x32_bf16 v[38:41], v[166:169], v[194:197], 0
	v_mfma_f32_16x16x32_bf16 v[30:33], v[150:153], v[206:209], 0
	v_mfma_f32_16x16x32_bf16 v[22:25], v[166:169], v[206:209], 0
	v_mfma_f32_16x16x32_bf16 v[14:17], v[150:153], v[210:213], 0
	v_mfma_f32_16x16x32_bf16 v[6:9], v[166:169], v[210:213], 0
	v_mfma_f32_16x16x32_bf16 v[62:65], v[162:165], v[198:201], v[62:65]
	v_mfma_f32_16x16x32_bf16 v[54:57], v[170:173], v[198:201], v[54:57]
	v_mfma_f32_16x16x32_bf16 v[46:49], v[162:165], v[202:205], v[46:49]
	v_mfma_f32_16x16x32_bf16 v[38:41], v[170:173], v[202:205], v[38:41]
	v_mfma_f32_16x16x32_bf16 v[30:33], v[162:165], v[214:217], v[30:33]
	v_mfma_f32_16x16x32_bf16 v[22:25], v[170:173], v[214:217], v[22:25]
	v_mfma_f32_16x16x32_bf16 v[14:17], v[162:165], v[218:221], v[14:17]
	v_mfma_f32_16x16x32_bf16 v[6:9], v[170:173], v[218:221], v[6:9]
	s_setprio 0
	s_setprio 1
	v_mfma_f32_16x16x32_bf16 v[58:61], v[174:177], v[190:193], 0
	v_mfma_f32_16x16x32_bf16 v[50:53], v[182:185], v[190:193], 0
	v_mfma_f32_16x16x32_bf16 v[42:45], v[174:177], v[194:197], 0
	v_mfma_f32_16x16x32_bf16 v[34:37], v[182:185], v[194:197], 0
	v_mfma_f32_16x16x32_bf16 v[26:29], v[174:177], v[206:209], 0
	v_mfma_f32_16x16x32_bf16 v[18:21], v[182:185], v[206:209], 0
	v_mfma_f32_16x16x32_bf16 v[10:13], v[174:177], v[210:213], 0
	v_mfma_f32_16x16x32_bf16 v[2:5], v[182:185], v[210:213], 0
	v_mfma_f32_16x16x32_bf16 v[58:61], v[178:181], v[198:201], v[58:61]
	v_mfma_f32_16x16x32_bf16 v[50:53], v[186:189], v[198:201], v[50:53]
	v_mfma_f32_16x16x32_bf16 v[42:45], v[178:181], v[202:205], v[42:45]
	v_mfma_f32_16x16x32_bf16 v[34:37], v[186:189], v[202:205], v[34:37]
	v_mfma_f32_16x16x32_bf16 v[26:29], v[178:181], v[214:217], v[26:29]
	v_mfma_f32_16x16x32_bf16 v[18:21], v[186:189], v[214:217], v[18:21]
	v_mfma_f32_16x16x32_bf16 v[10:13], v[178:181], v[218:221], v[10:13]
	v_mfma_f32_16x16x32_bf16 v[2:5], v[186:189], v[218:221], v[2:5]
	s_setprio 0
	s_barrier
	s_add_i32 s44, 0, 0x18000
	ds_read_b128 v[150:153], v245 offset:32768
	ds_read_b128 v[162:165], v246 offset:32768
	s_add_i32 s45, 0, 0x1c000
	ds_read_b128 v[166:169], v245 offset:34816
	ds_read_b128 v[170:173], v246 offset:34816
	ds_read_b128 v[174:177], v245 offset:49152
	ds_read_b128 v[178:181], v246 offset:49152
	ds_read_b128 v[182:185], v245 offset:51200
	ds_read_b128 v[186:189], v246 offset:51200
	s_add_u32 s42, s60, 0x40000
	s_addc_u32 s43, s61, 0
	s_mov_b32 m0, s64
	ds_read_b128 v[190:193], v158 offset:32768
	ds_read_b128 v[194:197], v158 offset:34816
	ds_read_b128 v[198:201], v159 offset:32768
	ds_read_b128 v[202:205], v159 offset:34816
	ds_read_b128 v[206:209], v158 offset:36864
	ds_read_b128 v[210:213], v158 offset:38912
	ds_read_b128 v[214:217], v159 offset:36864
	ds_read_b128 v[218:221], v159 offset:38912
	global_load_lds_dwordx4 v134, s[42:43]
	s_mov_b32 m0, s65
	s_nop 0
	global_load_lds_dwordx4 v136, s[42:43]
	s_waitcnt vmcnt(8)
	s_waitcnt lgkmcnt(0)
	s_barrier
	s_setprio 1
	s_waitcnt lgkmcnt(0)
	v_mfma_f32_16x16x32_bf16 v[126:129], v[150:153], v[190:193], v[126:129]
	v_mfma_f32_16x16x32_bf16 v[118:121], v[166:169], v[190:193], v[118:121]
	v_mfma_f32_16x16x32_bf16 v[110:113], v[150:153], v[194:197], v[110:113]
	v_mfma_f32_16x16x32_bf16 v[102:105], v[166:169], v[194:197], v[102:105]
	v_mfma_f32_16x16x32_bf16 v[94:97], v[150:153], v[206:209], v[94:97]
	v_mfma_f32_16x16x32_bf16 v[86:89], v[166:169], v[206:209], v[86:89]
	v_mfma_f32_16x16x32_bf16 v[78:81], v[150:153], v[210:213], v[78:81]
	v_mfma_f32_16x16x32_bf16 v[70:73], v[166:169], v[210:213], v[70:73]
	v_mfma_f32_16x16x32_bf16 v[126:129], v[162:165], v[198:201], v[126:129]
	v_mfma_f32_16x16x32_bf16 v[118:121], v[170:173], v[198:201], v[118:121]
	v_mfma_f32_16x16x32_bf16 v[110:113], v[162:165], v[202:205], v[110:113]
	v_mfma_f32_16x16x32_bf16 v[102:105], v[170:173], v[202:205], v[102:105]
	v_mfma_f32_16x16x32_bf16 v[94:97], v[162:165], v[214:217], v[94:97]
	v_mfma_f32_16x16x32_bf16 v[86:89], v[170:173], v[214:217], v[86:89]
	v_mfma_f32_16x16x32_bf16 v[78:81], v[162:165], v[218:221], v[78:81]
	v_mfma_f32_16x16x32_bf16 v[70:73], v[170:173], v[218:221], v[70:73]
	s_setprio 0
	s_setprio 1
	v_mfma_f32_16x16x32_bf16 v[122:125], v[174:177], v[190:193], v[122:125]
	v_mfma_f32_16x16x32_bf16 v[114:117], v[182:185], v[190:193], v[114:117]
	v_mfma_f32_16x16x32_bf16 v[106:109], v[174:177], v[194:197], v[106:109]
	v_mfma_f32_16x16x32_bf16 v[98:101], v[182:185], v[194:197], v[98:101]
	v_mfma_f32_16x16x32_bf16 v[90:93], v[174:177], v[206:209], v[90:93]
	v_mfma_f32_16x16x32_bf16 v[82:85], v[182:185], v[206:209], v[82:85]
	v_mfma_f32_16x16x32_bf16 v[74:77], v[174:177], v[210:213], v[74:77]
	v_mfma_f32_16x16x32_bf16 v[66:69], v[182:185], v[210:213], v[66:69]
	v_mfma_f32_16x16x32_bf16 v[122:125], v[178:181], v[198:201], v[122:125]
	v_mfma_f32_16x16x32_bf16 v[114:117], v[186:189], v[198:201], v[114:117]
	v_mfma_f32_16x16x32_bf16 v[106:109], v[178:181], v[202:205], v[106:109]
	v_mfma_f32_16x16x32_bf16 v[98:101], v[186:189], v[202:205], v[98:101]
	v_mfma_f32_16x16x32_bf16 v[90:93], v[178:181], v[214:217], v[90:93]
	v_mfma_f32_16x16x32_bf16 v[82:85], v[186:189], v[214:217], v[82:85]
	v_mfma_f32_16x16x32_bf16 v[74:77], v[178:181], v[218:221], v[74:77]
	v_mfma_f32_16x16x32_bf16 v[66:69], v[186:189], v[218:221], v[66:69]
	s_setprio 0
	s_barrier
	s_add_i32 s42, s44, s55
	s_add_i32 m0, s42, 0xffffff80
	ds_read_b128 v[190:193], v158 offset:49152
	ds_read_b128 v[194:197], v158 offset:51200
	ds_read_b128 v[198:201], v159 offset:49152
	ds_read_b128 v[202:205], v159 offset:51200
	ds_read_b128 v[206:209], v158 offset:53248
	ds_read_b128 v[210:213], v158 offset:55296
	ds_read_b128 v[214:217], v159 offset:53248
	ds_read_b128 v[218:221], v159 offset:55296
	global_load_lds_dwordx4 v130, s[58:59] offset:128
	s_add_i32 m0, s42, 0x1f80
	s_add_u32 s42, s58, 0x40080
	s_addc_u32 s43, s59, 0
	s_add_i32 s44, s45, s55
	global_load_lds_dwordx4 v138, s[58:59] offset:128
	s_mov_b32 m0, s44
	s_nop 0
	global_load_lds_dwordx4 v130, s[42:43]
	s_add_i32 m0, s44, 0x2000
	s_nop 0
	global_load_lds_dwordx4 v138, s[42:43]
	s_add_i32 m0, s69, 0xffffff80
	s_nop 0
	global_load_lds_dwordx4 v134, s[60:61] offset:128
	s_add_i32 m0, s70, 0xffffff80
	s_nop 0
	global_load_lds_dwordx4 v136, s[60:61] offset:128
	s_waitcnt vmcnt(8)
	s_waitcnt lgkmcnt(0)
	s_barrier
	s_setprio 1
	s_waitcnt lgkmcnt(0)
	v_mfma_f32_16x16x32_bf16 v[62:65], v[150:153], v[190:193], v[62:65]
	v_mfma_f32_16x16x32_bf16 v[54:57], v[166:169], v[190:193], v[54:57]
	v_mfma_f32_16x16x32_bf16 v[46:49], v[150:153], v[194:197], v[46:49]
	v_mfma_f32_16x16x32_bf16 v[38:41], v[166:169], v[194:197], v[38:41]
	v_mfma_f32_16x16x32_bf16 v[30:33], v[150:153], v[206:209], v[30:33]
	v_mfma_f32_16x16x32_bf16 v[22:25], v[166:169], v[206:209], v[22:25]
	v_mfma_f32_16x16x32_bf16 v[14:17], v[150:153], v[210:213], v[14:17]
	v_mfma_f32_16x16x32_bf16 v[6:9], v[166:169], v[210:213], v[6:9]
	v_mfma_f32_16x16x32_bf16 v[62:65], v[162:165], v[198:201], v[62:65]
	v_mfma_f32_16x16x32_bf16 v[54:57], v[170:173], v[198:201], v[54:57]
	v_mfma_f32_16x16x32_bf16 v[46:49], v[162:165], v[202:205], v[46:49]
	v_mfma_f32_16x16x32_bf16 v[38:41], v[170:173], v[202:205], v[38:41]
	v_mfma_f32_16x16x32_bf16 v[30:33], v[162:165], v[214:217], v[30:33]
	v_mfma_f32_16x16x32_bf16 v[22:25], v[170:173], v[214:217], v[22:25]
	v_mfma_f32_16x16x32_bf16 v[14:17], v[162:165], v[218:221], v[14:17]
	v_mfma_f32_16x16x32_bf16 v[6:9], v[170:173], v[218:221], v[6:9]
	s_setprio 0
	s_setprio 1
	v_mfma_f32_16x16x32_bf16 v[58:61], v[174:177], v[190:193], v[58:61]
	v_mfma_f32_16x16x32_bf16 v[50:53], v[182:185], v[190:193], v[50:53]
	v_mfma_f32_16x16x32_bf16 v[42:45], v[174:177], v[194:197], v[42:45]
	v_mfma_f32_16x16x32_bf16 v[34:37], v[182:185], v[194:197], v[34:37]
	v_mfma_f32_16x16x32_bf16 v[26:29], v[174:177], v[206:209], v[26:29]
	v_mfma_f32_16x16x32_bf16 v[18:21], v[182:185], v[206:209], v[18:21]
	v_mfma_f32_16x16x32_bf16 v[10:13], v[174:177], v[210:213], v[10:13]
	v_mfma_f32_16x16x32_bf16 v[2:5], v[182:185], v[210:213], v[2:5]
	v_mfma_f32_16x16x32_bf16 v[58:61], v[178:181], v[198:201], v[58:61]
	v_mfma_f32_16x16x32_bf16 v[50:53], v[186:189], v[198:201], v[50:53]
	v_mfma_f32_16x16x32_bf16 v[42:45], v[178:181], v[202:205], v[42:45]
	v_mfma_f32_16x16x32_bf16 v[34:37], v[186:189], v[202:205], v[34:37]
	v_mfma_f32_16x16x32_bf16 v[26:29], v[178:181], v[214:217], v[26:29]
	v_mfma_f32_16x16x32_bf16 v[18:21], v[186:189], v[214:217], v[18:21]
	v_mfma_f32_16x16x32_bf16 v[10:13], v[178:181], v[218:221], v[10:13]
	v_mfma_f32_16x16x32_bf16 v[2:5], v[186:189], v[218:221], v[2:5]
	s_setprio 0
	s_barrier
	s_add_i32 s86, s86, 2
	s_add_u32 s56, s56, 0x100
	s_addc_u32 s57, s57, 0
	s_add_u32 s84, s84, 0x100
	s_addc_u32 s85, s85, 0
	s_cmp_gt_u32 s86, 13
	s_cbranch_scc1 .LBB0_500
	s_branch .LBB0_497

.LBB0_588:
	s_add_u32 s40, s40, 0xb0080
	s_addc_u32 s41, s41, 0
	s_add_u32 s42, s52, 0x100
	v_add_u32_e32 v245, 0x10000, v210
	v_add_u32_e32 v246, 0x10000, v211
	s_mov_b32 s100, 1
	s_addc_u32 s43, s53, 0
	s_mov_b32 s44, -2
.LBB0_589:
	s_cmp_lg_u32 s100, 0
	s_cbranch_scc1 .Lpeel_1
	ds_read_b128 v[90:93], v212
	ds_read_b128 v[102:105], v213
	ds_read_b128 v[114:117], v214
	ds_read_b128 v[126:129], v215
	ds_read_b128 v[138:141], v216
	ds_read_b128 v[150:153], v217
	ds_read_b128 v[154:157], v218
	ds_read_b128 v[158:161], v219
	s_add_u32 s45, s40, 0xfff50080
	s_addc_u32 s46, s41, -1
	s_cmp_eq_u32 s44, 40
	s_cselect_b32 s55, s1, s46
	s_cselect_b32 s54, s0, s45
	s_cselect_b32 s53, s15, s43
	s_cselect_b32 s52, s14, s42
	s_add_i32 m0, s56, 0xc000
	ds_read_b128 v[162:165], v220
	ds_read_b128 v[166:169], v220 offset:2048
	ds_read_b128 v[170:173], v221
	ds_read_b128 v[174:177], v221 offset:2048
	ds_read_b128 v[178:181], v220 offset:4096
	ds_read_b128 v[182:185], v220 offset:6144
	ds_read_b128 v[204:207], v221 offset:4096
	ds_read_b128 v[226:229], v221 offset:6144
	global_load_lds_dwordx4 v196, s[40:41]
	s_add_i32 m0, s56, 0xe000
	s_nop 0
	global_load_lds_dwordx4 v198, s[40:41]
	s_waitcnt vmcnt(8)
	s_waitcnt lgkmcnt(0)
	s_barrier
	s_setprio 1
	s_waitcnt lgkmcnt(0)
	v_mfma_f32_16x16x32_bf16 v[146:149], v[90:93], v[162:165], v[146:149]
	v_mfma_f32_16x16x32_bf16 v[142:145], v[114:117], v[162:165], v[142:145]
	v_mfma_f32_16x16x32_bf16 v[122:125], v[90:93], v[166:169], v[122:125]
	v_mfma_f32_16x16x32_bf16 v[118:121], v[114:117], v[166:169], v[118:121]
	v_mfma_f32_16x16x32_bf16 v[98:101], v[90:93], v[178:181], v[98:101]
	v_mfma_f32_16x16x32_bf16 v[94:97], v[114:117], v[178:181], v[94:97]
	v_mfma_f32_16x16x32_bf16 v[78:81], v[90:93], v[182:185], v[78:81]
	v_mfma_f32_16x16x32_bf16 v[74:77], v[114:117], v[182:185], v[74:77]
	v_mfma_f32_16x16x32_bf16 v[146:149], v[102:105], v[170:173], v[146:149]
	v_mfma_f32_16x16x32_bf16 v[142:145], v[126:129], v[170:173], v[142:145]
	v_mfma_f32_16x16x32_bf16 v[122:125], v[102:105], v[174:177], v[122:125]
	v_mfma_f32_16x16x32_bf16 v[118:121], v[126:129], v[174:177], v[118:121]
	v_mfma_f32_16x16x32_bf16 v[98:101], v[102:105], v[204:207], v[98:101]
	v_mfma_f32_16x16x32_bf16 v[94:97], v[126:129], v[204:207], v[94:97]
	v_mfma_f32_16x16x32_bf16 v[78:81], v[102:105], v[226:229], v[78:81]
	v_mfma_f32_16x16x32_bf16 v[74:77], v[126:129], v[226:229], v[74:77]
	s_setprio 0
	s_setprio 1
	v_mfma_f32_16x16x32_bf16 v[134:137], v[138:141], v[162:165], v[134:137]
	v_mfma_f32_16x16x32_bf16 v[130:133], v[154:157], v[162:165], v[130:133]
	v_mfma_f32_16x16x32_bf16 v[110:113], v[138:141], v[166:169], v[110:113]
	v_mfma_f32_16x16x32_bf16 v[106:109], v[154:157], v[166:169], v[106:109]
	v_mfma_f32_16x16x32_bf16 v[86:89], v[138:141], v[178:181], v[86:89]
	v_mfma_f32_16x16x32_bf16 v[82:85], v[154:157], v[178:181], v[82:85]
	v_mfma_f32_16x16x32_bf16 v[70:73], v[138:141], v[182:185], v[70:73]
	v_mfma_f32_16x16x32_bf16 v[66:69], v[154:157], v[182:185], v[66:69]
	v_mfma_f32_16x16x32_bf16 v[134:137], v[150:153], v[170:173], v[134:137]
	v_mfma_f32_16x16x32_bf16 v[130:133], v[158:161], v[170:173], v[130:133]
	v_mfma_f32_16x16x32_bf16 v[110:113], v[150:153], v[174:177], v[110:113]
	v_mfma_f32_16x16x32_bf16 v[106:109], v[158:161], v[174:177], v[106:109]
	v_mfma_f32_16x16x32_bf16 v[86:89], v[150:153], v[204:207], v[86:89]
	v_mfma_f32_16x16x32_bf16 v[82:85], v[158:161], v[204:207], v[82:85]
	v_mfma_f32_16x16x32_bf16 v[70:73], v[150:153], v[226:229], v[70:73]
	v_mfma_f32_16x16x32_bf16 v[66:69], v[158:161], v[226:229], v[66:69]
	s_setprio 0
	s_barrier
	s_add_i32 s45, s68, s39
	s_mov_b32 m0, s45
	ds_read_b128 v[162:165], v220 offset:16384
	ds_read_b128 v[166:169], v220 offset:18432
	ds_read_b128 v[170:173], v221 offset:16384
	ds_read_b128 v[174:177], v221 offset:18432
	ds_read_b128 v[178:181], v220 offset:20480
	ds_read_b128 v[182:185], v220 offset:22528
	ds_read_b128 v[204:207], v221 offset:20480
	ds_read_b128 v[226:229], v221 offset:22528
	global_load_lds_dwordx4 v188, s[52:53]
	s_add_i32 m0, s45, 0x2000
	s_add_u32 s46, s52, 0xb0000
	s_addc_u32 s47, s53, 0
	s_add_i32 s45, s69, s39
	global_load_lds_dwordx4 v192, s[52:53]
	s_mov_b32 m0, s45
	s_nop 0
	global_load_lds_dwordx4 v188, s[46:47]
	s_add_i32 m0, s45, 0x2000
	s_nop 0
	global_load_lds_dwordx4 v192, s[46:47]
	s_mov_b32 m0, s56
	s_nop 0
	global_load_lds_dwordx4 v186, s[54:55]
	s_mov_b32 m0, s57
	s_nop 0
	global_load_lds_dwordx4 v190, s[54:55]
	s_waitcnt vmcnt(8)
	s_waitcnt lgkmcnt(0)
	s_barrier
	s_setprio 1
	s_waitcnt lgkmcnt(0)
	v_mfma_f32_16x16x32_bf16 v[62:65], v[90:93], v[162:165], v[62:65]
	v_mfma_f32_16x16x32_bf16 v[58:61], v[114:117], v[162:165], v[58:61]
	v_mfma_f32_16x16x32_bf16 v[46:49], v[90:93], v[166:169], v[46:49]
	v_mfma_f32_16x16x32_bf16 v[42:45], v[114:117], v[166:169], v[42:45]
	v_mfma_f32_16x16x32_bf16 v[30:33], v[90:93], v[178:181], v[30:33]
	v_mfma_f32_16x16x32_bf16 v[26:29], v[114:117], v[178:181], v[26:29]
	v_mfma_f32_16x16x32_bf16 v[14:17], v[90:93], v[182:185], v[14:17]
	v_mfma_f32_16x16x32_bf16 v[10:13], v[114:117], v[182:185], v[10:13]
	v_mfma_f32_16x16x32_bf16 v[62:65], v[102:105], v[170:173], v[62:65]
	v_mfma_f32_16x16x32_bf16 v[58:61], v[126:129], v[170:173], v[58:61]
	v_mfma_f32_16x16x32_bf16 v[46:49], v[102:105], v[174:177], v[46:49]
	v_mfma_f32_16x16x32_bf16 v[42:45], v[126:129], v[174:177], v[42:45]
	v_mfma_f32_16x16x32_bf16 v[30:33], v[102:105], v[204:207], v[30:33]
	v_mfma_f32_16x16x32_bf16 v[26:29], v[126:129], v[204:207], v[26:29]
	v_mfma_f32_16x16x32_bf16 v[14:17], v[102:105], v[226:229], v[14:17]
	v_mfma_f32_16x16x32_bf16 v[10:13], v[126:129], v[226:229], v[10:13]
	s_setprio 0
	s_setprio 1
	v_mfma_f32_16x16x32_bf16 v[54:57], v[138:141], v[162:165], v[54:57]
	v_mfma_f32_16x16x32_bf16 v[50:53], v[154:157], v[162:165], v[50:53]
	v_mfma_f32_16x16x32_bf16 v[38:41], v[138:141], v[166:169], v[38:41]
	v_mfma_f32_16x16x32_bf16 v[34:37], v[154:157], v[166:169], v[34:37]
	v_mfma_f32_16x16x32_bf16 v[22:25], v[138:141], v[178:181], v[22:25]
	v_mfma_f32_16x16x32_bf16 v[18:21], v[154:157], v[178:181], v[18:21]
	v_mfma_f32_16x16x32_bf16 v[6:9], v[138:141], v[182:185], v[6:9]
	v_mfma_f32_16x16x32_bf16 v[2:5], v[154:157], v[182:185], v[2:5]
	v_mfma_f32_16x16x32_bf16 v[54:57], v[150:153], v[170:173], v[54:57]
	v_mfma_f32_16x16x32_bf16 v[50:53], v[158:161], v[170:173], v[50:53]
	v_mfma_f32_16x16x32_bf16 v[38:41], v[150:153], v[174:177], v[38:41]
	v_mfma_f32_16x16x32_bf16 v[34:37], v[158:161], v[174:177], v[34:37]
	v_mfma_f32_16x16x32_bf16 v[22:25], v[150:153], v[204:207], v[22:25]
	v_mfma_f32_16x16x32_bf16 v[18:21], v[158:161], v[204:207], v[18:21]
	v_mfma_f32_16x16x32_bf16 v[6:9], v[150:153], v[226:229], v[6:9]
	v_mfma_f32_16x16x32_bf16 v[2:5], v[158:161], v[226:229], v[2:5]
	s_setprio 0
	s_barrier
	s_add_i32 s45, 0, 0x18000
	s_add_i32 s48, 0, 0x1c000
	ds_read_b128 v[90:93], v245 offset:32768
	ds_read_b128 v[102:105], v246 offset:32768
	ds_read_b128 v[114:117], v222
	ds_read_b128 v[126:129], v223
	ds_read_b128 v[138:141], v245 offset:49152
	ds_read_b128 v[150:153], v246 offset:49152
	ds_read_b128 v[154:157], v224
	ds_read_b128 v[158:161], v225
	s_add_u32 s46, s54, 0xb0000
	s_addc_u32 s47, s55, 0
	s_mov_b32 m0, s58
	ds_read_b128 v[162:165], v220 offset:32768
	ds_read_b128 v[166:169], v220 offset:34816
	ds_read_b128 v[170:173], v221 offset:32768
	ds_read_b128 v[174:177], v221 offset:34816
	ds_read_b128 v[178:181], v220 offset:36864
	ds_read_b128 v[182:185], v220 offset:38912
	ds_read_b128 v[204:207], v221 offset:36864
	ds_read_b128 v[226:229], v221 offset:38912
	global_load_lds_dwordx4 v186, s[46:47]
	s_mov_b32 m0, s59
	s_nop 0
	global_load_lds_dwordx4 v190, s[46:47]
	s_waitcnt vmcnt(8)
	s_waitcnt lgkmcnt(0)
	s_barrier
	s_setprio 1
	s_waitcnt lgkmcnt(0)
	v_mfma_f32_16x16x32_bf16 v[146:149], v[90:93], v[162:165], v[146:149]
	v_mfma_f32_16x16x32_bf16 v[142:145], v[114:117], v[162:165], v[142:145]
	v_mfma_f32_16x16x32_bf16 v[122:125], v[90:93], v[166:169], v[122:125]
	v_mfma_f32_16x16x32_bf16 v[118:121], v[114:117], v[166:169], v[118:121]
	v_mfma_f32_16x16x32_bf16 v[98:101], v[90:93], v[178:181], v[98:101]
	v_mfma_f32_16x16x32_bf16 v[94:97], v[114:117], v[178:181], v[94:97]
	v_mfma_f32_16x16x32_bf16 v[78:81], v[90:93], v[182:185], v[78:81]
	v_mfma_f32_16x16x32_bf16 v[74:77], v[114:117], v[182:185], v[74:77]
	v_mfma_f32_16x16x32_bf16 v[146:149], v[102:105], v[170:173], v[146:149]
	v_mfma_f32_16x16x32_bf16 v[142:145], v[126:129], v[170:173], v[142:145]
	v_mfma_f32_16x16x32_bf16 v[122:125], v[102:105], v[174:177], v[122:125]
	v_mfma_f32_16x16x32_bf16 v[118:121], v[126:129], v[174:177], v[118:121]
	v_mfma_f32_16x16x32_bf16 v[98:101], v[102:105], v[204:207], v[98:101]
	v_mfma_f32_16x16x32_bf16 v[94:97], v[126:129], v[204:207], v[94:97]
	v_mfma_f32_16x16x32_bf16 v[78:81], v[102:105], v[226:229], v[78:81]
	v_mfma_f32_16x16x32_bf16 v[74:77], v[126:129], v[226:229], v[74:77]
	s_setprio 0
	s_setprio 1
	v_mfma_f32_16x16x32_bf16 v[134:137], v[138:141], v[162:165], v[134:137]
	v_mfma_f32_16x16x32_bf16 v[130:133], v[154:157], v[162:165], v[130:133]
	v_mfma_f32_16x16x32_bf16 v[110:113], v[138:141], v[166:169], v[110:113]
	v_mfma_f32_16x16x32_bf16 v[106:109], v[154:157], v[166:169], v[106:109]
	v_mfma_f32_16x16x32_bf16 v[86:89], v[138:141], v[178:181], v[86:89]
	v_mfma_f32_16x16x32_bf16 v[82:85], v[154:157], v[178:181], v[82:85]
	v_mfma_f32_16x16x32_bf16 v[70:73], v[138:141], v[182:185], v[70:73]
	v_mfma_f32_16x16x32_bf16 v[66:69], v[154:157], v[182:185], v[66:69]
	v_mfma_f32_16x16x32_bf16 v[134:137], v[150:153], v[170:173], v[134:137]
	v_mfma_f32_16x16x32_bf16 v[130:133], v[158:161], v[170:173], v[130:133]
	v_mfma_f32_16x16x32_bf16 v[110:113], v[150:153], v[174:177], v[110:113]
	v_mfma_f32_16x16x32_bf16 v[106:109], v[158:161], v[174:177], v[106:109]
	v_mfma_f32_16x16x32_bf16 v[86:89], v[150:153], v[204:207], v[86:89]
	v_mfma_f32_16x16x32_bf16 v[82:85], v[158:161], v[204:207], v[82:85]
	v_mfma_f32_16x16x32_bf16 v[70:73], v[150:153], v[226:229], v[70:73]
	v_mfma_f32_16x16x32_bf16 v[66:69], v[158:161], v[226:229], v[66:69]
	s_setprio 0
	s_barrier
	s_add_i32 s45, s45, s39
	s_add_i32 m0, s45, 0xffffff80
	ds_read_b128 v[162:165], v220 offset:49152
	ds_read_b128 v[166:169], v220 offset:51200
	ds_read_b128 v[170:173], v221 offset:49152
	ds_read_b128 v[174:177], v221 offset:51200
	ds_read_b128 v[178:181], v220 offset:53248
	ds_read_b128 v[182:185], v220 offset:55296
	ds_read_b128 v[204:207], v221 offset:53248
	ds_read_b128 v[226:229], v221 offset:55296
	global_load_lds_dwordx4 v188, s[52:53] offset:128
	s_add_i32 m0, s45, 0x1f80
	s_add_u32 s46, s52, 0xb0080
	s_addc_u32 s47, s53, 0
	s_add_i32 s45, s48, s39
	global_load_lds_dwordx4 v192, s[52:53] offset:128
	s_mov_b32 m0, s45
	s_nop 0
	global_load_lds_dwordx4 v188, s[46:47]
	s_add_i32 m0, s45, 0x2000
	s_nop 0
	global_load_lds_dwordx4 v192, s[46:47]
	s_add_i32 m0, s63, 0xffffff80
	s_nop 0
	global_load_lds_dwordx4 v186, s[54:55] offset:128
	s_add_i32 m0, s64, 0xffffff80
	s_nop 0
	global_load_lds_dwordx4 v190, s[54:55] offset:128
	s_waitcnt vmcnt(8)
	s_waitcnt lgkmcnt(0)
	s_barrier
	s_setprio 1
	s_waitcnt lgkmcnt(0)
	v_mfma_f32_16x16x32_bf16 v[62:65], v[90:93], v[162:165], v[62:65]
	v_mfma_f32_16x16x32_bf16 v[58:61], v[114:117], v[162:165], v[58:61]
	v_mfma_f32_16x16x32_bf16 v[46:49], v[90:93], v[166:169], v[46:49]
	v_mfma_f32_16x16x32_bf16 v[42:45], v[114:117], v[166:169], v[42:45]
	v_mfma_f32_16x16x32_bf16 v[30:33], v[90:93], v[178:181], v[30:33]
	v_mfma_f32_16x16x32_bf16 v[26:29], v[114:117], v[178:181], v[26:29]
	v_mfma_f32_16x16x32_bf16 v[14:17], v[90:93], v[182:185], v[14:17]
	v_mfma_f32_16x16x32_bf16 v[10:13], v[114:117], v[182:185], v[10:13]
	v_mfma_f32_16x16x32_bf16 v[62:65], v[102:105], v[170:173], v[62:65]
	v_mfma_f32_16x16x32_bf16 v[58:61], v[126:129], v[170:173], v[58:61]
	v_mfma_f32_16x16x32_bf16 v[46:49], v[102:105], v[174:177], v[46:49]
	v_mfma_f32_16x16x32_bf16 v[42:45], v[126:129], v[174:177], v[42:45]
	v_mfma_f32_16x16x32_bf16 v[30:33], v[102:105], v[204:207], v[30:33]
	v_mfma_f32_16x16x32_bf16 v[26:29], v[126:129], v[204:207], v[26:29]
	v_mfma_f32_16x16x32_bf16 v[14:17], v[102:105], v[226:229], v[14:17]
	v_mfma_f32_16x16x32_bf16 v[10:13], v[126:129], v[226:229], v[10:13]
	s_setprio 0
	s_setprio 1
	v_mfma_f32_16x16x32_bf16 v[54:57], v[138:141], v[162:165], v[54:57]
	v_mfma_f32_16x16x32_bf16 v[50:53], v[154:157], v[162:165], v[50:53]
	v_mfma_f32_16x16x32_bf16 v[38:41], v[138:141], v[166:169], v[38:41]
	v_mfma_f32_16x16x32_bf16 v[34:37], v[154:157], v[166:169], v[34:37]
	v_mfma_f32_16x16x32_bf16 v[22:25], v[138:141], v[178:181], v[22:25]
	v_mfma_f32_16x16x32_bf16 v[18:21], v[154:157], v[178:181], v[18:21]
	v_mfma_f32_16x16x32_bf16 v[6:9], v[138:141], v[182:185], v[6:9]
	v_mfma_f32_16x16x32_bf16 v[2:5], v[154:157], v[182:185], v[2:5]
	v_mfma_f32_16x16x32_bf16 v[54:57], v[150:153], v[170:173], v[54:57]
	v_mfma_f32_16x16x32_bf16 v[50:53], v[158:161], v[170:173], v[50:53]
	v_mfma_f32_16x16x32_bf16 v[38:41], v[150:153], v[174:177], v[38:41]
	v_mfma_f32_16x16x32_bf16 v[34:37], v[158:161], v[174:177], v[34:37]
	v_mfma_f32_16x16x32_bf16 v[22:25], v[150:153], v[204:207], v[22:25]
	v_mfma_f32_16x16x32_bf16 v[18:21], v[158:161], v[204:207], v[18:21]
	v_mfma_f32_16x16x32_bf16 v[6:9], v[150:153], v[226:229], v[6:9]
	v_mfma_f32_16x16x32_bf16 v[2:5], v[158:161], v[226:229], v[2:5]
	s_setprio 0
	s_barrier
	s_add_i32 s44, s44, 2
	s_add_u32 s40, s40, 0x100
	s_addc_u32 s41, s41, 0
	s_add_u32 s42, s42, 0x100
	s_addc_u32 s43, s43, 0
	s_cmp_gt_u32 s44, 41
	s_cbranch_scc0 .LBB0_589
	s_branch .Lpx_1
.Lpeel_1:
	s_mov_b32 s100, 0
	ds_read_b128 v[90:93], v212
	ds_read_b128 v[102:105], v213
	ds_read_b128 v[114:117], v214
	ds_read_b128 v[126:129], v215
	ds_read_b128 v[138:141], v216
	ds_read_b128 v[150:153], v217
	ds_read_b128 v[154:157], v218
	ds_read_b128 v[158:161], v219
	s_add_u32 s45, s40, 0xfff50080
	s_addc_u32 s46, s41, -1
	s_cmp_eq_u32 s44, 40
	s_cselect_b32 s55, s1, s46
	s_cselect_b32 s54, s0, s45
	s_cselect_b32 s53, s15, s43
	s_cselect_b32 s52, s14, s42
	s_add_i32 m0, s56, 0xc000
	ds_read_b128 v[162:165], v220
	ds_read_b128 v[166:169], v220 offset:2048
	ds_read_b128 v[170:173], v221
	ds_read_b128 v[174:177], v221 offset:2048
	ds_read_b128 v[178:181], v220 offset:4096
	ds_read_b128 v[182:185], v220 offset:6144
	ds_read_b128 v[204:207], v221 offset:4096
	ds_read_b128 v[226:229], v221 offset:6144
	global_load_lds_dwordx4 v196, s[40:41]
	s_add_i32 m0, s56, 0xe000
	s_nop 0
	global_load_lds_dwordx4 v198, s[40:41]
	s_waitcnt vmcnt(8)
	s_waitcnt lgkmcnt(0)
	s_barrier
	s_setprio 1
	s_waitcnt lgkmcnt(0)
	v_mfma_f32_16x16x32_bf16 v[146:149], v[90:93], v[162:165], 0
	v_mfma_f32_16x16x32_bf16 v[142:145], v[114:117], v[162:165], 0
	v_mfma_f32_16x16x32_bf16 v[122:125], v[90:93], v[166:169], 0
	v_mfma_f32_16x16x32_bf16 v[118:121], v[114:117], v[166:169], 0
	v_mfma_f32_16x16x32_bf16 v[98:101], v[90:93], v[178:181], 0
	v_mfma_f32_16x16x32_bf16 v[94:97], v[114:117], v[178:181], 0
	v_mfma_f32_16x16x32_bf16 v[78:81], v[90:93], v[182:185], 0
	v_mfma_f32_16x16x32_bf16 v[74:77], v[114:117], v[182:185], 0
	v_mfma_f32_16x16x32_bf16 v[146:149], v[102:105], v[170:173], v[146:149]
	v_mfma_f32_16x16x32_bf16 v[142:145], v[126:129], v[170:173], v[142:145]
	v_mfma_f32_16x16x32_bf16 v[122:125], v[102:105], v[174:177], v[122:125]
	v_mfma_f32_16x16x32_bf16 v[118:121], v[126:129], v[174:177], v[118:121]
	v_mfma_f32_16x16x32_bf16 v[98:101], v[102:105], v[204:207], v[98:101]
	v_mfma_f32_16x16x32_bf16 v[94:97], v[126:129], v[204:207], v[94:97]
	v_mfma_f32_16x16x32_bf16 v[78:81], v[102:105], v[226:229], v[78:81]
	v_mfma_f32_16x16x32_bf16 v[74:77], v[126:129], v[226:229], v[74:77]
	s_setprio 0
	s_setprio 1
	v_mfma_f32_16x16x32_bf16 v[134:137], v[138:141], v[162:165], 0
	v_mfma_f32_16x16x32_bf16 v[130:133], v[154:157], v[162:165], 0
	v_mfma_f32_16x16x32_bf16 v[110:113], v[138:141], v[166:169], 0
	v_mfma_f32_16x16x32_bf16 v[106:109], v[154:157], v[166:169], 0
	v_mfma_f32_16x16x32_bf16 v[86:89], v[138:141], v[178:181], 0
	v_mfma_f32_16x16x32_bf16 v[82:85], v[154:157], v[178:181], 0
	v_mfma_f32_16x16x32_bf16 v[70:73], v[138:141], v[182:185], 0
	v_mfma_f32_16x16x32_bf16 v[66:69], v[154:157], v[182:185], 0
	v_mfma_f32_16x16x32_bf16 v[134:137], v[150:153], v[170:173], v[134:137]
	v_mfma_f32_16x16x32_bf16 v[130:133], v[158:161], v[170:173], v[130:133]
	v_mfma_f32_16x16x32_bf16 v[110:113], v[150:153], v[174:177], v[110:113]
	v_mfma_f32_16x16x32_bf16 v[106:109], v[158:161], v[174:177], v[106:109]
	v_mfma_f32_16x16x32_bf16 v[86:89], v[150:153], v[204:207], v[86:89]
	v_mfma_f32_16x16x32_bf16 v[82:85], v[158:161], v[204:207], v[82:85]
	v_mfma_f32_16x16x32_bf16 v[70:73], v[150:153], v[226:229], v[70:73]
	v_mfma_f32_16x16x32_bf16 v[66:69], v[158:161], v[226:229], v[66:69]
	s_setprio 0
	s_barrier
	s_add_i32 s45, s68, s39
	s_mov_b32 m0, s45
	ds_read_b128 v[162:165], v220 offset:16384
	ds_read_b128 v[166:169], v220 offset:18432
	ds_read_b128 v[170:173], v221 offset:16384
	ds_read_b128 v[174:177], v221 offset:18432
	ds_read_b128 v[178:181], v220 offset:20480
	ds_read_b128 v[182:185], v220 offset:22528
	ds_read_b128 v[204:207], v221 offset:20480
	ds_read_b128 v[226:229], v221 offset:22528
	global_load_lds_dwordx4 v188, s[52:53]
	s_add_i32 m0, s45, 0x2000
	s_add_u32 s46, s52, 0xb0000
	s_addc_u32 s47, s53, 0
	s_add_i32 s45, s69, s39
	global_load_lds_dwordx4 v192, s[52:53]
	s_mov_b32 m0, s45
	s_nop 0
	global_load_lds_dwordx4 v188, s[46:47]
	s_add_i32 m0, s45, 0x2000
	s_nop 0
	global_load_lds_dwordx4 v192, s[46:47]
	s_mov_b32 m0, s56
	s_nop 0
	global_load_lds_dwordx4 v186, s[54:55]
	s_mov_b32 m0, s57
	s_nop 0
	global_load_lds_dwordx4 v190, s[54:55]
	s_waitcnt vmcnt(8)
	s_waitcnt lgkmcnt(0)
	s_barrier
	s_setprio 1
	s_waitcnt lgkmcnt(0)
	v_mfma_f32_16x16x32_bf16 v[62:65], v[90:93], v[162:165], 0
	v_mfma_f32_16x16x32_bf16 v[58:61], v[114:117], v[162:165], 0
	v_mfma_f32_16x16x32_bf16 v[46:49], v[90:93], v[166:169], 0
	v_mfma_f32_16x16x32_bf16 v[42:45], v[114:117], v[166:169], 0
	v_mfma_f32_16x16x32_bf16 v[30:33], v[90:93], v[178:181], 0
	v_mfma_f32_16x16x32_bf16 v[26:29], v[114:117], v[178:181], 0
	v_mfma_f32_16x16x32_bf16 v[14:17], v[90:93], v[182:185], 0
	v_mfma_f32_16x16x32_bf16 v[10:13], v[114:117], v[182:185], 0
	v_mfma_f32_16x16x32_bf16 v[62:65], v[102:105], v[170:173], v[62:65]
	v_mfma_f32_16x16x32_bf16 v[58:61], v[126:129], v[170:173], v[58:61]
	v_mfma_f32_16x16x32_bf16 v[46:49], v[102:105], v[174:177], v[46:49]
	v_mfma_f32_16x16x32_bf16 v[42:45], v[126:129], v[174:177], v[42:45]
	v_mfma_f32_16x16x32_bf16 v[30:33], v[102:105], v[204:207], v[30:33]
	v_mfma_f32_16x16x32_bf16 v[26:29], v[126:129], v[204:207], v[26:29]
	v_mfma_f32_16x16x32_bf16 v[14:17], v[102:105], v[226:229], v[14:17]
	v_mfma_f32_16x16x32_bf16 v[10:13], v[126:129], v[226:229], v[10:13]
	s_setprio 0
	s_setprio 1
	v_mfma_f32_16x16x32_bf16 v[54:57], v[138:141], v[162:165], 0
	v_mfma_f32_16x16x32_bf16 v[50:53], v[154:157], v[162:165], 0
	v_mfma_f32_16x16x32_bf16 v[38:41], v[138:141], v[166:169], 0
	v_mfma_f32_16x16x32_bf16 v[34:37], v[154:157], v[166:169], 0
	v_mfma_f32_16x16x32_bf16 v[22:25], v[138:141], v[178:181], 0
	v_mfma_f32_16x16x32_bf16 v[18:21], v[154:157], v[178:181], 0
	v_mfma_f32_16x16x32_bf16 v[6:9], v[138:141], v[182:185], 0
	v_mfma_f32_16x16x32_bf16 v[2:5], v[154:157], v[182:185], 0
	v_mfma_f32_16x16x32_bf16 v[54:57], v[150:153], v[170:173], v[54:57]
	v_mfma_f32_16x16x32_bf16 v[50:53], v[158:161], v[170:173], v[50:53]
	v_mfma_f32_16x16x32_bf16 v[38:41], v[150:153], v[174:177], v[38:41]
	v_mfma_f32_16x16x32_bf16 v[34:37], v[158:161], v[174:177], v[34:37]
	v_mfma_f32_16x16x32_bf16 v[22:25], v[150:153], v[204:207], v[22:25]
	v_mfma_f32_16x16x32_bf16 v[18:21], v[158:161], v[204:207], v[18:21]
	v_mfma_f32_16x16x32_bf16 v[6:9], v[150:153], v[226:229], v[6:9]
	v_mfma_f32_16x16x32_bf16 v[2:5], v[158:161], v[226:229], v[2:5]
	s_setprio 0
	s_barrier
	s_add_i32 s45, 0, 0x18000
	s_add_i32 s48, 0, 0x1c000
	ds_read_b128 v[90:93], v245 offset:32768
	ds_read_b128 v[102:105], v246 offset:32768
	ds_read_b128 v[114:117], v222
	ds_read_b128 v[126:129], v223
	ds_read_b128 v[138:141], v245 offset:49152
	ds_read_b128 v[150:153], v246 offset:49152
	ds_read_b128 v[154:157], v224
	ds_read_b128 v[158:161], v225
	s_add_u32 s46, s54, 0xb0000
	s_addc_u32 s47, s55, 0
	s_mov_b32 m0, s58
	ds_read_b128 v[162:165], v220 offset:32768
	ds_read_b128 v[166:169], v220 offset:34816
	ds_read_b128 v[170:173], v221 offset:32768
	ds_read_b128 v[174:177], v221 offset:34816
	ds_read_b128 v[178:181], v220 offset:36864
	ds_read_b128 v[182:185], v220 offset:38912
	ds_read_b128 v[204:207], v221 offset:36864
	ds_read_b128 v[226:229], v221 offset:38912
	global_load_lds_dwordx4 v186, s[46:47]
	s_mov_b32 m0, s59
	s_nop 0
	global_load_lds_dwordx4 v190, s[46:47]
	s_waitcnt vmcnt(8)
	s_waitcnt lgkmcnt(0)
	s_barrier
	s_setprio 1
	s_waitcnt lgkmcnt(0)
	v_mfma_f32_16x16x32_bf16 v[146:149], v[90:93], v[162:165], v[146:149]
	v_mfma_f32_16x16x32_bf16 v[142:145], v[114:117], v[162:165], v[142:145]
	v_mfma_f32_16x16x32_bf16 v[122:125], v[90:93], v[166:169], v[122:125]
	v_mfma_f32_16x16x32_bf16 v[118:121], v[114:117], v[166:169], v[118:121]
	v_mfma_f32_16x16x32_bf16 v[98:101], v[90:93], v[178:181], v[98:101]
	v_mfma_f32_16x16x32_bf16 v[94:97], v[114:117], v[178:181], v[94:97]
	v_mfma_f32_16x16x32_bf16 v[78:81], v[90:93], v[182:185], v[78:81]
	v_mfma_f32_16x16x32_bf16 v[74:77], v[114:117], v[182:185], v[74:77]
	v_mfma_f32_16x16x32_bf16 v[146:149], v[102:105], v[170:173], v[146:149]
	v_mfma_f32_16x16x32_bf16 v[142:145], v[126:129], v[170:173], v[142:145]
	v_mfma_f32_16x16x32_bf16 v[122:125], v[102:105], v[174:177], v[122:125]
	v_mfma_f32_16x16x32_bf16 v[118:121], v[126:129], v[174:177], v[118:121]
	v_mfma_f32_16x16x32_bf16 v[98:101], v[102:105], v[204:207], v[98:101]
	v_mfma_f32_16x16x32_bf16 v[94:97], v[126:129], v[204:207], v[94:97]
	v_mfma_f32_16x16x32_bf16 v[78:81], v[102:105], v[226:229], v[78:81]
	v_mfma_f32_16x16x32_bf16 v[74:77], v[126:129], v[226:229], v[74:77]
	s_setprio 0
	s_setprio 1
	v_mfma_f32_16x16x32_bf16 v[134:137], v[138:141], v[162:165], v[134:137]
	v_mfma_f32_16x16x32_bf16 v[130:133], v[154:157], v[162:165], v[130:133]
	v_mfma_f32_16x16x32_bf16 v[110:113], v[138:141], v[166:169], v[110:113]
	v_mfma_f32_16x16x32_bf16 v[106:109], v[154:157], v[166:169], v[106:109]
	v_mfma_f32_16x16x32_bf16 v[86:89], v[138:141], v[178:181], v[86:89]
	v_mfma_f32_16x16x32_bf16 v[82:85], v[154:157], v[178:181], v[82:85]
	v_mfma_f32_16x16x32_bf16 v[70:73], v[138:141], v[182:185], v[70:73]
	v_mfma_f32_16x16x32_bf16 v[66:69], v[154:157], v[182:185], v[66:69]
	v_mfma_f32_16x16x32_bf16 v[134:137], v[150:153], v[170:173], v[134:137]
	v_mfma_f32_16x16x32_bf16 v[130:133], v[158:161], v[170:173], v[130:133]
	v_mfma_f32_16x16x32_bf16 v[110:113], v[150:153], v[174:177], v[110:113]
	v_mfma_f32_16x16x32_bf16 v[106:109], v[158:161], v[174:177], v[106:109]
	v_mfma_f32_16x16x32_bf16 v[86:89], v[150:153], v[204:207], v[86:89]
	v_mfma_f32_16x16x32_bf16 v[82:85], v[158:161], v[204:207], v[82:85]
	v_mfma_f32_16x16x32_bf16 v[70:73], v[150:153], v[226:229], v[70:73]
	v_mfma_f32_16x16x32_bf16 v[66:69], v[158:161], v[226:229], v[66:69]
	s_setprio 0
	s_barrier
	s_add_i32 s45, s45, s39
	s_add_i32 m0, s45, 0xffffff80
	ds_read_b128 v[162:165], v220 offset:49152
	ds_read_b128 v[166:169], v220 offset:51200
	ds_read_b128 v[170:173], v221 offset:49152
	ds_read_b128 v[174:177], v221 offset:51200
	ds_read_b128 v[178:181], v220 offset:53248
	ds_read_b128 v[182:185], v220 offset:55296
	ds_read_b128 v[204:207], v221 offset:53248
	ds_read_b128 v[226:229], v221 offset:55296
	global_load_lds_dwordx4 v188, s[52:53] offset:128
	s_add_i32 m0, s45, 0x1f80
	s_add_u32 s46, s52, 0xb0080
	s_addc_u32 s47, s53, 0
	s_add_i32 s45, s48, s39
	global_load_lds_dwordx4 v192, s[52:53] offset:128
	s_mov_b32 m0, s45
	s_nop 0
	global_load_lds_dwordx4 v188, s[46:47]
	s_add_i32 m0, s45, 0x2000
	s_nop 0
	global_load_lds_dwordx4 v192, s[46:47]
	s_add_i32 m0, s63, 0xffffff80
	s_nop 0
	global_load_lds_dwordx4 v186, s[54:55] offset:128
	s_add_i32 m0, s64, 0xffffff80
	s_nop 0
	global_load_lds_dwordx4 v190, s[54:55] offset:128
	s_waitcnt vmcnt(8)
	s_waitcnt lgkmcnt(0)
	s_barrier
	s_setprio 1
	s_waitcnt lgkmcnt(0)
	v_mfma_f32_16x16x32_bf16 v[62:65], v[90:93], v[162:165], v[62:65]
	v_mfma_f32_16x16x32_bf16 v[58:61], v[114:117], v[162:165], v[58:61]
	v_mfma_f32_16x16x32_bf16 v[46:49], v[90:93], v[166:169], v[46:49]
	v_mfma_f32_16x16x32_bf16 v[42:45], v[114:117], v[166:169], v[42:45]
	v_mfma_f32_16x16x32_bf16 v[30:33], v[90:93], v[178:181], v[30:33]
	v_mfma_f32_16x16x32_bf16 v[26:29], v[114:117], v[178:181], v[26:29]
	v_mfma_f32_16x16x32_bf16 v[14:17], v[90:93], v[182:185], v[14:17]
	v_mfma_f32_16x16x32_bf16 v[10:13], v[114:117], v[182:185], v[10:13]
	v_mfma_f32_16x16x32_bf16 v[62:65], v[102:105], v[170:173], v[62:65]
	v_mfma_f32_16x16x32_bf16 v[58:61], v[126:129], v[170:173], v[58:61]
	v_mfma_f32_16x16x32_bf16 v[46:49], v[102:105], v[174:177], v[46:49]
	v_mfma_f32_16x16x32_bf16 v[42:45], v[126:129], v[174:177], v[42:45]
	v_mfma_f32_16x16x32_bf16 v[30:33], v[102:105], v[204:207], v[30:33]
	v_mfma_f32_16x16x32_bf16 v[26:29], v[126:129], v[204:207], v[26:29]
	v_mfma_f32_16x16x32_bf16 v[14:17], v[102:105], v[226:229], v[14:17]
	v_mfma_f32_16x16x32_bf16 v[10:13], v[126:129], v[226:229], v[10:13]
	s_setprio 0
	s_setprio 1
	v_mfma_f32_16x16x32_bf16 v[54:57], v[138:141], v[162:165], v[54:57]
	v_mfma_f32_16x16x32_bf16 v[50:53], v[154:157], v[162:165], v[50:53]
	v_mfma_f32_16x16x32_bf16 v[38:41], v[138:141], v[166:169], v[38:41]
	v_mfma_f32_16x16x32_bf16 v[34:37], v[154:157], v[166:169], v[34:37]
	v_mfma_f32_16x16x32_bf16 v[22:25], v[138:141], v[178:181], v[22:25]
	v_mfma_f32_16x16x32_bf16 v[18:21], v[154:157], v[178:181], v[18:21]
	v_mfma_f32_16x16x32_bf16 v[6:9], v[138:141], v[182:185], v[6:9]
	v_mfma_f32_16x16x32_bf16 v[2:5], v[154:157], v[182:185], v[2:5]
	v_mfma_f32_16x16x32_bf16 v[54:57], v[150:153], v[170:173], v[54:57]
	v_mfma_f32_16x16x32_bf16 v[50:53], v[158:161], v[170:173], v[50:53]
	v_mfma_f32_16x16x32_bf16 v[38:41], v[150:153], v[174:177], v[38:41]
	v_mfma_f32_16x16x32_bf16 v[34:37], v[158:161], v[174:177], v[34:37]
	v_mfma_f32_16x16x32_bf16 v[22:25], v[150:153], v[204:207], v[22:25]
	v_mfma_f32_16x16x32_bf16 v[18:21], v[158:161], v[204:207], v[18:21]
	v_mfma_f32_16x16x32_bf16 v[6:9], v[150:153], v[226:229], v[6:9]
	v_mfma_f32_16x16x32_bf16 v[2:5], v[158:161], v[226:229], v[2:5]
	s_setprio 0
	s_barrier
	s_add_i32 s44, s44, 2
	s_add_u32 s40, s40, 0x100
	s_addc_u32 s41, s41, 0
	s_add_u32 s42, s42, 0x100
	s_addc_u32 s43, s43, 0
	s_cmp_gt_u32 s44, 41
	s_cbranch_scc0 .LBB0_589

.LBB0_683:
	s_ashr_i32 s5, s4, 31
	s_lshl_b64 s[38:39], s[4:5], 19
	v_readlane_b32 s16, v244, 44
	v_readlane_b32 s17, v244, 45
	s_add_u32 s72, s16, s38
	s_addc_u32 s73, s17, s39
	s_and_b64 s[38:39], s[6:7], exec
	s_cselect_b32 s5, s73, s11
	s_cselect_b32 s38, s72, s10
	s_ashr_i32 s13, s12, 31
	s_lshl_b64 s[42:43], s[12:13], 19
	s_add_u32 s70, s3, s42
	s_addc_u32 s71, s34, s43
	s_and_b64 s[42:43], s[6:7], exec
	s_cselect_b32 s13, s71, s87
	s_cselect_b32 s39, s70, s86
	s_lshl_b32 s44, s52, 10
	s_lshl_b32 s42, s4, 8
	s_add_i32 s53, s44, 0
	s_ashr_i32 s43, s42, 31
	s_add_i32 s53, s53, 0x20800
	s_add_u32 s10, s10, 0x40080
	s_addc_u32 s11, s11, 0
	s_add_u32 s68, s86, 0x100
	v_add_u32_e32 v245, 0x10000, v213
	v_add_u32_e32 v246, 0x10000, v214
	s_mov_b32 s100, 1
	s_waitcnt vmcnt(0)
	v_lshl_add_u64 v[130:131], s[42:43], 2, v[172:173]
	s_addc_u32 s69, s87, 0
	s_mov_b32 s42, -2
	s_branch .LBB0_685
.LBB0_684:
	s_cmp_lg_u32 s100, 0
	s_cbranch_scc1 .Lpeel_2
	ds_read_b128 v[132:135], v245
	ds_read_b128 v[136:139], v246
	ds_read_b128 v[140:143], v245 offset:2048
	ds_read_b128 v[144:147], v246 offset:2048
	ds_read_b128 v[148:151], v245 offset:16384
	ds_read_b128 v[152:155], v246 offset:16384
	ds_read_b128 v[156:159], v245 offset:18432
	ds_read_b128 v[160:163], v246 offset:18432
	s_add_u32 s43, s10, 0xfffc0080
	s_addc_u32 s46, s11, -1
	s_and_b64 s[44:45], s[86:87], exec
	s_cselect_b32 vcc_hi, s5, s46
	s_cselect_b32 vcc_lo, s38, s43
	s_cselect_b32 s87, s13, s69
	s_cselect_b32 s86, s39, s68
	s_add_i32 m0, s88, 0xc000
	ds_read_b128 v[164:167], v215
	s_waitcnt lgkmcnt(0)
	ds_read_b128 v[190:193], v215 offset:2048
	ds_read_b128 v[194:197], v216
	ds_read_b128 v[198:201], v216 offset:2048
	ds_read_b128 v[202:205], v215 offset:4096
	ds_read_b128 v[206:209], v215 offset:6144
	ds_read_b128 v[218:221], v216 offset:4096
	ds_read_b128 v[222:225], v216 offset:6144
	global_load_lds_dwordx4 v180, s[10:11]
	s_add_i32 m0, s88, 0xe000
	s_nop 0
	global_load_lds_dwordx4 v184, s[10:11]
	s_waitcnt vmcnt(8)
	s_waitcnt lgkmcnt(0)
	s_barrier
	s_setprio 1
	s_waitcnt lgkmcnt(0)
	v_mfma_f32_16x16x32_bf16 v[126:129], v[132:135], v[164:167], v[126:129]
	v_mfma_f32_16x16x32_bf16 v[122:125], v[140:143], v[164:167], v[122:125]
	v_mfma_f32_16x16x32_bf16 v[110:113], v[132:135], v[190:193], v[110:113]
	v_mfma_f32_16x16x32_bf16 v[106:109], v[140:143], v[190:193], v[106:109]
	v_mfma_f32_16x16x32_bf16 v[94:97], v[132:135], v[202:205], v[94:97]
	v_mfma_f32_16x16x32_bf16 v[90:93], v[140:143], v[202:205], v[90:93]
	v_mfma_f32_16x16x32_bf16 v[78:81], v[132:135], v[206:209], v[78:81]
	v_mfma_f32_16x16x32_bf16 v[74:77], v[140:143], v[206:209], v[74:77]
	v_mfma_f32_16x16x32_bf16 v[126:129], v[136:139], v[194:197], v[126:129]
	v_mfma_f32_16x16x32_bf16 v[122:125], v[144:147], v[194:197], v[122:125]
	v_mfma_f32_16x16x32_bf16 v[110:113], v[136:139], v[198:201], v[110:113]
	v_mfma_f32_16x16x32_bf16 v[106:109], v[144:147], v[198:201], v[106:109]
	v_mfma_f32_16x16x32_bf16 v[94:97], v[136:139], v[218:221], v[94:97]
	v_mfma_f32_16x16x32_bf16 v[90:93], v[144:147], v[218:221], v[90:93]
	v_mfma_f32_16x16x32_bf16 v[78:81], v[136:139], v[222:225], v[78:81]
	v_mfma_f32_16x16x32_bf16 v[74:77], v[144:147], v[222:225], v[74:77]
	s_setprio 0
	s_setprio 1
	v_mfma_f32_16x16x32_bf16 v[118:121], v[148:151], v[164:167], v[118:121]
	v_mfma_f32_16x16x32_bf16 v[114:117], v[156:159], v[164:167], v[114:117]
	v_mfma_f32_16x16x32_bf16 v[102:105], v[148:151], v[190:193], v[102:105]
	v_mfma_f32_16x16x32_bf16 v[98:101], v[156:159], v[190:193], v[98:101]
	v_mfma_f32_16x16x32_bf16 v[86:89], v[148:151], v[202:205], v[86:89]
	v_mfma_f32_16x16x32_bf16 v[82:85], v[156:159], v[202:205], v[82:85]
	v_mfma_f32_16x16x32_bf16 v[70:73], v[148:151], v[206:209], v[70:73]
	v_mfma_f32_16x16x32_bf16 v[66:69], v[156:159], v[206:209], v[66:69]
	v_mfma_f32_16x16x32_bf16 v[118:121], v[152:155], v[194:197], v[118:121]
	v_mfma_f32_16x16x32_bf16 v[114:117], v[160:163], v[194:197], v[114:117]
	v_mfma_f32_16x16x32_bf16 v[102:105], v[152:155], v[198:201], v[102:105]
	v_mfma_f32_16x16x32_bf16 v[98:101], v[160:163], v[198:201], v[98:101]
	v_mfma_f32_16x16x32_bf16 v[86:89], v[152:155], v[218:221], v[86:89]
	v_mfma_f32_16x16x32_bf16 v[82:85], v[160:163], v[218:221], v[82:85]
	v_mfma_f32_16x16x32_bf16 v[70:73], v[152:155], v[222:225], v[70:73]
	v_mfma_f32_16x16x32_bf16 v[66:69], v[160:163], v[222:225], v[66:69]
	s_setprio 0
	s_barrier
	s_add_i32 s43, s78, s15
	s_mov_b32 m0, s43
	ds_read_b128 v[164:167], v215 offset:16384
	ds_read_b128 v[190:193], v215 offset:18432
	ds_read_b128 v[194:197], v216 offset:16384
	ds_read_b128 v[198:201], v216 offset:18432
	ds_read_b128 v[202:205], v215 offset:20480
	ds_read_b128 v[206:209], v215 offset:22528
	ds_read_b128 v[218:221], v216 offset:20480
	ds_read_b128 v[222:225], v216 offset:22528
	global_load_lds_dwordx4 v170, s[86:87]
	s_add_i32 m0, s43, 0x2000
	s_add_u32 s44, s86, 0x40000
	s_addc_u32 s45, s87, 0
	s_add_i32 s43, s82, s15
	global_load_lds_dwordx4 v178, s[86:87]
	s_mov_b32 m0, s43
	s_nop 0
	global_load_lds_dwordx4 v170, s[44:45]
	s_add_i32 m0, s43, 0x2000
	s_nop 0
	global_load_lds_dwordx4 v178, s[44:45]
	s_mov_b32 m0, s88
	s_nop 0
	global_load_lds_dwordx4 v174, vcc
	s_mov_b32 m0, s89
	s_nop 0
	global_load_lds_dwordx4 v176, vcc
	s_waitcnt vmcnt(8)
	s_waitcnt lgkmcnt(0)
	s_barrier
	s_setprio 1
	s_waitcnt lgkmcnt(0)
	v_mfma_f32_16x16x32_bf16 v[62:65], v[132:135], v[164:167], v[62:65]
	v_mfma_f32_16x16x32_bf16 v[58:61], v[140:143], v[164:167], v[58:61]
	v_mfma_f32_16x16x32_bf16 v[46:49], v[132:135], v[190:193], v[46:49]
	v_mfma_f32_16x16x32_bf16 v[42:45], v[140:143], v[190:193], v[42:45]
	v_mfma_f32_16x16x32_bf16 v[30:33], v[132:135], v[202:205], v[30:33]
	v_mfma_f32_16x16x32_bf16 v[26:29], v[140:143], v[202:205], v[26:29]
	v_mfma_f32_16x16x32_bf16 v[14:17], v[132:135], v[206:209], v[14:17]
	v_mfma_f32_16x16x32_bf16 v[10:13], v[140:143], v[206:209], v[10:13]
	v_mfma_f32_16x16x32_bf16 v[62:65], v[136:139], v[194:197], v[62:65]
	v_mfma_f32_16x16x32_bf16 v[58:61], v[144:147], v[194:197], v[58:61]
	v_mfma_f32_16x16x32_bf16 v[46:49], v[136:139], v[198:201], v[46:49]
	v_mfma_f32_16x16x32_bf16 v[42:45], v[144:147], v[198:201], v[42:45]
	v_mfma_f32_16x16x32_bf16 v[30:33], v[136:139], v[218:221], v[30:33]
	v_mfma_f32_16x16x32_bf16 v[26:29], v[144:147], v[218:221], v[26:29]
	v_mfma_f32_16x16x32_bf16 v[14:17], v[136:139], v[222:225], v[14:17]
	v_mfma_f32_16x16x32_bf16 v[10:13], v[144:147], v[222:225], v[10:13]
	s_setprio 0
	s_setprio 1
	v_mfma_f32_16x16x32_bf16 v[54:57], v[148:151], v[164:167], v[54:57]
	v_mfma_f32_16x16x32_bf16 v[50:53], v[156:159], v[164:167], v[50:53]
	v_mfma_f32_16x16x32_bf16 v[38:41], v[148:151], v[190:193], v[38:41]
	v_mfma_f32_16x16x32_bf16 v[34:37], v[156:159], v[190:193], v[34:37]
	v_mfma_f32_16x16x32_bf16 v[22:25], v[148:151], v[202:205], v[22:25]
	v_mfma_f32_16x16x32_bf16 v[18:21], v[156:159], v[202:205], v[18:21]
	v_mfma_f32_16x16x32_bf16 v[6:9], v[148:151], v[206:209], v[6:9]
	v_mfma_f32_16x16x32_bf16 v[2:5], v[156:159], v[206:209], v[2:5]
	v_mfma_f32_16x16x32_bf16 v[54:57], v[152:155], v[194:197], v[54:57]
	v_mfma_f32_16x16x32_bf16 v[50:53], v[160:163], v[194:197], v[50:53]
	v_mfma_f32_16x16x32_bf16 v[38:41], v[152:155], v[198:201], v[38:41]
	v_mfma_f32_16x16x32_bf16 v[34:37], v[160:163], v[198:201], v[34:37]
	v_mfma_f32_16x16x32_bf16 v[22:25], v[152:155], v[218:221], v[22:25]
	v_mfma_f32_16x16x32_bf16 v[18:21], v[160:163], v[218:221], v[18:21]
	v_mfma_f32_16x16x32_bf16 v[6:9], v[152:155], v[222:225], v[6:9]
	v_mfma_f32_16x16x32_bf16 v[2:5], v[160:163], v[222:225], v[2:5]
	s_setprio 0
	s_barrier
	s_add_i32 s43, 0, 0x18000
	s_add_i32 s46, 0, 0x1c000
	ds_read_b128 v[132:135], v245 offset:32768
	ds_read_b128 v[136:139], v246 offset:32768
	ds_read_b128 v[140:143], v245 offset:34816
	ds_read_b128 v[144:147], v246 offset:34816
	ds_read_b128 v[148:151], v245 offset:49152
	ds_read_b128 v[152:155], v246 offset:49152
	ds_read_b128 v[156:159], v245 offset:51200
	ds_read_b128 v[160:163], v246 offset:51200
	s_add_u32 s44, vcc_lo, 0x40000
	s_addc_u32 s45, vcc_hi, 0
	s_mov_b32 m0, s94
	ds_read_b128 v[164:167], v215 offset:32768
	ds_read_b128 v[190:193], v215 offset:34816
	ds_read_b128 v[194:197], v216 offset:32768
	ds_read_b128 v[198:201], v216 offset:34816
	ds_read_b128 v[202:205], v215 offset:36864
	ds_read_b128 v[206:209], v215 offset:38912
	ds_read_b128 v[218:221], v216 offset:36864
	ds_read_b128 v[222:225], v216 offset:38912
	global_load_lds_dwordx4 v174, s[44:45]
	s_mov_b32 m0, s95
	s_nop 0
	global_load_lds_dwordx4 v176, s[44:45]
	s_waitcnt vmcnt(8)
	s_waitcnt lgkmcnt(0)
	s_barrier
	s_setprio 1
	s_waitcnt lgkmcnt(0)
	v_mfma_f32_16x16x32_bf16 v[126:129], v[132:135], v[164:167], v[126:129]
	v_mfma_f32_16x16x32_bf16 v[122:125], v[140:143], v[164:167], v[122:125]
	v_mfma_f32_16x16x32_bf16 v[110:113], v[132:135], v[190:193], v[110:113]
	v_mfma_f32_16x16x32_bf16 v[106:109], v[140:143], v[190:193], v[106:109]
	v_mfma_f32_16x16x32_bf16 v[94:97], v[132:135], v[202:205], v[94:97]
	v_mfma_f32_16x16x32_bf16 v[90:93], v[140:143], v[202:205], v[90:93]
	v_mfma_f32_16x16x32_bf16 v[78:81], v[132:135], v[206:209], v[78:81]
	v_mfma_f32_16x16x32_bf16 v[74:77], v[140:143], v[206:209], v[74:77]
	v_mfma_f32_16x16x32_bf16 v[126:129], v[136:139], v[194:197], v[126:129]
	v_mfma_f32_16x16x32_bf16 v[122:125], v[144:147], v[194:197], v[122:125]
	v_mfma_f32_16x16x32_bf16 v[110:113], v[136:139], v[198:201], v[110:113]
	v_mfma_f32_16x16x32_bf16 v[106:109], v[144:147], v[198:201], v[106:109]
	v_mfma_f32_16x16x32_bf16 v[94:97], v[136:139], v[218:221], v[94:97]
	v_mfma_f32_16x16x32_bf16 v[90:93], v[144:147], v[218:221], v[90:93]
	v_mfma_f32_16x16x32_bf16 v[78:81], v[136:139], v[222:225], v[78:81]
	v_mfma_f32_16x16x32_bf16 v[74:77], v[144:147], v[222:225], v[74:77]
	s_setprio 0
	s_setprio 1
	v_mfma_f32_16x16x32_bf16 v[118:121], v[148:151], v[164:167], v[118:121]
	v_mfma_f32_16x16x32_bf16 v[114:117], v[156:159], v[164:167], v[114:117]
	v_mfma_f32_16x16x32_bf16 v[102:105], v[148:151], v[190:193], v[102:105]
	v_mfma_f32_16x16x32_bf16 v[98:101], v[156:159], v[190:193], v[98:101]
	v_mfma_f32_16x16x32_bf16 v[86:89], v[148:151], v[202:205], v[86:89]
	v_mfma_f32_16x16x32_bf16 v[82:85], v[156:159], v[202:205], v[82:85]
	v_mfma_f32_16x16x32_bf16 v[70:73], v[148:151], v[206:209], v[70:73]
	v_mfma_f32_16x16x32_bf16 v[66:69], v[156:159], v[206:209], v[66:69]
	v_mfma_f32_16x16x32_bf16 v[118:121], v[152:155], v[194:197], v[118:121]
	v_mfma_f32_16x16x32_bf16 v[114:117], v[160:163], v[194:197], v[114:117]
	v_mfma_f32_16x16x32_bf16 v[102:105], v[152:155], v[198:201], v[102:105]
	v_mfma_f32_16x16x32_bf16 v[98:101], v[160:163], v[198:201], v[98:101]
	v_mfma_f32_16x16x32_bf16 v[86:89], v[152:155], v[218:221], v[86:89]
	v_mfma_f32_16x16x32_bf16 v[82:85], v[160:163], v[218:221], v[82:85]
	v_mfma_f32_16x16x32_bf16 v[70:73], v[152:155], v[222:225], v[70:73]
	v_mfma_f32_16x16x32_bf16 v[66:69], v[160:163], v[222:225], v[66:69]
	s_setprio 0
	s_barrier
	s_add_i32 s43, s43, s15
	s_add_i32 m0, s43, 0xffffff80
	ds_read_b128 v[164:167], v215 offset:49152
	ds_read_b128 v[190:193], v215 offset:51200
	ds_read_b128 v[194:197], v216 offset:49152
	ds_read_b128 v[198:201], v216 offset:51200
	ds_read_b128 v[202:205], v215 offset:53248
	ds_read_b128 v[206:209], v215 offset:55296
	ds_read_b128 v[218:221], v216 offset:53248
	ds_read_b128 v[222:225], v216 offset:55296
	global_load_lds_dwordx4 v170, s[86:87] offset:128
	s_add_i32 m0, s43, 0x1f80
	s_add_u32 s44, s86, 0x40080
	s_addc_u32 s45, s87, 0
	s_add_i32 s43, s46, s15
	global_load_lds_dwordx4 v178, s[86:87] offset:128
	s_mov_b32 m0, s43
	s_nop 0
	global_load_lds_dwordx4 v170, s[44:45]
	s_add_i32 m0, s43, 0x2000
	s_nop 0
	global_load_lds_dwordx4 v178, s[44:45]
	s_add_i32 m0, s80, 0xffffff80
	s_nop 0
	global_load_lds_dwordx4 v174, vcc offset:128
	s_add_i32 m0, s81, 0xffffff80
	s_nop 0
	global_load_lds_dwordx4 v176, vcc offset:128
	s_waitcnt vmcnt(8)
	s_waitcnt lgkmcnt(0)
	s_barrier
	s_setprio 1
	s_waitcnt lgkmcnt(0)
	v_mfma_f32_16x16x32_bf16 v[62:65], v[132:135], v[164:167], v[62:65]
	v_mfma_f32_16x16x32_bf16 v[58:61], v[140:143], v[164:167], v[58:61]
	v_mfma_f32_16x16x32_bf16 v[46:49], v[132:135], v[190:193], v[46:49]
	v_mfma_f32_16x16x32_bf16 v[42:45], v[140:143], v[190:193], v[42:45]
	v_mfma_f32_16x16x32_bf16 v[30:33], v[132:135], v[202:205], v[30:33]
	v_mfma_f32_16x16x32_bf16 v[26:29], v[140:143], v[202:205], v[26:29]
	v_mfma_f32_16x16x32_bf16 v[14:17], v[132:135], v[206:209], v[14:17]
	v_mfma_f32_16x16x32_bf16 v[10:13], v[140:143], v[206:209], v[10:13]
	v_mfma_f32_16x16x32_bf16 v[62:65], v[136:139], v[194:197], v[62:65]
	v_mfma_f32_16x16x32_bf16 v[58:61], v[144:147], v[194:197], v[58:61]
	v_mfma_f32_16x16x32_bf16 v[46:49], v[136:139], v[198:201], v[46:49]
	v_mfma_f32_16x16x32_bf16 v[42:45], v[144:147], v[198:201], v[42:45]
	v_mfma_f32_16x16x32_bf16 v[30:33], v[136:139], v[218:221], v[30:33]
	v_mfma_f32_16x16x32_bf16 v[26:29], v[144:147], v[218:221], v[26:29]
	v_mfma_f32_16x16x32_bf16 v[14:17], v[136:139], v[222:225], v[14:17]
	v_mfma_f32_16x16x32_bf16 v[10:13], v[144:147], v[222:225], v[10:13]
	s_setprio 0
	s_setprio 1
	v_mfma_f32_16x16x32_bf16 v[54:57], v[148:151], v[164:167], v[54:57]
	v_mfma_f32_16x16x32_bf16 v[50:53], v[156:159], v[164:167], v[50:53]
	v_mfma_f32_16x16x32_bf16 v[38:41], v[148:151], v[190:193], v[38:41]
	v_mfma_f32_16x16x32_bf16 v[34:37], v[156:159], v[190:193], v[34:37]
	v_mfma_f32_16x16x32_bf16 v[22:25], v[148:151], v[202:205], v[22:25]
	v_mfma_f32_16x16x32_bf16 v[18:21], v[156:159], v[202:205], v[18:21]
	v_mfma_f32_16x16x32_bf16 v[6:9], v[148:151], v[206:209], v[6:9]
	v_mfma_f32_16x16x32_bf16 v[2:5], v[156:159], v[206:209], v[2:5]
	v_mfma_f32_16x16x32_bf16 v[54:57], v[152:155], v[194:197], v[54:57]
	v_mfma_f32_16x16x32_bf16 v[50:53], v[160:163], v[194:197], v[50:53]
	v_mfma_f32_16x16x32_bf16 v[38:41], v[152:155], v[198:201], v[38:41]
	v_mfma_f32_16x16x32_bf16 v[34:37], v[160:163], v[198:201], v[34:37]
	v_mfma_f32_16x16x32_bf16 v[22:25], v[152:155], v[218:221], v[22:25]
	v_mfma_f32_16x16x32_bf16 v[18:21], v[160:163], v[218:221], v[18:21]
	v_mfma_f32_16x16x32_bf16 v[6:9], v[152:155], v[222:225], v[6:9]
	v_mfma_f32_16x16x32_bf16 v[2:5], v[160:163], v[222:225], v[2:5]
	s_setprio 0
	s_barrier
	s_add_i32 s42, s42, 2
	s_add_u32 s10, s10, 0x100
	s_addc_u32 s11, s11, 0
	s_add_u32 s68, s68, 0x100
	s_addc_u32 s69, s69, 0
	s_cmp_gt_u32 s42, 13
	s_cbranch_scc1 .LBB0_688

.Lpeel_2:
	s_mov_b32 s100, 0
	ds_read_b128 v[132:135], v245
	ds_read_b128 v[136:139], v246
	ds_read_b128 v[140:143], v245 offset:2048
	ds_read_b128 v[144:147], v246 offset:2048
	ds_read_b128 v[148:151], v245 offset:16384
	ds_read_b128 v[152:155], v246 offset:16384
	ds_read_b128 v[156:159], v245 offset:18432
	ds_read_b128 v[160:163], v246 offset:18432
	s_add_u32 s43, s10, 0xfffc0080
	s_addc_u32 s46, s11, -1
	s_and_b64 s[44:45], s[86:87], exec
	s_cselect_b32 vcc_hi, s5, s46
	s_cselect_b32 vcc_lo, s38, s43
	s_cselect_b32 s87, s13, s69
	s_cselect_b32 s86, s39, s68
	s_add_i32 m0, s88, 0xc000
	ds_read_b128 v[164:167], v215
	s_waitcnt lgkmcnt(0)
	ds_read_b128 v[190:193], v215 offset:2048
	ds_read_b128 v[194:197], v216
	ds_read_b128 v[198:201], v216 offset:2048
	ds_read_b128 v[202:205], v215 offset:4096
	ds_read_b128 v[206:209], v215 offset:6144
	ds_read_b128 v[218:221], v216 offset:4096
	ds_read_b128 v[222:225], v216 offset:6144
	global_load_lds_dwordx4 v180, s[10:11]
	s_add_i32 m0, s88, 0xe000
	s_nop 0
	global_load_lds_dwordx4 v184, s[10:11]
	s_waitcnt vmcnt(8)
	s_waitcnt lgkmcnt(0)
	s_barrier
	s_setprio 1
	s_waitcnt lgkmcnt(0)
	v_mfma_f32_16x16x32_bf16 v[126:129], v[132:135], v[164:167], 0
	v_mfma_f32_16x16x32_bf16 v[122:125], v[140:143], v[164:167], 0
	v_mfma_f32_16x16x32_bf16 v[110:113], v[132:135], v[190:193], 0
	v_mfma_f32_16x16x32_bf16 v[106:109], v[140:143], v[190:193], 0
	v_mfma_f32_16x16x32_bf16 v[94:97], v[132:135], v[202:205], 0
	v_mfma_f32_16x16x32_bf16 v[90:93], v[140:143], v[202:205], 0
	v_mfma_f32_16x16x32_bf16 v[78:81], v[132:135], v[206:209], 0
	v_mfma_f32_16x16x32_bf16 v[74:77], v[140:143], v[206:209], 0
	v_mfma_f32_16x16x32_bf16 v[126:129], v[136:139], v[194:197], v[126:129]
	v_mfma_f32_16x16x32_bf16 v[122:125], v[144:147], v[194:197], v[122:125]
	v_mfma_f32_16x16x32_bf16 v[110:113], v[136:139], v[198:201], v[110:113]
	v_mfma_f32_16x16x32_bf16 v[106:109], v[144:147], v[198:201], v[106:109]
	v_mfma_f32_16x16x32_bf16 v[94:97], v[136:139], v[218:221], v[94:97]
	v_mfma_f32_16x16x32_bf16 v[90:93], v[144:147], v[218:221], v[90:93]
	v_mfma_f32_16x16x32_bf16 v[78:81], v[136:139], v[222:225], v[78:81]
	v_mfma_f32_16x16x32_bf16 v[74:77], v[144:147], v[222:225], v[74:77]
	s_setprio 0
	s_setprio 1
	v_mfma_f32_16x16x32_bf16 v[118:121], v[148:151], v[164:167], 0
	v_mfma_f32_16x16x32_bf16 v[114:117], v[156:159], v[164:167], 0
	v_mfma_f32_16x16x32_bf16 v[102:105], v[148:151], v[190:193], 0
	v_mfma_f32_16x16x32_bf16 v[98:101], v[156:159], v[190:193], 0
	v_mfma_f32_16x16x32_bf16 v[86:89], v[148:151], v[202:205], 0
	v_mfma_f32_16x16x32_bf16 v[82:85], v[156:159], v[202:205], 0
	v_mfma_f32_16x16x32_bf16 v[70:73], v[148:151], v[206:209], 0
	v_mfma_f32_16x16x32_bf16 v[66:69], v[156:159], v[206:209], 0
	v_mfma_f32_16x16x32_bf16 v[118:121], v[152:155], v[194:197], v[118:121]
	v_mfma_f32_16x16x32_bf16 v[114:117], v[160:163], v[194:197], v[114:117]
	v_mfma_f32_16x16x32_bf16 v[102:105], v[152:155], v[198:201], v[102:105]
	v_mfma_f32_16x16x32_bf16 v[98:101], v[160:163], v[198:201], v[98:101]
	v_mfma_f32_16x16x32_bf16 v[86:89], v[152:155], v[218:221], v[86:89]
	v_mfma_f32_16x16x32_bf16 v[82:85], v[160:163], v[218:221], v[82:85]
	v_mfma_f32_16x16x32_bf16 v[70:73], v[152:155], v[222:225], v[70:73]
	v_mfma_f32_16x16x32_bf16 v[66:69], v[160:163], v[222:225], v[66:69]
	s_setprio 0
	s_barrier
	s_add_i32 s43, s78, s15
	s_mov_b32 m0, s43
	ds_read_b128 v[164:167], v215 offset:16384
	ds_read_b128 v[190:193], v215 offset:18432
	ds_read_b128 v[194:197], v216 offset:16384
	ds_read_b128 v[198:201], v216 offset:18432
	ds_read_b128 v[202:205], v215 offset:20480
	ds_read_b128 v[206:209], v215 offset:22528
	ds_read_b128 v[218:221], v216 offset:20480
	ds_read_b128 v[222:225], v216 offset:22528
	global_load_lds_dwordx4 v170, s[86:87]
	s_add_i32 m0, s43, 0x2000
	s_add_u32 s44, s86, 0x40000
	s_addc_u32 s45, s87, 0
	s_add_i32 s43, s82, s15
	global_load_lds_dwordx4 v178, s[86:87]
	s_mov_b32 m0, s43
	s_nop 0
	global_load_lds_dwordx4 v170, s[44:45]
	s_add_i32 m0, s43, 0x2000
	s_nop 0
	global_load_lds_dwordx4 v178, s[44:45]
	s_mov_b32 m0, s88
	s_nop 0
	global_load_lds_dwordx4 v174, vcc
	s_mov_b32 m0, s89
	s_nop 0
	global_load_lds_dwordx4 v176, vcc
	s_waitcnt vmcnt(8)
	s_waitcnt lgkmcnt(0)
	s_barrier
	s_setprio 1
	s_waitcnt lgkmcnt(0)
	v_mfma_f32_16x16x32_bf16 v[62:65], v[132:135], v[164:167], 0
	v_mfma_f32_16x16x32_bf16 v[58:61], v[140:143], v[164:167], 0
	v_mfma_f32_16x16x32_bf16 v[46:49], v[132:135], v[190:193], 0
	v_mfma_f32_16x16x32_bf16 v[42:45], v[140:143], v[190:193], 0
	v_mfma_f32_16x16x32_bf16 v[30:33], v[132:135], v[202:205], 0
	v_mfma_f32_16x16x32_bf16 v[26:29], v[140:143], v[202:205], 0
	v_mfma_f32_16x16x32_bf16 v[14:17], v[132:135], v[206:209], 0
	v_mfma_f32_16x16x32_bf16 v[10:13], v[140:143], v[206:209], 0
	v_mfma_f32_16x16x32_bf16 v[62:65], v[136:139], v[194:197], v[62:65]
	v_mfma_f32_16x16x32_bf16 v[58:61], v[144:147], v[194:197], v[58:61]
	v_mfma_f32_16x16x32_bf16 v[46:49], v[136:139], v[198:201], v[46:49]
	v_mfma_f32_16x16x32_bf16 v[42:45], v[144:147], v[198:201], v[42:45]
	v_mfma_f32_16x16x32_bf16 v[30:33], v[136:139], v[218:221], v[30:33]
	v_mfma_f32_16x16x32_bf16 v[26:29], v[144:147], v[218:221], v[26:29]
	v_mfma_f32_16x16x32_bf16 v[14:17], v[136:139], v[222:225], v[14:17]
	v_mfma_f32_16x16x32_bf16 v[10:13], v[144:147], v[222:225], v[10:13]
	s_setprio 0
	s_setprio 1
	v_mfma_f32_16x16x32_bf16 v[54:57], v[148:151], v[164:167], 0
	v_mfma_f32_16x16x32_bf16 v[50:53], v[156:159], v[164:167], 0
	v_mfma_f32_16x16x32_bf16 v[38:41], v[148:151], v[190:193], 0
	v_mfma_f32_16x16x32_bf16 v[34:37], v[156:159], v[190:193], 0
	v_mfma_f32_16x16x32_bf16 v[22:25], v[148:151], v[202:205], 0
	v_mfma_f32_16x16x32_bf16 v[18:21], v[156:159], v[202:205], 0
	v_mfma_f32_16x16x32_bf16 v[6:9], v[148:151], v[206:209], 0
	v_mfma_f32_16x16x32_bf16 v[2:5], v[156:159], v[206:209], 0
	v_mfma_f32_16x16x32_bf16 v[54:57], v[152:155], v[194:197], v[54:57]
	v_mfma_f32_16x16x32_bf16 v[50:53], v[160:163], v[194:197], v[50:53]
	v_mfma_f32_16x16x32_bf16 v[38:41], v[152:155], v[198:201], v[38:41]
	v_mfma_f32_16x16x32_bf16 v[34:37], v[160:163], v[198:201], v[34:37]
	v_mfma_f32_16x16x32_bf16 v[22:25], v[152:155], v[218:221], v[22:25]
	v_mfma_f32_16x16x32_bf16 v[18:21], v[160:163], v[218:221], v[18:21]
	v_mfma_f32_16x16x32_bf16 v[6:9], v[152:155], v[222:225], v[6:9]
	v_mfma_f32_16x16x32_bf16 v[2:5], v[160:163], v[222:225], v[2:5]
	s_setprio 0
	s_barrier
	s_add_i32 s43, 0, 0x18000
	s_add_i32 s46, 0, 0x1c000
	ds_read_b128 v[132:135], v245 offset:32768
	ds_read_b128 v[136:139], v246 offset:32768
	ds_read_b128 v[140:143], v245 offset:34816
	ds_read_b128 v[144:147], v246 offset:34816
	ds_read_b128 v[148:151], v245 offset:49152
	ds_read_b128 v[152:155], v246 offset:49152
	ds_read_b128 v[156:159], v245 offset:51200
	ds_read_b128 v[160:163], v246 offset:51200
	s_add_u32 s44, vcc_lo, 0x40000
	s_addc_u32 s45, vcc_hi, 0
	s_mov_b32 m0, s94
	ds_read_b128 v[164:167], v215 offset:32768
	ds_read_b128 v[190:193], v215 offset:34816
	ds_read_b128 v[194:197], v216 offset:32768
	ds_read_b128 v[198:201], v216 offset:34816
	ds_read_b128 v[202:205], v215 offset:36864
	ds_read_b128 v[206:209], v215 offset:38912
	ds_read_b128 v[218:221], v216 offset:36864
	ds_read_b128 v[222:225], v216 offset:38912
	global_load_lds_dwordx4 v174, s[44:45]
	s_mov_b32 m0, s95
	s_nop 0
	global_load_lds_dwordx4 v176, s[44:45]
	s_waitcnt vmcnt(8)
	s_waitcnt lgkmcnt(0)
	s_barrier
	s_setprio 1
	s_waitcnt lgkmcnt(0)
	v_mfma_f32_16x16x32_bf16 v[126:129], v[132:135], v[164:167], v[126:129]
	v_mfma_f32_16x16x32_bf16 v[122:125], v[140:143], v[164:167], v[122:125]
	v_mfma_f32_16x16x32_bf16 v[110:113], v[132:135], v[190:193], v[110:113]
	v_mfma_f32_16x16x32_bf16 v[106:109], v[140:143], v[190:193], v[106:109]
	v_mfma_f32_16x16x32_bf16 v[94:97], v[132:135], v[202:205], v[94:97]
	v_mfma_f32_16x16x32_bf16 v[90:93], v[140:143], v[202:205], v[90:93]
	v_mfma_f32_16x16x32_bf16 v[78:81], v[132:135], v[206:209], v[78:81]
	v_mfma_f32_16x16x32_bf16 v[74:77], v[140:143], v[206:209], v[74:77]
	v_mfma_f32_16x16x32_bf16 v[126:129], v[136:139], v[194:197], v[126:129]
	v_mfma_f32_16x16x32_bf16 v[122:125], v[144:147], v[194:197], v[122:125]
	v_mfma_f32_16x16x32_bf16 v[110:113], v[136:139], v[198:201], v[110:113]
	v_mfma_f32_16x16x32_bf16 v[106:109], v[144:147], v[198:201], v[106:109]
	v_mfma_f32_16x16x32_bf16 v[94:97], v[136:139], v[218:221], v[94:97]
	v_mfma_f32_16x16x32_bf16 v[90:93], v[144:147], v[218:221], v[90:93]
	v_mfma_f32_16x16x32_bf16 v[78:81], v[136:139], v[222:225], v[78:81]
	v_mfma_f32_16x16x32_bf16 v[74:77], v[144:147], v[222:225], v[74:77]
	s_setprio 0
	s_setprio 1
	v_mfma_f32_16x16x32_bf16 v[118:121], v[148:151], v[164:167], v[118:121]
	v_mfma_f32_16x16x32_bf16 v[114:117], v[156:159], v[164:167], v[114:117]
	v_mfma_f32_16x16x32_bf16 v[102:105], v[148:151], v[190:193], v[102:105]
	v_mfma_f32_16x16x32_bf16 v[98:101], v[156:159], v[190:193], v[98:101]
	v_mfma_f32_16x16x32_bf16 v[86:89], v[148:151], v[202:205], v[86:89]
	v_mfma_f32_16x16x32_bf16 v[82:85], v[156:159], v[202:205], v[82:85]
	v_mfma_f32_16x16x32_bf16 v[70:73], v[148:151], v[206:209], v[70:73]
	v_mfma_f32_16x16x32_bf16 v[66:69], v[156:159], v[206:209], v[66:69]
	v_mfma_f32_16x16x32_bf16 v[118:121], v[152:155], v[194:197], v[118:121]
	v_mfma_f32_16x16x32_bf16 v[114:117], v[160:163], v[194:197], v[114:117]
	v_mfma_f32_16x16x32_bf16 v[102:105], v[152:155], v[198:201], v[102:105]
	v_mfma_f32_16x16x32_bf16 v[98:101], v[160:163], v[198:201], v[98:101]
	v_mfma_f32_16x16x32_bf16 v[86:89], v[152:155], v[218:221], v[86:89]
	v_mfma_f32_16x16x32_bf16 v[82:85], v[160:163], v[218:221], v[82:85]
	v_mfma_f32_16x16x32_bf16 v[70:73], v[152:155], v[222:225], v[70:73]
	v_mfma_f32_16x16x32_bf16 v[66:69], v[160:163], v[222:225], v[66:69]
	s_setprio 0
	s_barrier
	s_add_i32 s43, s43, s15
	s_add_i32 m0, s43, 0xffffff80
	ds_read_b128 v[164:167], v215 offset:49152
	ds_read_b128 v[190:193], v215 offset:51200
	ds_read_b128 v[194:197], v216 offset:49152
	ds_read_b128 v[198:201], v216 offset:51200
	ds_read_b128 v[202:205], v215 offset:53248
	ds_read_b128 v[206:209], v215 offset:55296
	ds_read_b128 v[218:221], v216 offset:53248
	ds_read_b128 v[222:225], v216 offset:55296
	global_load_lds_dwordx4 v170, s[86:87] offset:128
	s_add_i32 m0, s43, 0x1f80
	s_add_u32 s44, s86, 0x40080
	s_addc_u32 s45, s87, 0
	s_add_i32 s43, s46, s15
	global_load_lds_dwordx4 v178, s[86:87] offset:128
	s_mov_b32 m0, s43
	s_nop 0
	global_load_lds_dwordx4 v170, s[44:45]
	s_add_i32 m0, s43, 0x2000
	s_nop 0
	global_load_lds_dwordx4 v178, s[44:45]
	s_add_i32 m0, s80, 0xffffff80
	s_nop 0
	global_load_lds_dwordx4 v174, vcc offset:128
	s_add_i32 m0, s81, 0xffffff80
	s_nop 0
	global_load_lds_dwordx4 v176, vcc offset:128
	s_waitcnt vmcnt(8)
	s_waitcnt lgkmcnt(0)
	s_barrier
	s_setprio 1
	s_waitcnt lgkmcnt(0)
	v_mfma_f32_16x16x32_bf16 v[62:65], v[132:135], v[164:167], v[62:65]
	v_mfma_f32_16x16x32_bf16 v[58:61], v[140:143], v[164:167], v[58:61]
	v_mfma_f32_16x16x32_bf16 v[46:49], v[132:135], v[190:193], v[46:49]
	v_mfma_f32_16x16x32_bf16 v[42:45], v[140:143], v[190:193], v[42:45]
	v_mfma_f32_16x16x32_bf16 v[30:33], v[132:135], v[202:205], v[30:33]
	v_mfma_f32_16x16x32_bf16 v[26:29], v[140:143], v[202:205], v[26:29]
	v_mfma_f32_16x16x32_bf16 v[14:17], v[132:135], v[206:209], v[14:17]
	v_mfma_f32_16x16x32_bf16 v[10:13], v[140:143], v[206:209], v[10:13]
	v_mfma_f32_16x16x32_bf16 v[62:65], v[136:139], v[194:197], v[62:65]
	v_mfma_f32_16x16x32_bf16 v[58:61], v[144:147], v[194:197], v[58:61]
	v_mfma_f32_16x16x32_bf16 v[46:49], v[136:139], v[198:201], v[46:49]
	v_mfma_f32_16x16x32_bf16 v[42:45], v[144:147], v[198:201], v[42:45]
	v_mfma_f32_16x16x32_bf16 v[30:33], v[136:139], v[218:221], v[30:33]
	v_mfma_f32_16x16x32_bf16 v[26:29], v[144:147], v[218:221], v[26:29]
	v_mfma_f32_16x16x32_bf16 v[14:17], v[136:139], v[222:225], v[14:17]
	v_mfma_f32_16x16x32_bf16 v[10:13], v[144:147], v[222:225], v[10:13]
	s_setprio 0
	s_setprio 1
	v_mfma_f32_16x16x32_bf16 v[54:57], v[148:151], v[164:167], v[54:57]
	v_mfma_f32_16x16x32_bf16 v[50:53], v[156:159], v[164:167], v[50:53]
	v_mfma_f32_16x16x32_bf16 v[38:41], v[148:151], v[190:193], v[38:41]
	v_mfma_f32_16x16x32_bf16 v[34:37], v[156:159], v[190:193], v[34:37]
	v_mfma_f32_16x16x32_bf16 v[22:25], v[148:151], v[202:205], v[22:25]
	v_mfma_f32_16x16x32_bf16 v[18:21], v[156:159], v[202:205], v[18:21]
	v_mfma_f32_16x16x32_bf16 v[6:9], v[148:151], v[206:209], v[6:9]
	v_mfma_f32_16x16x32_bf16 v[2:5], v[156:159], v[206:209], v[2:5]
	v_mfma_f32_16x16x32_bf16 v[54:57], v[152:155], v[194:197], v[54:57]
	v_mfma_f32_16x16x32_bf16 v[50:53], v[160:163], v[194:197], v[50:53]
	v_mfma_f32_16x16x32_bf16 v[38:41], v[152:155], v[198:201], v[38:41]
	v_mfma_f32_16x16x32_bf16 v[34:37], v[160:163], v[198:201], v[34:37]
	v_mfma_f32_16x16x32_bf16 v[22:25], v[152:155], v[218:221], v[22:25]
	v_mfma_f32_16x16x32_bf16 v[18:21], v[160:163], v[218:221], v[18:21]
	v_mfma_f32_16x16x32_bf16 v[6:9], v[152:155], v[222:225], v[6:9]
	v_mfma_f32_16x16x32_bf16 v[2:5], v[160:163], v[222:225], v[2:5]
	s_setprio 0
	s_barrier
	s_add_i32 s42, s42, 2
	s_add_u32 s10, s10, 0x100
	s_addc_u32 s11, s11, 0
	s_add_u32 s68, s68, 0x100
	s_addc_u32 s69, s69, 0
	s_cmp_gt_u32 s42, 13
	s_cbranch_scc1 .LBB0_688
	s_branch .LBB0_685

.LBB0_1315:
	s_lshl_b32 s44, s66, 10
	s_lshl_b32 s42, s67, 8
	s_add_i32 s69, s44, 0
	s_add_i32 s68, s39, -2
	s_ashr_i32 s43, s42, 31
	s_add_i32 s69, s69, 0x20800
	s_cmp_lt_i32 s28, 3
	s_cselect_b32 s44, s93, s61
	s_cselect_b32 s45, s92, s60
	s_lshl_b64 s[42:43], s[42:43], 2
	s_add_u32 s42, s45, s42
	s_addc_u32 s43, s44, s43
	s_add_u32 s12, s12, 0x18080
	s_addc_u32 s13, s13, 0
	s_add_u32 s48, s78, 0x100
	v_add_u32_e32 v245, 0x10000, v209
	v_add_u32_e32 v246, 0x10000, v210
	s_mov_b32 s100, 1
	v_lshl_add_u64 v[130:131], s[42:43], 0, v[188:189]
	s_addc_u32 s72, s79, 0
	s_mov_b32 s42, 0
	s_branch .LBB0_1317
.LBB0_1316:
	s_cmp_lg_u32 s100, 0
	s_cbranch_scc1 .Lpeel_3
	ds_read_b128 v[132:135], v245
	ds_read_b128 v[136:139], v246
	ds_read_b128 v[140:143], v245 offset:2048
	ds_read_b128 v[144:147], v246 offset:2048
	ds_read_b128 v[148:151], v245 offset:16384
	ds_read_b128 v[152:155], v246 offset:16384
	ds_read_b128 v[156:159], v245 offset:18432
	ds_read_b128 v[160:163], v246 offset:18432
	s_add_i32 s42, s42, 2
	s_add_u32 s43, s12, 0xfffe8080
	s_addc_u32 s46, s13, -1
	s_and_b64 s[44:45], s[78:79], exec
	s_cselect_b32 s81, s75, s46
	s_cselect_b32 s80, s74, s43
	s_cselect_b32 s79, s77, s72
	s_cselect_b32 s78, s76, s48
	s_add_i32 m0, s63, 0xc000
	ds_read_b128 v[164:167], v211
	ds_read_b128 v[190:193], v211 offset:2048
	s_waitcnt lgkmcnt(0)
	ds_read_b128 v[194:197], v212
	ds_read_b128 v[198:201], v212 offset:2048
	ds_read_b128 v[202:205], v211 offset:4096
	ds_read_b128 v[214:217], v211 offset:6144
	ds_read_b128 v[218:221], v212 offset:4096
	ds_read_b128 v[222:225], v212 offset:6144
	global_load_lds_dwordx4 v178, s[12:13]
	s_add_i32 m0, s63, 0xe000
	s_nop 0
	global_load_lds_dwordx4 v182, s[12:13]
	s_waitcnt vmcnt(8)
	s_waitcnt lgkmcnt(0)
	s_barrier
	s_setprio 1
	s_waitcnt lgkmcnt(0)
	v_mfma_f32_16x16x32_bf16 v[126:129], v[132:135], v[164:167], v[126:129]
	v_mfma_f32_16x16x32_bf16 v[122:125], v[140:143], v[164:167], v[122:125]
	v_mfma_f32_16x16x32_bf16 v[110:113], v[132:135], v[190:193], v[110:113]
	v_mfma_f32_16x16x32_bf16 v[106:109], v[140:143], v[190:193], v[106:109]
	v_mfma_f32_16x16x32_bf16 v[94:97], v[132:135], v[202:205], v[94:97]
	v_mfma_f32_16x16x32_bf16 v[90:93], v[140:143], v[202:205], v[90:93]
	v_mfma_f32_16x16x32_bf16 v[78:81], v[132:135], v[214:217], v[78:81]
	v_mfma_f32_16x16x32_bf16 v[74:77], v[140:143], v[214:217], v[74:77]
	v_mfma_f32_16x16x32_bf16 v[126:129], v[136:139], v[194:197], v[126:129]
	v_mfma_f32_16x16x32_bf16 v[122:125], v[144:147], v[194:197], v[122:125]
	v_mfma_f32_16x16x32_bf16 v[110:113], v[136:139], v[198:201], v[110:113]
	v_mfma_f32_16x16x32_bf16 v[106:109], v[144:147], v[198:201], v[106:109]
	v_mfma_f32_16x16x32_bf16 v[94:97], v[136:139], v[218:221], v[94:97]
	v_mfma_f32_16x16x32_bf16 v[90:93], v[144:147], v[218:221], v[90:93]
	v_mfma_f32_16x16x32_bf16 v[78:81], v[136:139], v[222:225], v[78:81]
	v_mfma_f32_16x16x32_bf16 v[74:77], v[144:147], v[222:225], v[74:77]
	s_setprio 0
	s_setprio 1
	v_mfma_f32_16x16x32_bf16 v[118:121], v[148:151], v[164:167], v[118:121]
	v_mfma_f32_16x16x32_bf16 v[114:117], v[156:159], v[164:167], v[114:117]
	v_mfma_f32_16x16x32_bf16 v[102:105], v[148:151], v[190:193], v[102:105]
	v_mfma_f32_16x16x32_bf16 v[98:101], v[156:159], v[190:193], v[98:101]
	v_mfma_f32_16x16x32_bf16 v[86:89], v[148:151], v[202:205], v[86:89]
	v_mfma_f32_16x16x32_bf16 v[82:85], v[156:159], v[202:205], v[82:85]
	v_mfma_f32_16x16x32_bf16 v[70:73], v[148:151], v[214:217], v[70:73]
	v_mfma_f32_16x16x32_bf16 v[66:69], v[156:159], v[214:217], v[66:69]
	v_mfma_f32_16x16x32_bf16 v[118:121], v[152:155], v[194:197], v[118:121]
	v_mfma_f32_16x16x32_bf16 v[114:117], v[160:163], v[194:197], v[114:117]
	v_mfma_f32_16x16x32_bf16 v[102:105], v[152:155], v[198:201], v[102:105]
	v_mfma_f32_16x16x32_bf16 v[98:101], v[160:163], v[198:201], v[98:101]
	v_mfma_f32_16x16x32_bf16 v[86:89], v[152:155], v[218:221], v[86:89]
	v_mfma_f32_16x16x32_bf16 v[82:85], v[160:163], v[218:221], v[82:85]
	v_mfma_f32_16x16x32_bf16 v[70:73], v[152:155], v[222:225], v[70:73]
	v_mfma_f32_16x16x32_bf16 v[66:69], v[160:163], v[222:225], v[66:69]
	s_setprio 0
	s_barrier
	s_add_i32 s43, s96, s62
	s_mov_b32 m0, s43
	ds_read_b128 v[164:167], v211 offset:16384
	ds_read_b128 v[190:193], v211 offset:18432
	ds_read_b128 v[194:197], v212 offset:16384
	ds_read_b128 v[198:201], v212 offset:18432
	ds_read_b128 v[202:205], v211 offset:20480
	ds_read_b128 v[214:217], v211 offset:22528
	ds_read_b128 v[218:221], v212 offset:20480
	ds_read_b128 v[222:225], v212 offset:22528
	global_load_lds_dwordx4 v170, s[78:79]
	s_add_i32 m0, s43, 0x2000
	s_add_u32 s44, s78, 0x18000
	s_addc_u32 s45, s79, 0
	s_add_i32 s43, s83, s62
	global_load_lds_dwordx4 v176, s[78:79]
	s_mov_b32 m0, s43
	s_nop 0
	global_load_lds_dwordx4 v170, s[44:45]
	s_add_i32 m0, s43, 0x2000
	s_nop 0
	global_load_lds_dwordx4 v176, s[44:45]
	s_mov_b32 m0, s63
	s_nop 0
	global_load_lds_dwordx4 v172, s[80:81]
	s_mov_b32 m0, s64
	s_nop 0
	global_load_lds_dwordx4 v174, s[80:81]
	s_waitcnt vmcnt(8)
	s_waitcnt lgkmcnt(0)
	s_barrier
	s_setprio 1
	s_waitcnt lgkmcnt(0)
	v_mfma_f32_16x16x32_bf16 v[62:65], v[132:135], v[164:167], v[62:65]
	v_mfma_f32_16x16x32_bf16 v[58:61], v[140:143], v[164:167], v[58:61]
	v_mfma_f32_16x16x32_bf16 v[46:49], v[132:135], v[190:193], v[46:49]
	v_mfma_f32_16x16x32_bf16 v[42:45], v[140:143], v[190:193], v[42:45]
	v_mfma_f32_16x16x32_bf16 v[30:33], v[132:135], v[202:205], v[30:33]
	v_mfma_f32_16x16x32_bf16 v[26:29], v[140:143], v[202:205], v[26:29]
	v_mfma_f32_16x16x32_bf16 v[14:17], v[132:135], v[214:217], v[14:17]
	v_mfma_f32_16x16x32_bf16 v[10:13], v[140:143], v[214:217], v[10:13]
	v_mfma_f32_16x16x32_bf16 v[62:65], v[136:139], v[194:197], v[62:65]
	v_mfma_f32_16x16x32_bf16 v[58:61], v[144:147], v[194:197], v[58:61]
	v_mfma_f32_16x16x32_bf16 v[46:49], v[136:139], v[198:201], v[46:49]
	v_mfma_f32_16x16x32_bf16 v[42:45], v[144:147], v[198:201], v[42:45]
	v_mfma_f32_16x16x32_bf16 v[30:33], v[136:139], v[218:221], v[30:33]
	v_mfma_f32_16x16x32_bf16 v[26:29], v[144:147], v[218:221], v[26:29]
	v_mfma_f32_16x16x32_bf16 v[14:17], v[136:139], v[222:225], v[14:17]
	v_mfma_f32_16x16x32_bf16 v[10:13], v[144:147], v[222:225], v[10:13]
	s_setprio 0
	s_setprio 1
	v_mfma_f32_16x16x32_bf16 v[54:57], v[148:151], v[164:167], v[54:57]
	v_mfma_f32_16x16x32_bf16 v[50:53], v[156:159], v[164:167], v[50:53]
	v_mfma_f32_16x16x32_bf16 v[38:41], v[148:151], v[190:193], v[38:41]
	v_mfma_f32_16x16x32_bf16 v[34:37], v[156:159], v[190:193], v[34:37]
	v_mfma_f32_16x16x32_bf16 v[22:25], v[148:151], v[202:205], v[22:25]
	v_mfma_f32_16x16x32_bf16 v[18:21], v[156:159], v[202:205], v[18:21]
	v_mfma_f32_16x16x32_bf16 v[6:9], v[148:151], v[214:217], v[6:9]
	v_mfma_f32_16x16x32_bf16 v[2:5], v[156:159], v[214:217], v[2:5]
	v_mfma_f32_16x16x32_bf16 v[54:57], v[152:155], v[194:197], v[54:57]
	v_mfma_f32_16x16x32_bf16 v[50:53], v[160:163], v[194:197], v[50:53]
	v_mfma_f32_16x16x32_bf16 v[38:41], v[152:155], v[198:201], v[38:41]
	v_mfma_f32_16x16x32_bf16 v[34:37], v[160:163], v[198:201], v[34:37]
	v_mfma_f32_16x16x32_bf16 v[22:25], v[152:155], v[218:221], v[22:25]
	v_mfma_f32_16x16x32_bf16 v[18:21], v[160:163], v[218:221], v[18:21]
	v_mfma_f32_16x16x32_bf16 v[6:9], v[152:155], v[222:225], v[6:9]
	v_mfma_f32_16x16x32_bf16 v[2:5], v[160:163], v[222:225], v[2:5]
	s_setprio 0
	s_barrier
	s_add_i32 s43, 0, 0x18000
	s_add_i32 s46, 0, 0x1c000
	ds_read_b128 v[132:135], v245 offset:32768
	ds_read_b128 v[136:139], v246 offset:32768
	ds_read_b128 v[140:143], v245 offset:34816
	ds_read_b128 v[144:147], v246 offset:34816
	ds_read_b128 v[148:151], v245 offset:49152
	ds_read_b128 v[152:155], v246 offset:49152
	ds_read_b128 v[156:159], v245 offset:51200
	ds_read_b128 v[160:163], v246 offset:51200
	s_add_u32 s44, s80, 0x18000
	s_addc_u32 s45, s81, 0
	s_mov_b32 m0, s65
	ds_read_b128 v[164:167], v211 offset:32768
	ds_read_b128 v[190:193], v211 offset:34816
	ds_read_b128 v[194:197], v212 offset:32768
	ds_read_b128 v[198:201], v212 offset:34816
	ds_read_b128 v[202:205], v211 offset:36864
	ds_read_b128 v[214:217], v211 offset:38912
	ds_read_b128 v[218:221], v212 offset:36864
	ds_read_b128 v[222:225], v212 offset:38912
	global_load_lds_dwordx4 v172, s[44:45]
	s_mov_b32 m0, s82
	s_nop 0
	global_load_lds_dwordx4 v174, s[44:45]
	s_waitcnt vmcnt(8)
	s_waitcnt lgkmcnt(0)
	s_barrier
	s_setprio 1
	s_waitcnt lgkmcnt(0)
	v_mfma_f32_16x16x32_bf16 v[126:129], v[132:135], v[164:167], v[126:129]
	v_mfma_f32_16x16x32_bf16 v[122:125], v[140:143], v[164:167], v[122:125]
	v_mfma_f32_16x16x32_bf16 v[110:113], v[132:135], v[190:193], v[110:113]
	v_mfma_f32_16x16x32_bf16 v[106:109], v[140:143], v[190:193], v[106:109]
	v_mfma_f32_16x16x32_bf16 v[94:97], v[132:135], v[202:205], v[94:97]
	v_mfma_f32_16x16x32_bf16 v[90:93], v[140:143], v[202:205], v[90:93]
	v_mfma_f32_16x16x32_bf16 v[78:81], v[132:135], v[214:217], v[78:81]
	v_mfma_f32_16x16x32_bf16 v[74:77], v[140:143], v[214:217], v[74:77]
	v_mfma_f32_16x16x32_bf16 v[126:129], v[136:139], v[194:197], v[126:129]
	v_mfma_f32_16x16x32_bf16 v[122:125], v[144:147], v[194:197], v[122:125]
	v_mfma_f32_16x16x32_bf16 v[110:113], v[136:139], v[198:201], v[110:113]
	v_mfma_f32_16x16x32_bf16 v[106:109], v[144:147], v[198:201], v[106:109]
	v_mfma_f32_16x16x32_bf16 v[94:97], v[136:139], v[218:221], v[94:97]
	v_mfma_f32_16x16x32_bf16 v[90:93], v[144:147], v[218:221], v[90:93]
	v_mfma_f32_16x16x32_bf16 v[78:81], v[136:139], v[222:225], v[78:81]
	v_mfma_f32_16x16x32_bf16 v[74:77], v[144:147], v[222:225], v[74:77]
	s_setprio 0
	s_setprio 1
	v_mfma_f32_16x16x32_bf16 v[118:121], v[148:151], v[164:167], v[118:121]
	v_mfma_f32_16x16x32_bf16 v[114:117], v[156:159], v[164:167], v[114:117]
	v_mfma_f32_16x16x32_bf16 v[102:105], v[148:151], v[190:193], v[102:105]
	v_mfma_f32_16x16x32_bf16 v[98:101], v[156:159], v[190:193], v[98:101]
	v_mfma_f32_16x16x32_bf16 v[86:89], v[148:151], v[202:205], v[86:89]
	v_mfma_f32_16x16x32_bf16 v[82:85], v[156:159], v[202:205], v[82:85]
	v_mfma_f32_16x16x32_bf16 v[70:73], v[148:151], v[214:217], v[70:73]
	v_mfma_f32_16x16x32_bf16 v[66:69], v[156:159], v[214:217], v[66:69]
	v_mfma_f32_16x16x32_bf16 v[118:121], v[152:155], v[194:197], v[118:121]
	v_mfma_f32_16x16x32_bf16 v[114:117], v[160:163], v[194:197], v[114:117]
	v_mfma_f32_16x16x32_bf16 v[102:105], v[152:155], v[198:201], v[102:105]
	v_mfma_f32_16x16x32_bf16 v[98:101], v[160:163], v[198:201], v[98:101]
	v_mfma_f32_16x16x32_bf16 v[86:89], v[152:155], v[218:221], v[86:89]
	v_mfma_f32_16x16x32_bf16 v[82:85], v[160:163], v[218:221], v[82:85]
	v_mfma_f32_16x16x32_bf16 v[70:73], v[152:155], v[222:225], v[70:73]
	v_mfma_f32_16x16x32_bf16 v[66:69], v[160:163], v[222:225], v[66:69]
	s_setprio 0
	s_barrier
	s_add_i32 s43, s43, s62
	s_add_i32 m0, s43, 0xffffff80
	ds_read_b128 v[164:167], v211 offset:49152
	ds_read_b128 v[190:193], v211 offset:51200
	ds_read_b128 v[194:197], v212 offset:49152
	ds_read_b128 v[198:201], v212 offset:51200
	ds_read_b128 v[202:205], v211 offset:53248
	ds_read_b128 v[214:217], v211 offset:55296
	ds_read_b128 v[218:221], v212 offset:53248
	ds_read_b128 v[222:225], v212 offset:55296
	global_load_lds_dwordx4 v170, s[78:79] offset:128
	s_add_i32 m0, s43, 0x1f80
	s_add_u32 s44, s78, 0x18080
	s_addc_u32 s45, s79, 0
	s_add_i32 s43, s46, s62
	global_load_lds_dwordx4 v176, s[78:79] offset:128
	s_mov_b32 m0, s43
	s_nop 0
	global_load_lds_dwordx4 v170, s[44:45]
	s_add_i32 m0, s43, 0x2000
	s_nop 0
	global_load_lds_dwordx4 v176, s[44:45]
	s_add_i32 m0, s89, 0xffffff80
	s_nop 0
	global_load_lds_dwordx4 v172, s[80:81] offset:128
	s_add_i32 m0, s91, 0xffffff80
	s_nop 0
	global_load_lds_dwordx4 v174, s[80:81] offset:128
	s_waitcnt vmcnt(8)
	s_waitcnt lgkmcnt(0)
	s_barrier
	s_setprio 1
	s_waitcnt lgkmcnt(0)
	v_mfma_f32_16x16x32_bf16 v[62:65], v[132:135], v[164:167], v[62:65]
	v_mfma_f32_16x16x32_bf16 v[58:61], v[140:143], v[164:167], v[58:61]
	v_mfma_f32_16x16x32_bf16 v[46:49], v[132:135], v[190:193], v[46:49]
	v_mfma_f32_16x16x32_bf16 v[42:45], v[140:143], v[190:193], v[42:45]
	v_mfma_f32_16x16x32_bf16 v[30:33], v[132:135], v[202:205], v[30:33]
	v_mfma_f32_16x16x32_bf16 v[26:29], v[140:143], v[202:205], v[26:29]
	v_mfma_f32_16x16x32_bf16 v[14:17], v[132:135], v[214:217], v[14:17]
	v_mfma_f32_16x16x32_bf16 v[10:13], v[140:143], v[214:217], v[10:13]
	v_mfma_f32_16x16x32_bf16 v[62:65], v[136:139], v[194:197], v[62:65]
	v_mfma_f32_16x16x32_bf16 v[58:61], v[144:147], v[194:197], v[58:61]
	v_mfma_f32_16x16x32_bf16 v[46:49], v[136:139], v[198:201], v[46:49]
	v_mfma_f32_16x16x32_bf16 v[42:45], v[144:147], v[198:201], v[42:45]
	v_mfma_f32_16x16x32_bf16 v[30:33], v[136:139], v[218:221], v[30:33]
	v_mfma_f32_16x16x32_bf16 v[26:29], v[144:147], v[218:221], v[26:29]
	v_mfma_f32_16x16x32_bf16 v[14:17], v[136:139], v[222:225], v[14:17]
	v_mfma_f32_16x16x32_bf16 v[10:13], v[144:147], v[222:225], v[10:13]
	s_setprio 0
	s_setprio 1
	v_mfma_f32_16x16x32_bf16 v[54:57], v[148:151], v[164:167], v[54:57]
	v_mfma_f32_16x16x32_bf16 v[50:53], v[156:159], v[164:167], v[50:53]
	v_mfma_f32_16x16x32_bf16 v[38:41], v[148:151], v[190:193], v[38:41]
	v_mfma_f32_16x16x32_bf16 v[34:37], v[156:159], v[190:193], v[34:37]
	v_mfma_f32_16x16x32_bf16 v[22:25], v[148:151], v[202:205], v[22:25]
	v_mfma_f32_16x16x32_bf16 v[18:21], v[156:159], v[202:205], v[18:21]
	v_mfma_f32_16x16x32_bf16 v[6:9], v[148:151], v[214:217], v[6:9]
	v_mfma_f32_16x16x32_bf16 v[2:5], v[156:159], v[214:217], v[2:5]
	v_mfma_f32_16x16x32_bf16 v[54:57], v[152:155], v[194:197], v[54:57]
	v_mfma_f32_16x16x32_bf16 v[50:53], v[160:163], v[194:197], v[50:53]
	v_mfma_f32_16x16x32_bf16 v[38:41], v[152:155], v[198:201], v[38:41]
	v_mfma_f32_16x16x32_bf16 v[34:37], v[160:163], v[198:201], v[34:37]
	v_mfma_f32_16x16x32_bf16 v[22:25], v[152:155], v[218:221], v[22:25]
	v_mfma_f32_16x16x32_bf16 v[18:21], v[160:163], v[218:221], v[18:21]
	v_mfma_f32_16x16x32_bf16 v[6:9], v[152:155], v[222:225], v[6:9]
	v_mfma_f32_16x16x32_bf16 v[2:5], v[160:163], v[222:225], v[2:5]
	s_setprio 0
	s_barrier
	s_add_u32 s12, s12, 0x100
	s_addc_u32 s13, s13, 0
	s_add_u32 s48, s48, 0x100
	s_addc_u32 s72, s72, 0
	s_cmp_ge_i32 s42, s39
	s_cbranch_scc1 .LBB0_1320

.Lpeel_3:
	s_mov_b32 s100, 0
	ds_read_b128 v[132:135], v245
	ds_read_b128 v[136:139], v246
	ds_read_b128 v[140:143], v245 offset:2048
	ds_read_b128 v[144:147], v246 offset:2048
	ds_read_b128 v[148:151], v245 offset:16384
	ds_read_b128 v[152:155], v246 offset:16384
	ds_read_b128 v[156:159], v245 offset:18432
	ds_read_b128 v[160:163], v246 offset:18432
	s_add_i32 s42, s42, 2
	s_add_u32 s43, s12, 0xfffe8080
	s_addc_u32 s46, s13, -1
	s_and_b64 s[44:45], s[78:79], exec
	s_cselect_b32 s81, s75, s46
	s_cselect_b32 s80, s74, s43
	s_cselect_b32 s79, s77, s72
	s_cselect_b32 s78, s76, s48
	s_add_i32 m0, s63, 0xc000
	ds_read_b128 v[164:167], v211
	ds_read_b128 v[190:193], v211 offset:2048
	s_waitcnt lgkmcnt(0)
	ds_read_b128 v[194:197], v212
	ds_read_b128 v[198:201], v212 offset:2048
	ds_read_b128 v[202:205], v211 offset:4096
	ds_read_b128 v[214:217], v211 offset:6144
	ds_read_b128 v[218:221], v212 offset:4096
	ds_read_b128 v[222:225], v212 offset:6144
	global_load_lds_dwordx4 v178, s[12:13]
	s_add_i32 m0, s63, 0xe000
	s_nop 0
	global_load_lds_dwordx4 v182, s[12:13]
	s_waitcnt vmcnt(8)
	s_waitcnt lgkmcnt(0)
	s_barrier
	s_setprio 1
	s_waitcnt lgkmcnt(0)
	v_mfma_f32_16x16x32_bf16 v[126:129], v[132:135], v[164:167], 0
	v_mfma_f32_16x16x32_bf16 v[122:125], v[140:143], v[164:167], 0
	v_mfma_f32_16x16x32_bf16 v[110:113], v[132:135], v[190:193], 0
	v_mfma_f32_16x16x32_bf16 v[106:109], v[140:143], v[190:193], 0
	v_mfma_f32_16x16x32_bf16 v[94:97], v[132:135], v[202:205], 0
	v_mfma_f32_16x16x32_bf16 v[90:93], v[140:143], v[202:205], 0
	v_mfma_f32_16x16x32_bf16 v[78:81], v[132:135], v[214:217], 0
	v_mfma_f32_16x16x32_bf16 v[74:77], v[140:143], v[214:217], 0
	v_mfma_f32_16x16x32_bf16 v[126:129], v[136:139], v[194:197], v[126:129]
	v_mfma_f32_16x16x32_bf16 v[122:125], v[144:147], v[194:197], v[122:125]
	v_mfma_f32_16x16x32_bf16 v[110:113], v[136:139], v[198:201], v[110:113]
	v_mfma_f32_16x16x32_bf16 v[106:109], v[144:147], v[198:201], v[106:109]
	v_mfma_f32_16x16x32_bf16 v[94:97], v[136:139], v[218:221], v[94:97]
	v_mfma_f32_16x16x32_bf16 v[90:93], v[144:147], v[218:221], v[90:93]
	v_mfma_f32_16x16x32_bf16 v[78:81], v[136:139], v[222:225], v[78:81]
	v_mfma_f32_16x16x32_bf16 v[74:77], v[144:147], v[222:225], v[74:77]
	s_setprio 0
	s_setprio 1
	v_mfma_f32_16x16x32_bf16 v[118:121], v[148:151], v[164:167], 0
	v_mfma_f32_16x16x32_bf16 v[114:117], v[156:159], v[164:167], 0
	v_mfma_f32_16x16x32_bf16 v[102:105], v[148:151], v[190:193], 0
	v_mfma_f32_16x16x32_bf16 v[98:101], v[156:159], v[190:193], 0
	v_mfma_f32_16x16x32_bf16 v[86:89], v[148:151], v[202:205], 0
	v_mfma_f32_16x16x32_bf16 v[82:85], v[156:159], v[202:205], 0
	v_mfma_f32_16x16x32_bf16 v[70:73], v[148:151], v[214:217], 0
	v_mfma_f32_16x16x32_bf16 v[66:69], v[156:159], v[214:217], 0
	v_mfma_f32_16x16x32_bf16 v[118:121], v[152:155], v[194:197], v[118:121]
	v_mfma_f32_16x16x32_bf16 v[114:117], v[160:163], v[194:197], v[114:117]
	v_mfma_f32_16x16x32_bf16 v[102:105], v[152:155], v[198:201], v[102:105]
	v_mfma_f32_16x16x32_bf16 v[98:101], v[160:163], v[198:201], v[98:101]
	v_mfma_f32_16x16x32_bf16 v[86:89], v[152:155], v[218:221], v[86:89]
	v_mfma_f32_16x16x32_bf16 v[82:85], v[160:163], v[218:221], v[82:85]
	v_mfma_f32_16x16x32_bf16 v[70:73], v[152:155], v[222:225], v[70:73]
	v_mfma_f32_16x16x32_bf16 v[66:69], v[160:163], v[222:225], v[66:69]
	s_setprio 0
	s_barrier
	s_add_i32 s43, s96, s62
	s_mov_b32 m0, s43
	ds_read_b128 v[164:167], v211 offset:16384
	ds_read_b128 v[190:193], v211 offset:18432
	ds_read_b128 v[194:197], v212 offset:16384
	ds_read_b128 v[198:201], v212 offset:18432
	ds_read_b128 v[202:205], v211 offset:20480
	ds_read_b128 v[214:217], v211 offset:22528
	ds_read_b128 v[218:221], v212 offset:20480
	ds_read_b128 v[222:225], v212 offset:22528
	global_load_lds_dwordx4 v170, s[78:79]
	s_add_i32 m0, s43, 0x2000
	s_add_u32 s44, s78, 0x18000
	s_addc_u32 s45, s79, 0
	s_add_i32 s43, s83, s62
	global_load_lds_dwordx4 v176, s[78:79]
	s_mov_b32 m0, s43
	s_nop 0
	global_load_lds_dwordx4 v170, s[44:45]
	s_add_i32 m0, s43, 0x2000
	s_nop 0
	global_load_lds_dwordx4 v176, s[44:45]
	s_mov_b32 m0, s63
	s_nop 0
	global_load_lds_dwordx4 v172, s[80:81]
	s_mov_b32 m0, s64
	s_nop 0
	global_load_lds_dwordx4 v174, s[80:81]
	s_waitcnt vmcnt(8)
	s_waitcnt lgkmcnt(0)
	s_barrier
	s_setprio 1
	s_waitcnt lgkmcnt(0)
	v_mfma_f32_16x16x32_bf16 v[62:65], v[132:135], v[164:167], 0
	v_mfma_f32_16x16x32_bf16 v[58:61], v[140:143], v[164:167], 0
	v_mfma_f32_16x16x32_bf16 v[46:49], v[132:135], v[190:193], 0
	v_mfma_f32_16x16x32_bf16 v[42:45], v[140:143], v[190:193], 0
	v_mfma_f32_16x16x32_bf16 v[30:33], v[132:135], v[202:205], 0
	v_mfma_f32_16x16x32_bf16 v[26:29], v[140:143], v[202:205], 0
	v_mfma_f32_16x16x32_bf16 v[14:17], v[132:135], v[214:217], 0
	v_mfma_f32_16x16x32_bf16 v[10:13], v[140:143], v[214:217], 0
	v_mfma_f32_16x16x32_bf16 v[62:65], v[136:139], v[194:197], v[62:65]
	v_mfma_f32_16x16x32_bf16 v[58:61], v[144:147], v[194:197], v[58:61]
	v_mfma_f32_16x16x32_bf16 v[46:49], v[136:139], v[198:201], v[46:49]
	v_mfma_f32_16x16x32_bf16 v[42:45], v[144:147], v[198:201], v[42:45]
	v_mfma_f32_16x16x32_bf16 v[30:33], v[136:139], v[218:221], v[30:33]
	v_mfma_f32_16x16x32_bf16 v[26:29], v[144:147], v[218:221], v[26:29]
	v_mfma_f32_16x16x32_bf16 v[14:17], v[136:139], v[222:225], v[14:17]
	v_mfma_f32_16x16x32_bf16 v[10:13], v[144:147], v[222:225], v[10:13]
	s_setprio 0
	s_setprio 1
	v_mfma_f32_16x16x32_bf16 v[54:57], v[148:151], v[164:167], 0
	v_mfma_f32_16x16x32_bf16 v[50:53], v[156:159], v[164:167], 0
	v_mfma_f32_16x16x32_bf16 v[38:41], v[148:151], v[190:193], 0
	v_mfma_f32_16x16x32_bf16 v[34:37], v[156:159], v[190:193], 0
	v_mfma_f32_16x16x32_bf16 v[22:25], v[148:151], v[202:205], 0
	v_mfma_f32_16x16x32_bf16 v[18:21], v[156:159], v[202:205], 0
	v_mfma_f32_16x16x32_bf16 v[6:9], v[148:151], v[214:217], 0
	v_mfma_f32_16x16x32_bf16 v[2:5], v[156:159], v[214:217], 0
	v_mfma_f32_16x16x32_bf16 v[54:57], v[152:155], v[194:197], v[54:57]
	v_mfma_f32_16x16x32_bf16 v[50:53], v[160:163], v[194:197], v[50:53]
	v_mfma_f32_16x16x32_bf16 v[38:41], v[152:155], v[198:201], v[38:41]
	v_mfma_f32_16x16x32_bf16 v[34:37], v[160:163], v[198:201], v[34:37]
	v_mfma_f32_16x16x32_bf16 v[22:25], v[152:155], v[218:221], v[22:25]
	v_mfma_f32_16x16x32_bf16 v[18:21], v[160:163], v[218:221], v[18:21]
	v_mfma_f32_16x16x32_bf16 v[6:9], v[152:155], v[222:225], v[6:9]
	v_mfma_f32_16x16x32_bf16 v[2:5], v[160:163], v[222:225], v[2:5]
	s_setprio 0
	s_barrier
	s_add_i32 s43, 0, 0x18000
	s_add_i32 s46, 0, 0x1c000
	ds_read_b128 v[132:135], v245 offset:32768
	ds_read_b128 v[136:139], v246 offset:32768
	ds_read_b128 v[140:143], v245 offset:34816
	ds_read_b128 v[144:147], v246 offset:34816
	ds_read_b128 v[148:151], v245 offset:49152
	ds_read_b128 v[152:155], v246 offset:49152
	ds_read_b128 v[156:159], v245 offset:51200
	ds_read_b128 v[160:163], v246 offset:51200
	s_add_u32 s44, s80, 0x18000
	s_addc_u32 s45, s81, 0
	s_mov_b32 m0, s65
	ds_read_b128 v[164:167], v211 offset:32768
	ds_read_b128 v[190:193], v211 offset:34816
	ds_read_b128 v[194:197], v212 offset:32768
	ds_read_b128 v[198:201], v212 offset:34816
	ds_read_b128 v[202:205], v211 offset:36864
	ds_read_b128 v[214:217], v211 offset:38912
	ds_read_b128 v[218:221], v212 offset:36864
	ds_read_b128 v[222:225], v212 offset:38912
	global_load_lds_dwordx4 v172, s[44:45]
	s_mov_b32 m0, s82
	s_nop 0
	global_load_lds_dwordx4 v174, s[44:45]
	s_waitcnt vmcnt(8)
	s_waitcnt lgkmcnt(0)
	s_barrier
	s_setprio 1
	s_waitcnt lgkmcnt(0)
	v_mfma_f32_16x16x32_bf16 v[126:129], v[132:135], v[164:167], v[126:129]
	v_mfma_f32_16x16x32_bf16 v[122:125], v[140:143], v[164:167], v[122:125]
	v_mfma_f32_16x16x32_bf16 v[110:113], v[132:135], v[190:193], v[110:113]
	v_mfma_f32_16x16x32_bf16 v[106:109], v[140:143], v[190:193], v[106:109]
	v_mfma_f32_16x16x32_bf16 v[94:97], v[132:135], v[202:205], v[94:97]
	v_mfma_f32_16x16x32_bf16 v[90:93], v[140:143], v[202:205], v[90:93]
	v_mfma_f32_16x16x32_bf16 v[78:81], v[132:135], v[214:217], v[78:81]
	v_mfma_f32_16x16x32_bf16 v[74:77], v[140:143], v[214:217], v[74:77]
	v_mfma_f32_16x16x32_bf16 v[126:129], v[136:139], v[194:197], v[126:129]
	v_mfma_f32_16x16x32_bf16 v[122:125], v[144:147], v[194:197], v[122:125]
	v_mfma_f32_16x16x32_bf16 v[110:113], v[136:139], v[198:201], v[110:113]
	v_mfma_f32_16x16x32_bf16 v[106:109], v[144:147], v[198:201], v[106:109]
	v_mfma_f32_16x16x32_bf16 v[94:97], v[136:139], v[218:221], v[94:97]
	v_mfma_f32_16x16x32_bf16 v[90:93], v[144:147], v[218:221], v[90:93]
	v_mfma_f32_16x16x32_bf16 v[78:81], v[136:139], v[222:225], v[78:81]
	v_mfma_f32_16x16x32_bf16 v[74:77], v[144:147], v[222:225], v[74:77]
	s_setprio 0
	s_setprio 1
	v_mfma_f32_16x16x32_bf16 v[118:121], v[148:151], v[164:167], v[118:121]
	v_mfma_f32_16x16x32_bf16 v[114:117], v[156:159], v[164:167], v[114:117]
	v_mfma_f32_16x16x32_bf16 v[102:105], v[148:151], v[190:193], v[102:105]
	v_mfma_f32_16x16x32_bf16 v[98:101], v[156:159], v[190:193], v[98:101]
	v_mfma_f32_16x16x32_bf16 v[86:89], v[148:151], v[202:205], v[86:89]
	v_mfma_f32_16x16x32_bf16 v[82:85], v[156:159], v[202:205], v[82:85]
	v_mfma_f32_16x16x32_bf16 v[70:73], v[148:151], v[214:217], v[70:73]
	v_mfma_f32_16x16x32_bf16 v[66:69], v[156:159], v[214:217], v[66:69]
	v_mfma_f32_16x16x32_bf16 v[118:121], v[152:155], v[194:197], v[118:121]
	v_mfma_f32_16x16x32_bf16 v[114:117], v[160:163], v[194:197], v[114:117]
	v_mfma_f32_16x16x32_bf16 v[102:105], v[152:155], v[198:201], v[102:105]
	v_mfma_f32_16x16x32_bf16 v[98:101], v[160:163], v[198:201], v[98:101]
	v_mfma_f32_16x16x32_bf16 v[86:89], v[152:155], v[218:221], v[86:89]
	v_mfma_f32_16x16x32_bf16 v[82:85], v[160:163], v[218:221], v[82:85]
	v_mfma_f32_16x16x32_bf16 v[70:73], v[152:155], v[222:225], v[70:73]
	v_mfma_f32_16x16x32_bf16 v[66:69], v[160:163], v[222:225], v[66:69]
	s_setprio 0
	s_barrier
	s_add_i32 s43, s43, s62
	s_add_i32 m0, s43, 0xffffff80
	ds_read_b128 v[164:167], v211 offset:49152
	ds_read_b128 v[190:193], v211 offset:51200
	ds_read_b128 v[194:197], v212 offset:49152
	ds_read_b128 v[198:201], v212 offset:51200
	ds_read_b128 v[202:205], v211 offset:53248
	ds_read_b128 v[214:217], v211 offset:55296
	ds_read_b128 v[218:221], v212 offset:53248
	ds_read_b128 v[222:225], v212 offset:55296
	global_load_lds_dwordx4 v170, s[78:79] offset:128
	s_add_i32 m0, s43, 0x1f80
	s_add_u32 s44, s78, 0x18080
	s_addc_u32 s45, s79, 0
	s_add_i32 s43, s46, s62
	global_load_lds_dwordx4 v176, s[78:79] offset:128
	s_mov_b32 m0, s43
	s_nop 0
	global_load_lds_dwordx4 v170, s[44:45]
	s_add_i32 m0, s43, 0x2000
	s_nop 0
	global_load_lds_dwordx4 v176, s[44:45]
	s_add_i32 m0, s89, 0xffffff80
	s_nop 0
	global_load_lds_dwordx4 v172, s[80:81] offset:128
	s_add_i32 m0, s91, 0xffffff80
	s_nop 0
	global_load_lds_dwordx4 v174, s[80:81] offset:128
	s_waitcnt vmcnt(8)
	s_waitcnt lgkmcnt(0)
	s_barrier
	s_setprio 1
	s_waitcnt lgkmcnt(0)
	v_mfma_f32_16x16x32_bf16 v[62:65], v[132:135], v[164:167], v[62:65]
	v_mfma_f32_16x16x32_bf16 v[58:61], v[140:143], v[164:167], v[58:61]
	v_mfma_f32_16x16x32_bf16 v[46:49], v[132:135], v[190:193], v[46:49]
	v_mfma_f32_16x16x32_bf16 v[42:45], v[140:143], v[190:193], v[42:45]
	v_mfma_f32_16x16x32_bf16 v[30:33], v[132:135], v[202:205], v[30:33]
	v_mfma_f32_16x16x32_bf16 v[26:29], v[140:143], v[202:205], v[26:29]
	v_mfma_f32_16x16x32_bf16 v[14:17], v[132:135], v[214:217], v[14:17]
	v_mfma_f32_16x16x32_bf16 v[10:13], v[140:143], v[214:217], v[10:13]
	v_mfma_f32_16x16x32_bf16 v[62:65], v[136:139], v[194:197], v[62:65]
	v_mfma_f32_16x16x32_bf16 v[58:61], v[144:147], v[194:197], v[58:61]
	v_mfma_f32_16x16x32_bf16 v[46:49], v[136:139], v[198:201], v[46:49]
	v_mfma_f32_16x16x32_bf16 v[42:45], v[144:147], v[198:201], v[42:45]
	v_mfma_f32_16x16x32_bf16 v[30:33], v[136:139], v[218:221], v[30:33]
	v_mfma_f32_16x16x32_bf16 v[26:29], v[144:147], v[218:221], v[26:29]
	v_mfma_f32_16x16x32_bf16 v[14:17], v[136:139], v[222:225], v[14:17]
	v_mfma_f32_16x16x32_bf16 v[10:13], v[144:147], v[222:225], v[10:13]
	s_setprio 0
	s_setprio 1
	v_mfma_f32_16x16x32_bf16 v[54:57], v[148:151], v[164:167], v[54:57]
	v_mfma_f32_16x16x32_bf16 v[50:53], v[156:159], v[164:167], v[50:53]
	v_mfma_f32_16x16x32_bf16 v[38:41], v[148:151], v[190:193], v[38:41]
	v_mfma_f32_16x16x32_bf16 v[34:37], v[156:159], v[190:193], v[34:37]
	v_mfma_f32_16x16x32_bf16 v[22:25], v[148:151], v[202:205], v[22:25]
	v_mfma_f32_16x16x32_bf16 v[18:21], v[156:159], v[202:205], v[18:21]
	v_mfma_f32_16x16x32_bf16 v[6:9], v[148:151], v[214:217], v[6:9]
	v_mfma_f32_16x16x32_bf16 v[2:5], v[156:159], v[214:217], v[2:5]
	v_mfma_f32_16x16x32_bf16 v[54:57], v[152:155], v[194:197], v[54:57]
	v_mfma_f32_16x16x32_bf16 v[50:53], v[160:163], v[194:197], v[50:53]
	v_mfma_f32_16x16x32_bf16 v[38:41], v[152:155], v[198:201], v[38:41]
	v_mfma_f32_16x16x32_bf16 v[34:37], v[160:163], v[198:201], v[34:37]
	v_mfma_f32_16x16x32_bf16 v[22:25], v[152:155], v[218:221], v[22:25]
	v_mfma_f32_16x16x32_bf16 v[18:21], v[160:163], v[218:221], v[18:21]
	v_mfma_f32_16x16x32_bf16 v[6:9], v[152:155], v[222:225], v[6:9]
	v_mfma_f32_16x16x32_bf16 v[2:5], v[160:163], v[222:225], v[2:5]
	s_setprio 0
	s_barrier
	s_add_u32 s12, s12, 0x100
	s_addc_u32 s13, s13, 0
	s_add_u32 s48, s48, 0x100
	s_addc_u32 s72, s72, 0
	s_cmp_ge_i32 s42, s39
	s_cbranch_scc1 .LBB0_1320
	s_branch .LBB0_1317

.LBB0_1628:
	s_ashr_i32 s15, s14, 31
	s_lshl_b64 s[16:17], s[14:15], 19
	s_add_u32 s16, s3, s16
	s_addc_u32 s17, s90, s17
	s_and_b64 s[18:19], s[6:7], exec
	s_cselect_b32 s15, s17, s25
	s_cselect_b32 s21, s16, s24
	s_ashr_i32 s13, s12, 31
	s_lshl_b64 s[18:19], s[12:13], 19
	s_add_u32 s18, s38, s18
	s_addc_u32 s19, s39, s19
	s_and_b64 s[28:29], s[6:7], exec
	s_cselect_b32 s13, s19, s27
	s_cselect_b32 s23, s18, s26
	s_add_u32 s24, s24, 0x40080
	s_addc_u32 s25, s25, 0
	s_add_u32 s55, s26, 0x100
	v_add_u32_e32 v245, 0x10000, v209
	v_add_u32_e32 v246, 0x10000, v210
	s_mov_b32 s100, 1
	s_addc_u32 s56, s27, 0
	s_mov_b32 s57, -2
	s_waitcnt vmcnt(0)
.LBB0_1629:
	s_cmp_lg_u32 s100, 0
	s_cbranch_scc1 .Lpeel_4
	ds_read_b128 v[90:93], v211
	ds_read_b128 v[102:105], v212
	ds_read_b128 v[114:117], v213
	ds_read_b128 v[126:129], v214
	ds_read_b128 v[138:141], v215
	ds_read_b128 v[150:153], v216
	ds_read_b128 v[154:157], v217
	ds_read_b128 v[158:161], v218
	s_add_u32 s26, s24, 0xfffc0080
	s_addc_u32 s27, s25, -1
	s_cmp_eq_u32 s57, 12
	s_cselect_b32 s29, s15, s27
	s_cselect_b32 s28, s21, s26
	s_cselect_b32 s27, s13, s56
	s_cselect_b32 s26, s23, s55
	s_add_i32 m0, s41, 0xc000
	ds_read_b128 v[162:165], v219
	ds_read_b128 v[166:169], v219 offset:2048
	ds_read_b128 v[170:173], v220
	ds_read_b128 v[174:177], v220 offset:2048
	ds_read_b128 v[178:181], v219 offset:4096
	ds_read_b128 v[182:185], v219 offset:6144
	ds_read_b128 v[204:207], v220 offset:4096
	ds_read_b128 v[226:229], v220 offset:6144
	global_load_lds_dwordx4 v196, s[24:25]
	s_add_i32 m0, s41, 0xe000
	s_nop 0
	global_load_lds_dwordx4 v198, s[24:25]
	s_waitcnt vmcnt(8)
	s_waitcnt lgkmcnt(0)
	s_barrier
	s_setprio 1
	s_waitcnt lgkmcnt(0)
	v_mfma_f32_16x16x32_bf16 v[146:149], v[90:93], v[162:165], v[146:149]
	v_mfma_f32_16x16x32_bf16 v[142:145], v[114:117], v[162:165], v[142:145]
	v_mfma_f32_16x16x32_bf16 v[122:125], v[90:93], v[166:169], v[122:125]
	v_mfma_f32_16x16x32_bf16 v[118:121], v[114:117], v[166:169], v[118:121]
	v_mfma_f32_16x16x32_bf16 v[98:101], v[90:93], v[178:181], v[98:101]
	v_mfma_f32_16x16x32_bf16 v[94:97], v[114:117], v[178:181], v[94:97]
	v_mfma_f32_16x16x32_bf16 v[78:81], v[90:93], v[182:185], v[78:81]
	v_mfma_f32_16x16x32_bf16 v[74:77], v[114:117], v[182:185], v[74:77]
	v_mfma_f32_16x16x32_bf16 v[146:149], v[102:105], v[170:173], v[146:149]
	v_mfma_f32_16x16x32_bf16 v[142:145], v[126:129], v[170:173], v[142:145]
	v_mfma_f32_16x16x32_bf16 v[122:125], v[102:105], v[174:177], v[122:125]
	v_mfma_f32_16x16x32_bf16 v[118:121], v[126:129], v[174:177], v[118:121]
	v_mfma_f32_16x16x32_bf16 v[98:101], v[102:105], v[204:207], v[98:101]
	v_mfma_f32_16x16x32_bf16 v[94:97], v[126:129], v[204:207], v[94:97]
	v_mfma_f32_16x16x32_bf16 v[78:81], v[102:105], v[226:229], v[78:81]
	v_mfma_f32_16x16x32_bf16 v[74:77], v[126:129], v[226:229], v[74:77]
	s_setprio 0
	s_setprio 1
	v_mfma_f32_16x16x32_bf16 v[134:137], v[138:141], v[162:165], v[134:137]
	v_mfma_f32_16x16x32_bf16 v[130:133], v[154:157], v[162:165], v[130:133]
	v_mfma_f32_16x16x32_bf16 v[110:113], v[138:141], v[166:169], v[110:113]
	v_mfma_f32_16x16x32_bf16 v[106:109], v[154:157], v[166:169], v[106:109]
	v_mfma_f32_16x16x32_bf16 v[86:89], v[138:141], v[178:181], v[86:89]
	v_mfma_f32_16x16x32_bf16 v[82:85], v[154:157], v[178:181], v[82:85]
	v_mfma_f32_16x16x32_bf16 v[70:73], v[138:141], v[182:185], v[70:73]
	v_mfma_f32_16x16x32_bf16 v[66:69], v[154:157], v[182:185], v[66:69]
	v_mfma_f32_16x16x32_bf16 v[134:137], v[150:153], v[170:173], v[134:137]
	v_mfma_f32_16x16x32_bf16 v[130:133], v[158:161], v[170:173], v[130:133]
	v_mfma_f32_16x16x32_bf16 v[110:113], v[150:153], v[174:177], v[110:113]
	v_mfma_f32_16x16x32_bf16 v[106:109], v[158:161], v[174:177], v[106:109]
	v_mfma_f32_16x16x32_bf16 v[86:89], v[150:153], v[204:207], v[86:89]
	v_mfma_f32_16x16x32_bf16 v[82:85], v[158:161], v[204:207], v[82:85]
	v_mfma_f32_16x16x32_bf16 v[70:73], v[150:153], v[226:229], v[70:73]
	v_mfma_f32_16x16x32_bf16 v[66:69], v[158:161], v[226:229], v[66:69]
	s_setprio 0
	s_barrier
	s_add_i32 s58, s53, s40
	s_mov_b32 m0, s58
	ds_read_b128 v[162:165], v219 offset:16384
	ds_read_b128 v[166:169], v219 offset:18432
	ds_read_b128 v[170:173], v220 offset:16384
	ds_read_b128 v[174:177], v220 offset:18432
	ds_read_b128 v[178:181], v219 offset:20480
	ds_read_b128 v[182:185], v219 offset:22528
	ds_read_b128 v[204:207], v220 offset:20480
	ds_read_b128 v[226:229], v220 offset:22528
	global_load_lds_dwordx4 v188, s[26:27]
	s_add_i32 m0, s58, 0x2000
	s_add_u32 s58, s26, 0x40000
	v_lshl_add_u64 v[232:233], s[26:27], 0, v[192:193]
	s_addc_u32 s59, s27, 0
	s_add_i32 s60, s54, s40
	global_load_lds_dwordx4 v192, s[26:27]
	s_mov_b32 m0, s60
	v_lshl_add_u64 v[236:237], s[28:29], 0, v[190:191]
	global_load_lds_dwordx4 v188, s[58:59]
	s_add_i32 m0, s60, 0x2000
	s_nop 0
	global_load_lds_dwordx4 v192, s[58:59]
	v_lshl_add_u64 v[234:235], s[28:29], 0, v[186:187]
	s_mov_b32 m0, s41
	s_nop 0
	global_load_lds_dwordx4 v186, s[28:29]
	s_mov_b32 m0, s42
	s_nop 0
	global_load_lds_dwordx4 v190, s[28:29]
	s_waitcnt vmcnt(8)
	s_waitcnt lgkmcnt(0)
	s_barrier
	s_setprio 1
	s_waitcnt lgkmcnt(0)
	v_mfma_f32_16x16x32_bf16 v[62:65], v[90:93], v[162:165], v[62:65]
	v_mfma_f32_16x16x32_bf16 v[58:61], v[114:117], v[162:165], v[58:61]
	v_mfma_f32_16x16x32_bf16 v[46:49], v[90:93], v[166:169], v[46:49]
	v_mfma_f32_16x16x32_bf16 v[42:45], v[114:117], v[166:169], v[42:45]
	v_mfma_f32_16x16x32_bf16 v[30:33], v[90:93], v[178:181], v[30:33]
	v_mfma_f32_16x16x32_bf16 v[26:29], v[114:117], v[178:181], v[26:29]
	v_mfma_f32_16x16x32_bf16 v[14:17], v[90:93], v[182:185], v[14:17]
	v_mfma_f32_16x16x32_bf16 v[10:13], v[114:117], v[182:185], v[10:13]
	v_mfma_f32_16x16x32_bf16 v[62:65], v[102:105], v[170:173], v[62:65]
	v_mfma_f32_16x16x32_bf16 v[58:61], v[126:129], v[170:173], v[58:61]
	v_mfma_f32_16x16x32_bf16 v[46:49], v[102:105], v[174:177], v[46:49]
	v_mfma_f32_16x16x32_bf16 v[42:45], v[126:129], v[174:177], v[42:45]
	v_mfma_f32_16x16x32_bf16 v[30:33], v[102:105], v[204:207], v[30:33]
	v_mfma_f32_16x16x32_bf16 v[26:29], v[126:129], v[204:207], v[26:29]
	v_mfma_f32_16x16x32_bf16 v[14:17], v[102:105], v[226:229], v[14:17]
	v_mfma_f32_16x16x32_bf16 v[10:13], v[126:129], v[226:229], v[10:13]
	s_setprio 0
	s_setprio 1
	v_mfma_f32_16x16x32_bf16 v[54:57], v[138:141], v[162:165], v[54:57]
	v_mfma_f32_16x16x32_bf16 v[50:53], v[154:157], v[162:165], v[50:53]
	v_mfma_f32_16x16x32_bf16 v[38:41], v[138:141], v[166:169], v[38:41]
	v_mfma_f32_16x16x32_bf16 v[34:37], v[154:157], v[166:169], v[34:37]
	v_mfma_f32_16x16x32_bf16 v[22:25], v[138:141], v[178:181], v[22:25]
	v_mfma_f32_16x16x32_bf16 v[18:21], v[154:157], v[178:181], v[18:21]
	v_mfma_f32_16x16x32_bf16 v[6:9], v[138:141], v[182:185], v[6:9]
	v_mfma_f32_16x16x32_bf16 v[2:5], v[154:157], v[182:185], v[2:5]
	v_mfma_f32_16x16x32_bf16 v[54:57], v[150:153], v[170:173], v[54:57]
	v_mfma_f32_16x16x32_bf16 v[50:53], v[158:161], v[170:173], v[50:53]
	v_mfma_f32_16x16x32_bf16 v[38:41], v[150:153], v[174:177], v[38:41]
	v_mfma_f32_16x16x32_bf16 v[34:37], v[158:161], v[174:177], v[34:37]
	v_mfma_f32_16x16x32_bf16 v[22:25], v[150:153], v[204:207], v[22:25]
	v_mfma_f32_16x16x32_bf16 v[18:21], v[158:161], v[204:207], v[18:21]
	v_mfma_f32_16x16x32_bf16 v[6:9], v[150:153], v[226:229], v[6:9]
	v_mfma_f32_16x16x32_bf16 v[2:5], v[158:161], v[226:229], v[2:5]
	s_setprio 0
	s_barrier
	s_add_i32 s58, 0, 0x18000
	s_add_i32 s59, 0, 0x1c000
	ds_read_b128 v[90:93], v245 offset:32768
	ds_read_b128 v[102:105], v246 offset:32768
	ds_read_b128 v[114:117], v221
	ds_read_b128 v[126:129], v222
	ds_read_b128 v[138:141], v245 offset:49152
	ds_read_b128 v[150:153], v246 offset:49152
	ds_read_b128 v[154:157], v223
	ds_read_b128 v[158:161], v224
	s_add_u32 s28, s28, 0x40000
	s_addc_u32 s29, s29, 0
	s_mov_b32 m0, s43
	ds_read_b128 v[162:165], v219 offset:32768
	ds_read_b128 v[166:169], v219 offset:34816
	ds_read_b128 v[170:173], v220 offset:32768
	ds_read_b128 v[174:177], v220 offset:34816
	ds_read_b128 v[178:181], v219 offset:36864
	ds_read_b128 v[182:185], v219 offset:38912
	ds_read_b128 v[204:207], v220 offset:36864
	ds_read_b128 v[226:229], v220 offset:38912
	global_load_lds_dwordx4 v186, s[28:29]
	s_mov_b32 m0, s44
	s_nop 0
	global_load_lds_dwordx4 v190, s[28:29]
	s_waitcnt vmcnt(8)
	s_waitcnt lgkmcnt(0)
	s_barrier
	s_setprio 1
	s_waitcnt lgkmcnt(0)
	v_mfma_f32_16x16x32_bf16 v[146:149], v[90:93], v[162:165], v[146:149]
	v_mfma_f32_16x16x32_bf16 v[142:145], v[114:117], v[162:165], v[142:145]
	v_mfma_f32_16x16x32_bf16 v[122:125], v[90:93], v[166:169], v[122:125]
	v_mfma_f32_16x16x32_bf16 v[118:121], v[114:117], v[166:169], v[118:121]
	v_mfma_f32_16x16x32_bf16 v[98:101], v[90:93], v[178:181], v[98:101]
	v_mfma_f32_16x16x32_bf16 v[94:97], v[114:117], v[178:181], v[94:97]
	v_mfma_f32_16x16x32_bf16 v[78:81], v[90:93], v[182:185], v[78:81]
	v_mfma_f32_16x16x32_bf16 v[74:77], v[114:117], v[182:185], v[74:77]
	v_mfma_f32_16x16x32_bf16 v[146:149], v[102:105], v[170:173], v[146:149]
	v_mfma_f32_16x16x32_bf16 v[142:145], v[126:129], v[170:173], v[142:145]
	v_mfma_f32_16x16x32_bf16 v[122:125], v[102:105], v[174:177], v[122:125]
	v_mfma_f32_16x16x32_bf16 v[118:121], v[126:129], v[174:177], v[118:121]
	v_mfma_f32_16x16x32_bf16 v[98:101], v[102:105], v[204:207], v[98:101]
	v_mfma_f32_16x16x32_bf16 v[94:97], v[126:129], v[204:207], v[94:97]
	v_mfma_f32_16x16x32_bf16 v[78:81], v[102:105], v[226:229], v[78:81]
	v_mfma_f32_16x16x32_bf16 v[74:77], v[126:129], v[226:229], v[74:77]
	s_setprio 0
	s_setprio 1
	v_mfma_f32_16x16x32_bf16 v[134:137], v[138:141], v[162:165], v[134:137]
	v_mfma_f32_16x16x32_bf16 v[130:133], v[154:157], v[162:165], v[130:133]
	v_mfma_f32_16x16x32_bf16 v[110:113], v[138:141], v[166:169], v[110:113]
	v_mfma_f32_16x16x32_bf16 v[106:109], v[154:157], v[166:169], v[106:109]
	v_mfma_f32_16x16x32_bf16 v[86:89], v[138:141], v[178:181], v[86:89]
	v_mfma_f32_16x16x32_bf16 v[82:85], v[154:157], v[178:181], v[82:85]
	v_mfma_f32_16x16x32_bf16 v[70:73], v[138:141], v[182:185], v[70:73]
	v_mfma_f32_16x16x32_bf16 v[66:69], v[154:157], v[182:185], v[66:69]
	v_mfma_f32_16x16x32_bf16 v[134:137], v[150:153], v[170:173], v[134:137]
	v_mfma_f32_16x16x32_bf16 v[130:133], v[158:161], v[170:173], v[130:133]
	v_mfma_f32_16x16x32_bf16 v[110:113], v[150:153], v[174:177], v[110:113]
	v_mfma_f32_16x16x32_bf16 v[106:109], v[158:161], v[174:177], v[106:109]
	v_mfma_f32_16x16x32_bf16 v[86:89], v[150:153], v[204:207], v[86:89]
	v_mfma_f32_16x16x32_bf16 v[82:85], v[158:161], v[204:207], v[82:85]
	v_mfma_f32_16x16x32_bf16 v[70:73], v[150:153], v[226:229], v[70:73]
	v_mfma_f32_16x16x32_bf16 v[66:69], v[158:161], v[226:229], v[66:69]
	s_setprio 0
	s_barrier
	s_add_i32 s28, s58, s40
	s_add_i32 m0, s28, 0xffffff80
	ds_read_b128 v[162:165], v219 offset:49152
	ds_read_b128 v[166:169], v219 offset:51200
	ds_read_b128 v[170:173], v220 offset:49152
	ds_read_b128 v[174:177], v220 offset:51200
	ds_read_b128 v[178:181], v219 offset:53248
	ds_read_b128 v[182:185], v219 offset:55296
	ds_read_b128 v[204:207], v220 offset:53248
	ds_read_b128 v[226:229], v220 offset:55296
	global_load_lds_dwordx4 v188, s[26:27] offset:128
	s_add_i32 m0, s28, 0x2000
	s_add_u32 s26, s26, 0x40080
	v_lshl_add_u64 v[230:231], v[232:233], 0, s[8:9]
	s_addc_u32 s27, s27, 0
	s_add_i32 s28, s59, s40
	global_load_lds_dwordx4 v[230:231], off
	s_mov_b32 m0, s28
	s_nop 0
	global_load_lds_dwordx4 v188, s[26:27]
	s_add_i32 m0, s28, 0x2000
	s_nop 0
	global_load_lds_dwordx4 v192, s[26:27]
	v_lshl_add_u64 v[230:231], v[234:235], 0, s[8:9]
	s_mov_b32 m0, s48
	s_nop 0
	global_load_lds_dwordx4 v[230:231], off
	v_lshl_add_u64 v[230:231], v[236:237], 0, s[8:9]
	s_mov_b32 m0, s49
	s_nop 0
	global_load_lds_dwordx4 v[230:231], off
	s_waitcnt vmcnt(8)
	s_waitcnt lgkmcnt(0)
	s_barrier
	s_setprio 1
	s_waitcnt lgkmcnt(0)
	v_mfma_f32_16x16x32_bf16 v[62:65], v[90:93], v[162:165], v[62:65]
	v_mfma_f32_16x16x32_bf16 v[58:61], v[114:117], v[162:165], v[58:61]
	v_mfma_f32_16x16x32_bf16 v[46:49], v[90:93], v[166:169], v[46:49]
	v_mfma_f32_16x16x32_bf16 v[42:45], v[114:117], v[166:169], v[42:45]
	v_mfma_f32_16x16x32_bf16 v[30:33], v[90:93], v[178:181], v[30:33]
	v_mfma_f32_16x16x32_bf16 v[26:29], v[114:117], v[178:181], v[26:29]
	v_mfma_f32_16x16x32_bf16 v[14:17], v[90:93], v[182:185], v[14:17]
	v_mfma_f32_16x16x32_bf16 v[10:13], v[114:117], v[182:185], v[10:13]
	v_mfma_f32_16x16x32_bf16 v[62:65], v[102:105], v[170:173], v[62:65]
	v_mfma_f32_16x16x32_bf16 v[58:61], v[126:129], v[170:173], v[58:61]
	v_mfma_f32_16x16x32_bf16 v[46:49], v[102:105], v[174:177], v[46:49]
	v_mfma_f32_16x16x32_bf16 v[42:45], v[126:129], v[174:177], v[42:45]
	v_mfma_f32_16x16x32_bf16 v[30:33], v[102:105], v[204:207], v[30:33]
	v_mfma_f32_16x16x32_bf16 v[26:29], v[126:129], v[204:207], v[26:29]
	v_mfma_f32_16x16x32_bf16 v[14:17], v[102:105], v[226:229], v[14:17]
	v_mfma_f32_16x16x32_bf16 v[10:13], v[126:129], v[226:229], v[10:13]
	s_setprio 0
	s_setprio 1
	v_mfma_f32_16x16x32_bf16 v[54:57], v[138:141], v[162:165], v[54:57]
	v_mfma_f32_16x16x32_bf16 v[50:53], v[154:157], v[162:165], v[50:53]
	v_mfma_f32_16x16x32_bf16 v[38:41], v[138:141], v[166:169], v[38:41]
	v_mfma_f32_16x16x32_bf16 v[34:37], v[154:157], v[166:169], v[34:37]
	v_mfma_f32_16x16x32_bf16 v[22:25], v[138:141], v[178:181], v[22:25]
	v_mfma_f32_16x16x32_bf16 v[18:21], v[154:157], v[178:181], v[18:21]
	v_mfma_f32_16x16x32_bf16 v[6:9], v[138:141], v[182:185], v[6:9]
	v_mfma_f32_16x16x32_bf16 v[2:5], v[154:157], v[182:185], v[2:5]
	v_mfma_f32_16x16x32_bf16 v[54:57], v[150:153], v[170:173], v[54:57]
	v_mfma_f32_16x16x32_bf16 v[50:53], v[158:161], v[170:173], v[50:53]
	v_mfma_f32_16x16x32_bf16 v[38:41], v[150:153], v[174:177], v[38:41]
	v_mfma_f32_16x16x32_bf16 v[34:37], v[158:161], v[174:177], v[34:37]
	v_mfma_f32_16x16x32_bf16 v[22:25], v[150:153], v[204:207], v[22:25]
	v_mfma_f32_16x16x32_bf16 v[18:21], v[158:161], v[204:207], v[18:21]
	v_mfma_f32_16x16x32_bf16 v[6:9], v[150:153], v[226:229], v[6:9]
	v_mfma_f32_16x16x32_bf16 v[2:5], v[158:161], v[226:229], v[2:5]
	s_setprio 0
	s_barrier
	s_add_i32 s57, s57, 2
	s_add_u32 s24, s24, 0x100
	s_addc_u32 s25, s25, 0
	s_add_u32 s55, s55, 0x100
	s_addc_u32 s56, s56, 0
	s_cmp_gt_u32 s57, 13
	s_cbranch_scc0 .LBB0_1629
	s_branch .Lpx_4
.Lpeel_4:
	s_mov_b32 s100, 0
	ds_read_b128 v[90:93], v211
	ds_read_b128 v[102:105], v212
	ds_read_b128 v[114:117], v213
	ds_read_b128 v[126:129], v214
	ds_read_b128 v[138:141], v215
	ds_read_b128 v[150:153], v216
	ds_read_b128 v[154:157], v217
	ds_read_b128 v[158:161], v218
	s_add_u32 s26, s24, 0xfffc0080
	s_addc_u32 s27, s25, -1
	s_cmp_eq_u32 s57, 12
	s_cselect_b32 s29, s15, s27
	s_cselect_b32 s28, s21, s26
	s_cselect_b32 s27, s13, s56
	s_cselect_b32 s26, s23, s55
	s_add_i32 m0, s41, 0xc000
	ds_read_b128 v[162:165], v219
	ds_read_b128 v[166:169], v219 offset:2048
	ds_read_b128 v[170:173], v220
	ds_read_b128 v[174:177], v220 offset:2048
	ds_read_b128 v[178:181], v219 offset:4096
	ds_read_b128 v[182:185], v219 offset:6144
	ds_read_b128 v[204:207], v220 offset:4096
	ds_read_b128 v[226:229], v220 offset:6144
	global_load_lds_dwordx4 v196, s[24:25]
	s_add_i32 m0, s41, 0xe000
	s_nop 0
	global_load_lds_dwordx4 v198, s[24:25]
	s_waitcnt vmcnt(8)
	s_waitcnt lgkmcnt(0)
	s_barrier
	s_setprio 1
	s_waitcnt lgkmcnt(0)
	v_mfma_f32_16x16x32_bf16 v[146:149], v[90:93], v[162:165], 0
	v_mfma_f32_16x16x32_bf16 v[142:145], v[114:117], v[162:165], 0
	v_mfma_f32_16x16x32_bf16 v[122:125], v[90:93], v[166:169], 0
	v_mfma_f32_16x16x32_bf16 v[118:121], v[114:117], v[166:169], 0
	v_mfma_f32_16x16x32_bf16 v[98:101], v[90:93], v[178:181], 0
	v_mfma_f32_16x16x32_bf16 v[94:97], v[114:117], v[178:181], 0
	v_mfma_f32_16x16x32_bf16 v[78:81], v[90:93], v[182:185], 0
	v_mfma_f32_16x16x32_bf16 v[74:77], v[114:117], v[182:185], 0
	v_mfma_f32_16x16x32_bf16 v[146:149], v[102:105], v[170:173], v[146:149]
	v_mfma_f32_16x16x32_bf16 v[142:145], v[126:129], v[170:173], v[142:145]
	v_mfma_f32_16x16x32_bf16 v[122:125], v[102:105], v[174:177], v[122:125]
	v_mfma_f32_16x16x32_bf16 v[118:121], v[126:129], v[174:177], v[118:121]
	v_mfma_f32_16x16x32_bf16 v[98:101], v[102:105], v[204:207], v[98:101]
	v_mfma_f32_16x16x32_bf16 v[94:97], v[126:129], v[204:207], v[94:97]
	v_mfma_f32_16x16x32_bf16 v[78:81], v[102:105], v[226:229], v[78:81]
	v_mfma_f32_16x16x32_bf16 v[74:77], v[126:129], v[226:229], v[74:77]
	s_setprio 0
	s_setprio 1
	v_mfma_f32_16x16x32_bf16 v[134:137], v[138:141], v[162:165], 0
	v_mfma_f32_16x16x32_bf16 v[130:133], v[154:157], v[162:165], 0
	v_mfma_f32_16x16x32_bf16 v[110:113], v[138:141], v[166:169], 0
	v_mfma_f32_16x16x32_bf16 v[106:109], v[154:157], v[166:169], 0
	v_mfma_f32_16x16x32_bf16 v[86:89], v[138:141], v[178:181], 0
	v_mfma_f32_16x16x32_bf16 v[82:85], v[154:157], v[178:181], 0
	v_mfma_f32_16x16x32_bf16 v[70:73], v[138:141], v[182:185], 0
	v_mfma_f32_16x16x32_bf16 v[66:69], v[154:157], v[182:185], 0
	v_mfma_f32_16x16x32_bf16 v[134:137], v[150:153], v[170:173], v[134:137]
	v_mfma_f32_16x16x32_bf16 v[130:133], v[158:161], v[170:173], v[130:133]
	v_mfma_f32_16x16x32_bf16 v[110:113], v[150:153], v[174:177], v[110:113]
	v_mfma_f32_16x16x32_bf16 v[106:109], v[158:161], v[174:177], v[106:109]
	v_mfma_f32_16x16x32_bf16 v[86:89], v[150:153], v[204:207], v[86:89]
	v_mfma_f32_16x16x32_bf16 v[82:85], v[158:161], v[204:207], v[82:85]
	v_mfma_f32_16x16x32_bf16 v[70:73], v[150:153], v[226:229], v[70:73]
	v_mfma_f32_16x16x32_bf16 v[66:69], v[158:161], v[226:229], v[66:69]
	s_setprio 0
	s_barrier
	s_add_i32 s58, s53, s40
	s_mov_b32 m0, s58
	ds_read_b128 v[162:165], v219 offset:16384
	ds_read_b128 v[166:169], v219 offset:18432
	ds_read_b128 v[170:173], v220 offset:16384
	ds_read_b128 v[174:177], v220 offset:18432
	ds_read_b128 v[178:181], v219 offset:20480
	ds_read_b128 v[182:185], v219 offset:22528
	ds_read_b128 v[204:207], v220 offset:20480
	ds_read_b128 v[226:229], v220 offset:22528
	global_load_lds_dwordx4 v188, s[26:27]
	s_add_i32 m0, s58, 0x2000
	s_add_u32 s58, s26, 0x40000
	v_lshl_add_u64 v[232:233], s[26:27], 0, v[192:193]
	s_addc_u32 s59, s27, 0
	s_add_i32 s60, s54, s40
	global_load_lds_dwordx4 v192, s[26:27]
	s_mov_b32 m0, s60
	v_lshl_add_u64 v[236:237], s[28:29], 0, v[190:191]
	global_load_lds_dwordx4 v188, s[58:59]
	s_add_i32 m0, s60, 0x2000
	s_nop 0
	global_load_lds_dwordx4 v192, s[58:59]
	v_lshl_add_u64 v[234:235], s[28:29], 0, v[186:187]
	s_mov_b32 m0, s41
	s_nop 0
	global_load_lds_dwordx4 v186, s[28:29]
	s_mov_b32 m0, s42
	s_nop 0
	global_load_lds_dwordx4 v190, s[28:29]
	s_waitcnt vmcnt(8)
	s_waitcnt lgkmcnt(0)
	s_barrier
	s_setprio 1
	s_waitcnt lgkmcnt(0)
	v_mfma_f32_16x16x32_bf16 v[62:65], v[90:93], v[162:165], 0
	v_mfma_f32_16x16x32_bf16 v[58:61], v[114:117], v[162:165], 0
	v_mfma_f32_16x16x32_bf16 v[46:49], v[90:93], v[166:169], 0
	v_mfma_f32_16x16x32_bf16 v[42:45], v[114:117], v[166:169], 0
	v_mfma_f32_16x16x32_bf16 v[30:33], v[90:93], v[178:181], 0
	v_mfma_f32_16x16x32_bf16 v[26:29], v[114:117], v[178:181], 0
	v_mfma_f32_16x16x32_bf16 v[14:17], v[90:93], v[182:185], 0
	v_mfma_f32_16x16x32_bf16 v[10:13], v[114:117], v[182:185], 0
	v_mfma_f32_16x16x32_bf16 v[62:65], v[102:105], v[170:173], v[62:65]
	v_mfma_f32_16x16x32_bf16 v[58:61], v[126:129], v[170:173], v[58:61]
	v_mfma_f32_16x16x32_bf16 v[46:49], v[102:105], v[174:177], v[46:49]
	v_mfma_f32_16x16x32_bf16 v[42:45], v[126:129], v[174:177], v[42:45]
	v_mfma_f32_16x16x32_bf16 v[30:33], v[102:105], v[204:207], v[30:33]
	v_mfma_f32_16x16x32_bf16 v[26:29], v[126:129], v[204:207], v[26:29]
	v_mfma_f32_16x16x32_bf16 v[14:17], v[102:105], v[226:229], v[14:17]
	v_mfma_f32_16x16x32_bf16 v[10:13], v[126:129], v[226:229], v[10:13]
	s_setprio 0
	s_setprio 1
	v_mfma_f32_16x16x32_bf16 v[54:57], v[138:141], v[162:165], 0
	v_mfma_f32_16x16x32_bf16 v[50:53], v[154:157], v[162:165], 0
	v_mfma_f32_16x16x32_bf16 v[38:41], v[138:141], v[166:169], 0
	v_mfma_f32_16x16x32_bf16 v[34:37], v[154:157], v[166:169], 0
	v_mfma_f32_16x16x32_bf16 v[22:25], v[138:141], v[178:181], 0
	v_mfma_f32_16x16x32_bf16 v[18:21], v[154:157], v[178:181], 0
	v_mfma_f32_16x16x32_bf16 v[6:9], v[138:141], v[182:185], 0
	v_mfma_f32_16x16x32_bf16 v[2:5], v[154:157], v[182:185], 0
	v_mfma_f32_16x16x32_bf16 v[54:57], v[150:153], v[170:173], v[54:57]
	v_mfma_f32_16x16x32_bf16 v[50:53], v[158:161], v[170:173], v[50:53]
	v_mfma_f32_16x16x32_bf16 v[38:41], v[150:153], v[174:177], v[38:41]
	v_mfma_f32_16x16x32_bf16 v[34:37], v[158:161], v[174:177], v[34:37]
	v_mfma_f32_16x16x32_bf16 v[22:25], v[150:153], v[204:207], v[22:25]
	v_mfma_f32_16x16x32_bf16 v[18:21], v[158:161], v[204:207], v[18:21]
	v_mfma_f32_16x16x32_bf16 v[6:9], v[150:153], v[226:229], v[6:9]
	v_mfma_f32_16x16x32_bf16 v[2:5], v[158:161], v[226:229], v[2:5]
	s_setprio 0
	s_barrier
	s_add_i32 s58, 0, 0x18000
	s_add_i32 s59, 0, 0x1c000
	ds_read_b128 v[90:93], v245 offset:32768
	ds_read_b128 v[102:105], v246 offset:32768
	ds_read_b128 v[114:117], v221
	ds_read_b128 v[126:129], v222
	ds_read_b128 v[138:141], v245 offset:49152
	ds_read_b128 v[150:153], v246 offset:49152
	ds_read_b128 v[154:157], v223
	ds_read_b128 v[158:161], v224
	s_add_u32 s28, s28, 0x40000
	s_addc_u32 s29, s29, 0
	s_mov_b32 m0, s43
	ds_read_b128 v[162:165], v219 offset:32768
	ds_read_b128 v[166:169], v219 offset:34816
	ds_read_b128 v[170:173], v220 offset:32768
	ds_read_b128 v[174:177], v220 offset:34816
	ds_read_b128 v[178:181], v219 offset:36864
	ds_read_b128 v[182:185], v219 offset:38912
	ds_read_b128 v[204:207], v220 offset:36864
	ds_read_b128 v[226:229], v220 offset:38912
	global_load_lds_dwordx4 v186, s[28:29]
	s_mov_b32 m0, s44
	s_nop 0
	global_load_lds_dwordx4 v190, s[28:29]
	s_waitcnt vmcnt(8)
	s_waitcnt lgkmcnt(0)
	s_barrier
	s_setprio 1
	s_waitcnt lgkmcnt(0)
	v_mfma_f32_16x16x32_bf16 v[146:149], v[90:93], v[162:165], v[146:149]
	v_mfma_f32_16x16x32_bf16 v[142:145], v[114:117], v[162:165], v[142:145]
	v_mfma_f32_16x16x32_bf16 v[122:125], v[90:93], v[166:169], v[122:125]
	v_mfma_f32_16x16x32_bf16 v[118:121], v[114:117], v[166:169], v[118:121]
	v_mfma_f32_16x16x32_bf16 v[98:101], v[90:93], v[178:181], v[98:101]
	v_mfma_f32_16x16x32_bf16 v[94:97], v[114:117], v[178:181], v[94:97]
	v_mfma_f32_16x16x32_bf16 v[78:81], v[90:93], v[182:185], v[78:81]
	v_mfma_f32_16x16x32_bf16 v[74:77], v[114:117], v[182:185], v[74:77]
	v_mfma_f32_16x16x32_bf16 v[146:149], v[102:105], v[170:173], v[146:149]
	v_mfma_f32_16x16x32_bf16 v[142:145], v[126:129], v[170:173], v[142:145]
	v_mfma_f32_16x16x32_bf16 v[122:125], v[102:105], v[174:177], v[122:125]
	v_mfma_f32_16x16x32_bf16 v[118:121], v[126:129], v[174:177], v[118:121]
	v_mfma_f32_16x16x32_bf16 v[98:101], v[102:105], v[204:207], v[98:101]
	v_mfma_f32_16x16x32_bf16 v[94:97], v[126:129], v[204:207], v[94:97]
	v_mfma_f32_16x16x32_bf16 v[78:81], v[102:105], v[226:229], v[78:81]
	v_mfma_f32_16x16x32_bf16 v[74:77], v[126:129], v[226:229], v[74:77]
	s_setprio 0
	s_setprio 1
	v_mfma_f32_16x16x32_bf16 v[134:137], v[138:141], v[162:165], v[134:137]
	v_mfma_f32_16x16x32_bf16 v[130:133], v[154:157], v[162:165], v[130:133]
	v_mfma_f32_16x16x32_bf16 v[110:113], v[138:141], v[166:169], v[110:113]
	v_mfma_f32_16x16x32_bf16 v[106:109], v[154:157], v[166:169], v[106:109]
	v_mfma_f32_16x16x32_bf16 v[86:89], v[138:141], v[178:181], v[86:89]
	v_mfma_f32_16x16x32_bf16 v[82:85], v[154:157], v[178:181], v[82:85]
	v_mfma_f32_16x16x32_bf16 v[70:73], v[138:141], v[182:185], v[70:73]
	v_mfma_f32_16x16x32_bf16 v[66:69], v[154:157], v[182:185], v[66:69]
	v_mfma_f32_16x16x32_bf16 v[134:137], v[150:153], v[170:173], v[134:137]
	v_mfma_f32_16x16x32_bf16 v[130:133], v[158:161], v[170:173], v[130:133]
	v_mfma_f32_16x16x32_bf16 v[110:113], v[150:153], v[174:177], v[110:113]
	v_mfma_f32_16x16x32_bf16 v[106:109], v[158:161], v[174:177], v[106:109]
	v_mfma_f32_16x16x32_bf16 v[86:89], v[150:153], v[204:207], v[86:89]
	v_mfma_f32_16x16x32_bf16 v[82:85], v[158:161], v[204:207], v[82:85]
	v_mfma_f32_16x16x32_bf16 v[70:73], v[150:153], v[226:229], v[70:73]
	v_mfma_f32_16x16x32_bf16 v[66:69], v[158:161], v[226:229], v[66:69]
	s_setprio 0
	s_barrier
	s_add_i32 s28, s58, s40
	s_add_i32 m0, s28, 0xffffff80
	ds_read_b128 v[162:165], v219 offset:49152
	ds_read_b128 v[166:169], v219 offset:51200
	ds_read_b128 v[170:173], v220 offset:49152
	ds_read_b128 v[174:177], v220 offset:51200
	ds_read_b128 v[178:181], v219 offset:53248
	ds_read_b128 v[182:185], v219 offset:55296
	ds_read_b128 v[204:207], v220 offset:53248
	ds_read_b128 v[226:229], v220 offset:55296
	global_load_lds_dwordx4 v188, s[26:27] offset:128
	s_add_i32 m0, s28, 0x2000
	s_add_u32 s26, s26, 0x40080
	v_lshl_add_u64 v[230:231], v[232:233], 0, s[8:9]
	s_addc_u32 s27, s27, 0
	s_add_i32 s28, s59, s40
	global_load_lds_dwordx4 v[230:231], off
	s_mov_b32 m0, s28
	s_nop 0
	global_load_lds_dwordx4 v188, s[26:27]
	s_add_i32 m0, s28, 0x2000
	s_nop 0
	global_load_lds_dwordx4 v192, s[26:27]
	v_lshl_add_u64 v[230:231], v[234:235], 0, s[8:9]
	s_mov_b32 m0, s48
	s_nop 0
	global_load_lds_dwordx4 v[230:231], off
	v_lshl_add_u64 v[230:231], v[236:237], 0, s[8:9]
	s_mov_b32 m0, s49
	s_nop 0
	global_load_lds_dwordx4 v[230:231], off
	s_waitcnt vmcnt(8)
	s_waitcnt lgkmcnt(0)
	s_barrier
	s_setprio 1
	s_waitcnt lgkmcnt(0)
	v_mfma_f32_16x16x32_bf16 v[62:65], v[90:93], v[162:165], v[62:65]
	v_mfma_f32_16x16x32_bf16 v[58:61], v[114:117], v[162:165], v[58:61]
	v_mfma_f32_16x16x32_bf16 v[46:49], v[90:93], v[166:169], v[46:49]
	v_mfma_f32_16x16x32_bf16 v[42:45], v[114:117], v[166:169], v[42:45]
	v_mfma_f32_16x16x32_bf16 v[30:33], v[90:93], v[178:181], v[30:33]
	v_mfma_f32_16x16x32_bf16 v[26:29], v[114:117], v[178:181], v[26:29]
	v_mfma_f32_16x16x32_bf16 v[14:17], v[90:93], v[182:185], v[14:17]
	v_mfma_f32_16x16x32_bf16 v[10:13], v[114:117], v[182:185], v[10:13]
	v_mfma_f32_16x16x32_bf16 v[62:65], v[102:105], v[170:173], v[62:65]
	v_mfma_f32_16x16x32_bf16 v[58:61], v[126:129], v[170:173], v[58:61]
	v_mfma_f32_16x16x32_bf16 v[46:49], v[102:105], v[174:177], v[46:49]
	v_mfma_f32_16x16x32_bf16 v[42:45], v[126:129], v[174:177], v[42:45]
	v_mfma_f32_16x16x32_bf16 v[30:33], v[102:105], v[204:207], v[30:33]
	v_mfma_f32_16x16x32_bf16 v[26:29], v[126:129], v[204:207], v[26:29]
	v_mfma_f32_16x16x32_bf16 v[14:17], v[102:105], v[226:229], v[14:17]
	v_mfma_f32_16x16x32_bf16 v[10:13], v[126:129], v[226:229], v[10:13]
	s_setprio 0
	s_setprio 1
	v_mfma_f32_16x16x32_bf16 v[54:57], v[138:141], v[162:165], v[54:57]
	v_mfma_f32_16x16x32_bf16 v[50:53], v[154:157], v[162:165], v[50:53]
	v_mfma_f32_16x16x32_bf16 v[38:41], v[138:141], v[166:169], v[38:41]
	v_mfma_f32_16x16x32_bf16 v[34:37], v[154:157], v[166:169], v[34:37]
	v_mfma_f32_16x16x32_bf16 v[22:25], v[138:141], v[178:181], v[22:25]
	v_mfma_f32_16x16x32_bf16 v[18:21], v[154:157], v[178:181], v[18:21]
	v_mfma_f32_16x16x32_bf16 v[6:9], v[138:141], v[182:185], v[6:9]
	v_mfma_f32_16x16x32_bf16 v[2:5], v[154:157], v[182:185], v[2:5]
	v_mfma_f32_16x16x32_bf16 v[54:57], v[150:153], v[170:173], v[54:57]
	v_mfma_f32_16x16x32_bf16 v[50:53], v[158:161], v[170:173], v[50:53]
	v_mfma_f32_16x16x32_bf16 v[38:41], v[150:153], v[174:177], v[38:41]
	v_mfma_f32_16x16x32_bf16 v[34:37], v[158:161], v[174:177], v[34:37]
	v_mfma_f32_16x16x32_bf16 v[22:25], v[150:153], v[204:207], v[22:25]
	v_mfma_f32_16x16x32_bf16 v[18:21], v[158:161], v[204:207], v[18:21]
	v_mfma_f32_16x16x32_bf16 v[6:9], v[150:153], v[226:229], v[6:9]
	v_mfma_f32_16x16x32_bf16 v[2:5], v[158:161], v[226:229], v[2:5]
	s_setprio 0
	s_barrier
	s_add_i32 s57, s57, 2
	s_add_u32 s24, s24, 0x100
	s_addc_u32 s25, s25, 0
	s_add_u32 s55, s55, 0x100
	s_addc_u32 s56, s56, 0
	s_cmp_gt_u32 s57, 13
	s_cbranch_scc0 .LBB0_1629

.LBB0_1720:
	s_ashr_i32 s13, s12, 31
	s_lshl_b64 s[14:15], s[12:13], 19
	s_add_u32 s14, s80, s14
	s_addc_u32 s15, s81, s15
	s_and_b64 s[16:17], s[6:7], exec
	s_cselect_b32 s13, s15, s23
	s_cselect_b32 s58, s14, s22
	s_ashr_i32 s5, s4, 31
	s_lshl_b64 s[16:17], s[4:5], 19
	s_add_u32 s16, s28, s16
	s_addc_u32 s17, s29, s17
	s_and_b64 s[26:27], s[6:7], exec
	s_cselect_b32 s5, s17, s25
	s_cselect_b32 s59, s16, s24
	s_lshl_b32 s60, s57, 10
	s_lshl_b32 s26, s12, 8
	s_add_i32 s60, s60, 0
	s_ashr_i32 s27, s26, 31
	s_add_i32 s60, s60, 0x20800
	s_add_u32 s22, s22, 0x40080
	s_addc_u32 s23, s23, 0
	s_add_u32 s61, s24, 0x100
	v_add_u32_e32 v245, 0x10000, v155
	v_add_u32_e32 v246, 0x10000, v156
	s_mov_b32 s100, 1
	v_lshl_add_u64 v[148:149], s[26:27], 2, v[138:139]
	s_addc_u32 s62, s25, 0
	s_mov_b32 s63, -2
	s_branch .LBB0_1722
.LBB0_1721:
	s_cmp_lg_u32 s100, 0
	s_cbranch_scc1 .Lpeel_5
	ds_read_b128 v[150:153], v245
	ds_read_b128 v[160:163], v246
	ds_read_b128 v[164:167], v245 offset:2048
	ds_read_b128 v[168:171], v246 offset:2048
	ds_read_b128 v[172:175], v245 offset:16384
	ds_read_b128 v[176:179], v246 offset:16384
	ds_read_b128 v[180:183], v245 offset:18432
	ds_read_b128 v[184:187], v246 offset:18432
	s_add_u32 s26, s22, 0xfffc0080
	s_addc_u32 s27, s23, -1
	s_and_b64 s[24:25], s[24:25], exec
	s_cselect_b32 s27, s13, s27
	s_cselect_b32 s26, s58, s26
	s_cselect_b32 s25, s5, s62
	s_cselect_b32 s24, s59, s61
	s_add_i32 m0, s38, 0xc000
	ds_read_b128 v[188:191], v157
	s_waitcnt lgkmcnt(0)
	ds_read_b128 v[192:195], v157 offset:2048
	ds_read_b128 v[196:199], v158
	ds_read_b128 v[200:203], v158 offset:2048
	ds_read_b128 v[204:207], v157 offset:4096
	ds_read_b128 v[208:211], v157 offset:6144
	ds_read_b128 v[212:215], v158 offset:4096
	ds_read_b128 v[216:219], v158 offset:6144
	global_load_lds_dwordx4 v140, s[22:23]
	s_add_i32 m0, s38, 0xe000
	s_nop 0
	global_load_lds_dwordx4 v142, s[22:23]
	s_waitcnt vmcnt(8)
	s_waitcnt lgkmcnt(0)
	s_barrier
	s_setprio 1
	v_mfma_f32_16x16x32_bf16 v[126:129], v[150:153], v[188:191], v[126:129]
	v_mfma_f32_16x16x32_bf16 v[118:121], v[164:167], v[188:191], v[118:121]
	s_waitcnt lgkmcnt(0)
	v_mfma_f32_16x16x32_bf16 v[110:113], v[150:153], v[192:195], v[110:113]
	v_mfma_f32_16x16x32_bf16 v[102:105], v[164:167], v[192:195], v[102:105]
	v_mfma_f32_16x16x32_bf16 v[94:97], v[150:153], v[204:207], v[94:97]
	v_mfma_f32_16x16x32_bf16 v[86:89], v[164:167], v[204:207], v[86:89]
	v_mfma_f32_16x16x32_bf16 v[78:81], v[150:153], v[208:211], v[78:81]
	v_mfma_f32_16x16x32_bf16 v[70:73], v[164:167], v[208:211], v[70:73]
	v_mfma_f32_16x16x32_bf16 v[126:129], v[160:163], v[196:199], v[126:129]
	v_mfma_f32_16x16x32_bf16 v[118:121], v[168:171], v[196:199], v[118:121]
	v_mfma_f32_16x16x32_bf16 v[110:113], v[160:163], v[200:203], v[110:113]
	v_mfma_f32_16x16x32_bf16 v[102:105], v[168:171], v[200:203], v[102:105]
	v_mfma_f32_16x16x32_bf16 v[94:97], v[160:163], v[212:215], v[94:97]
	v_mfma_f32_16x16x32_bf16 v[86:89], v[168:171], v[212:215], v[86:89]
	v_mfma_f32_16x16x32_bf16 v[78:81], v[160:163], v[216:219], v[78:81]
	v_mfma_f32_16x16x32_bf16 v[70:73], v[168:171], v[216:219], v[70:73]
	s_setprio 0
	s_setprio 1
	v_mfma_f32_16x16x32_bf16 v[122:125], v[172:175], v[188:191], v[122:125]
	v_mfma_f32_16x16x32_bf16 v[114:117], v[180:183], v[188:191], v[114:117]
	v_mfma_f32_16x16x32_bf16 v[106:109], v[172:175], v[192:195], v[106:109]
	v_mfma_f32_16x16x32_bf16 v[98:101], v[180:183], v[192:195], v[98:101]
	v_mfma_f32_16x16x32_bf16 v[90:93], v[172:175], v[204:207], v[90:93]
	v_mfma_f32_16x16x32_bf16 v[82:85], v[180:183], v[204:207], v[82:85]
	v_mfma_f32_16x16x32_bf16 v[74:77], v[172:175], v[208:211], v[74:77]
	v_mfma_f32_16x16x32_bf16 v[66:69], v[180:183], v[208:211], v[66:69]
	v_mfma_f32_16x16x32_bf16 v[122:125], v[176:179], v[196:199], v[122:125]
	v_mfma_f32_16x16x32_bf16 v[114:117], v[184:187], v[196:199], v[114:117]
	v_mfma_f32_16x16x32_bf16 v[106:109], v[176:179], v[200:203], v[106:109]
	v_mfma_f32_16x16x32_bf16 v[98:101], v[184:187], v[200:203], v[98:101]
	v_mfma_f32_16x16x32_bf16 v[90:93], v[176:179], v[212:215], v[90:93]
	v_mfma_f32_16x16x32_bf16 v[82:85], v[184:187], v[212:215], v[82:85]
	v_mfma_f32_16x16x32_bf16 v[74:77], v[176:179], v[216:219], v[74:77]
	v_mfma_f32_16x16x32_bf16 v[66:69], v[184:187], v[216:219], v[66:69]
	s_setprio 0
	s_barrier
	s_add_i32 s64, s49, s21
	s_mov_b32 m0, s64
	ds_read_b128 v[188:191], v157 offset:16384
	ds_read_b128 v[192:195], v157 offset:18432
	ds_read_b128 v[196:199], v158 offset:16384
	ds_read_b128 v[200:203], v158 offset:18432
	ds_read_b128 v[204:207], v157 offset:20480
	ds_read_b128 v[208:211], v157 offset:22528
	ds_read_b128 v[212:215], v158 offset:20480
	ds_read_b128 v[216:219], v158 offset:22528
	global_load_lds_dwordx4 v132, s[24:25]
	s_add_i32 m0, s64, 0x2000
	s_add_u32 s64, s24, 0x40000
	v_lshl_add_u64 v[222:223], s[24:25], 0, v[136:137]
	s_addc_u32 s65, s25, 0
	s_add_i32 s66, s51, s21
	global_load_lds_dwordx4 v136, s[24:25]
	s_mov_b32 m0, s66
	v_lshl_add_u64 v[226:227], s[26:27], 0, v[134:135]
	global_load_lds_dwordx4 v132, s[64:65]
	s_add_i32 m0, s66, 0x2000
	s_nop 0
	global_load_lds_dwordx4 v136, s[64:65]
	v_lshl_add_u64 v[224:225], s[26:27], 0, v[130:131]
	s_mov_b32 m0, s38
	s_nop 0
	global_load_lds_dwordx4 v130, s[26:27]
	s_mov_b32 m0, s39
	s_nop 0
	global_load_lds_dwordx4 v134, s[26:27]
	s_waitcnt vmcnt(8)
	s_waitcnt lgkmcnt(0)
	s_barrier
	s_setprio 1
	s_waitcnt lgkmcnt(0)
	v_mfma_f32_16x16x32_bf16 v[62:65], v[150:153], v[188:191], v[62:65]
	v_mfma_f32_16x16x32_bf16 v[54:57], v[164:167], v[188:191], v[54:57]
	v_mfma_f32_16x16x32_bf16 v[46:49], v[150:153], v[192:195], v[46:49]
	v_mfma_f32_16x16x32_bf16 v[38:41], v[164:167], v[192:195], v[38:41]
	v_mfma_f32_16x16x32_bf16 v[30:33], v[150:153], v[204:207], v[30:33]
	v_mfma_f32_16x16x32_bf16 v[22:25], v[164:167], v[204:207], v[22:25]
	v_mfma_f32_16x16x32_bf16 v[14:17], v[150:153], v[208:211], v[14:17]
	v_mfma_f32_16x16x32_bf16 v[6:9], v[164:167], v[208:211], v[6:9]
	v_mfma_f32_16x16x32_bf16 v[62:65], v[160:163], v[196:199], v[62:65]
	v_mfma_f32_16x16x32_bf16 v[54:57], v[168:171], v[196:199], v[54:57]
	v_mfma_f32_16x16x32_bf16 v[46:49], v[160:163], v[200:203], v[46:49]
	v_mfma_f32_16x16x32_bf16 v[38:41], v[168:171], v[200:203], v[38:41]
	v_mfma_f32_16x16x32_bf16 v[30:33], v[160:163], v[212:215], v[30:33]
	v_mfma_f32_16x16x32_bf16 v[22:25], v[168:171], v[212:215], v[22:25]
	v_mfma_f32_16x16x32_bf16 v[14:17], v[160:163], v[216:219], v[14:17]
	v_mfma_f32_16x16x32_bf16 v[6:9], v[168:171], v[216:219], v[6:9]
	s_setprio 0
	s_setprio 1
	v_mfma_f32_16x16x32_bf16 v[58:61], v[172:175], v[188:191], v[58:61]
	v_mfma_f32_16x16x32_bf16 v[50:53], v[180:183], v[188:191], v[50:53]
	v_mfma_f32_16x16x32_bf16 v[42:45], v[172:175], v[192:195], v[42:45]
	v_mfma_f32_16x16x32_bf16 v[34:37], v[180:183], v[192:195], v[34:37]
	v_mfma_f32_16x16x32_bf16 v[26:29], v[172:175], v[204:207], v[26:29]
	v_mfma_f32_16x16x32_bf16 v[18:21], v[180:183], v[204:207], v[18:21]
	v_mfma_f32_16x16x32_bf16 v[10:13], v[172:175], v[208:211], v[10:13]
	v_mfma_f32_16x16x32_bf16 v[2:5], v[180:183], v[208:211], v[2:5]
	v_mfma_f32_16x16x32_bf16 v[58:61], v[176:179], v[196:199], v[58:61]
	v_mfma_f32_16x16x32_bf16 v[50:53], v[184:187], v[196:199], v[50:53]
	v_mfma_f32_16x16x32_bf16 v[42:45], v[176:179], v[200:203], v[42:45]
	v_mfma_f32_16x16x32_bf16 v[34:37], v[184:187], v[200:203], v[34:37]
	v_mfma_f32_16x16x32_bf16 v[26:29], v[176:179], v[212:215], v[26:29]
	v_mfma_f32_16x16x32_bf16 v[18:21], v[184:187], v[212:215], v[18:21]
	v_mfma_f32_16x16x32_bf16 v[10:13], v[176:179], v[216:219], v[10:13]
	v_mfma_f32_16x16x32_bf16 v[2:5], v[184:187], v[216:219], v[2:5]
	s_setprio 0
	s_barrier
	s_add_i32 s64, 0, 0x18000
	s_add_i32 s65, 0, 0x1c000
	ds_read_b128 v[150:153], v245 offset:32768
	ds_read_b128 v[160:163], v246 offset:32768
	ds_read_b128 v[164:167], v245 offset:34816
	ds_read_b128 v[168:171], v246 offset:34816
	ds_read_b128 v[172:175], v245 offset:49152
	ds_read_b128 v[176:179], v246 offset:49152
	ds_read_b128 v[180:183], v245 offset:51200
	ds_read_b128 v[184:187], v246 offset:51200
	s_add_u32 s26, s26, 0x40000
	s_addc_u32 s27, s27, 0
	s_mov_b32 m0, s40
	ds_read_b128 v[188:191], v157 offset:32768
	ds_read_b128 v[192:195], v157 offset:34816
	ds_read_b128 v[196:199], v158 offset:32768
	ds_read_b128 v[200:203], v158 offset:34816
	ds_read_b128 v[204:207], v157 offset:36864
	ds_read_b128 v[208:211], v157 offset:38912
	ds_read_b128 v[212:215], v158 offset:36864
	ds_read_b128 v[216:219], v158 offset:38912
	global_load_lds_dwordx4 v130, s[26:27]
	s_mov_b32 m0, s41
	s_nop 0
	global_load_lds_dwordx4 v134, s[26:27]
	s_waitcnt vmcnt(8)
	s_waitcnt lgkmcnt(0)
	s_barrier
	s_setprio 1
	s_waitcnt lgkmcnt(0)
	v_mfma_f32_16x16x32_bf16 v[126:129], v[150:153], v[188:191], v[126:129]
	v_mfma_f32_16x16x32_bf16 v[118:121], v[164:167], v[188:191], v[118:121]
	v_mfma_f32_16x16x32_bf16 v[110:113], v[150:153], v[192:195], v[110:113]
	v_mfma_f32_16x16x32_bf16 v[102:105], v[164:167], v[192:195], v[102:105]
	v_mfma_f32_16x16x32_bf16 v[94:97], v[150:153], v[204:207], v[94:97]
	v_mfma_f32_16x16x32_bf16 v[86:89], v[164:167], v[204:207], v[86:89]
	v_mfma_f32_16x16x32_bf16 v[78:81], v[150:153], v[208:211], v[78:81]
	v_mfma_f32_16x16x32_bf16 v[70:73], v[164:167], v[208:211], v[70:73]
	v_mfma_f32_16x16x32_bf16 v[126:129], v[160:163], v[196:199], v[126:129]
	v_mfma_f32_16x16x32_bf16 v[118:121], v[168:171], v[196:199], v[118:121]
	v_mfma_f32_16x16x32_bf16 v[110:113], v[160:163], v[200:203], v[110:113]
	v_mfma_f32_16x16x32_bf16 v[102:105], v[168:171], v[200:203], v[102:105]
	v_mfma_f32_16x16x32_bf16 v[94:97], v[160:163], v[212:215], v[94:97]
	v_mfma_f32_16x16x32_bf16 v[86:89], v[168:171], v[212:215], v[86:89]
	v_mfma_f32_16x16x32_bf16 v[78:81], v[160:163], v[216:219], v[78:81]
	v_mfma_f32_16x16x32_bf16 v[70:73], v[168:171], v[216:219], v[70:73]
	s_setprio 0
	s_setprio 1
	v_mfma_f32_16x16x32_bf16 v[122:125], v[172:175], v[188:191], v[122:125]
	v_mfma_f32_16x16x32_bf16 v[114:117], v[180:183], v[188:191], v[114:117]
	v_mfma_f32_16x16x32_bf16 v[106:109], v[172:175], v[192:195], v[106:109]
	v_mfma_f32_16x16x32_bf16 v[98:101], v[180:183], v[192:195], v[98:101]
	v_mfma_f32_16x16x32_bf16 v[90:93], v[172:175], v[204:207], v[90:93]
	v_mfma_f32_16x16x32_bf16 v[82:85], v[180:183], v[204:207], v[82:85]
	v_mfma_f32_16x16x32_bf16 v[74:77], v[172:175], v[208:211], v[74:77]
	v_mfma_f32_16x16x32_bf16 v[66:69], v[180:183], v[208:211], v[66:69]
	v_mfma_f32_16x16x32_bf16 v[122:125], v[176:179], v[196:199], v[122:125]
	v_mfma_f32_16x16x32_bf16 v[114:117], v[184:187], v[196:199], v[114:117]
	v_mfma_f32_16x16x32_bf16 v[106:109], v[176:179], v[200:203], v[106:109]
	v_mfma_f32_16x16x32_bf16 v[98:101], v[184:187], v[200:203], v[98:101]
	v_mfma_f32_16x16x32_bf16 v[90:93], v[176:179], v[212:215], v[90:93]
	v_mfma_f32_16x16x32_bf16 v[82:85], v[184:187], v[212:215], v[82:85]
	v_mfma_f32_16x16x32_bf16 v[74:77], v[176:179], v[216:219], v[74:77]
	v_mfma_f32_16x16x32_bf16 v[66:69], v[184:187], v[216:219], v[66:69]
	s_setprio 0
	s_barrier
	s_add_i32 s26, s64, s21
	s_add_i32 m0, s26, 0xffffff80
	ds_read_b128 v[188:191], v157 offset:49152
	ds_read_b128 v[192:195], v157 offset:51200
	ds_read_b128 v[196:199], v158 offset:49152
	ds_read_b128 v[200:203], v158 offset:51200
	ds_read_b128 v[204:207], v157 offset:53248
	ds_read_b128 v[208:211], v157 offset:55296
	ds_read_b128 v[212:215], v158 offset:53248
	ds_read_b128 v[216:219], v158 offset:55296
	global_load_lds_dwordx4 v132, s[24:25] offset:128
	s_add_i32 m0, s26, 0x2000
	s_add_u32 s24, s24, 0x40080
	v_lshl_add_u64 v[220:221], v[222:223], 0, s[8:9]
	s_addc_u32 s25, s25, 0
	s_add_i32 s26, s65, s21
	global_load_lds_dwordx4 v[220:221], off
	s_mov_b32 m0, s26
	s_nop 0
	global_load_lds_dwordx4 v132, s[24:25]
	s_add_i32 m0, s26, 0x2000
	s_nop 0
	global_load_lds_dwordx4 v136, s[24:25]
	v_lshl_add_u64 v[220:221], v[224:225], 0, s[8:9]
	s_mov_b32 m0, s44
	s_nop 0
	global_load_lds_dwordx4 v[220:221], off
	v_lshl_add_u64 v[220:221], v[226:227], 0, s[8:9]
	s_mov_b32 m0, s45
	s_nop 0
	global_load_lds_dwordx4 v[220:221], off
	s_waitcnt vmcnt(8)
	s_waitcnt lgkmcnt(0)
	s_barrier
	s_setprio 1
	s_waitcnt lgkmcnt(0)
	v_mfma_f32_16x16x32_bf16 v[62:65], v[150:153], v[188:191], v[62:65]
	v_mfma_f32_16x16x32_bf16 v[54:57], v[164:167], v[188:191], v[54:57]
	v_mfma_f32_16x16x32_bf16 v[46:49], v[150:153], v[192:195], v[46:49]
	v_mfma_f32_16x16x32_bf16 v[38:41], v[164:167], v[192:195], v[38:41]
	v_mfma_f32_16x16x32_bf16 v[30:33], v[150:153], v[204:207], v[30:33]
	v_mfma_f32_16x16x32_bf16 v[22:25], v[164:167], v[204:207], v[22:25]
	v_mfma_f32_16x16x32_bf16 v[14:17], v[150:153], v[208:211], v[14:17]
	v_mfma_f32_16x16x32_bf16 v[6:9], v[164:167], v[208:211], v[6:9]
	v_mfma_f32_16x16x32_bf16 v[62:65], v[160:163], v[196:199], v[62:65]
	v_mfma_f32_16x16x32_bf16 v[54:57], v[168:171], v[196:199], v[54:57]
	v_mfma_f32_16x16x32_bf16 v[46:49], v[160:163], v[200:203], v[46:49]
	v_mfma_f32_16x16x32_bf16 v[38:41], v[168:171], v[200:203], v[38:41]
	v_mfma_f32_16x16x32_bf16 v[30:33], v[160:163], v[212:215], v[30:33]
	v_mfma_f32_16x16x32_bf16 v[22:25], v[168:171], v[212:215], v[22:25]
	v_mfma_f32_16x16x32_bf16 v[14:17], v[160:163], v[216:219], v[14:17]
	v_mfma_f32_16x16x32_bf16 v[6:9], v[168:171], v[216:219], v[6:9]
	s_setprio 0
	s_setprio 1
	v_mfma_f32_16x16x32_bf16 v[58:61], v[172:175], v[188:191], v[58:61]
	v_mfma_f32_16x16x32_bf16 v[50:53], v[180:183], v[188:191], v[50:53]
	v_mfma_f32_16x16x32_bf16 v[42:45], v[172:175], v[192:195], v[42:45]
	v_mfma_f32_16x16x32_bf16 v[34:37], v[180:183], v[192:195], v[34:37]
	v_mfma_f32_16x16x32_bf16 v[26:29], v[172:175], v[204:207], v[26:29]
	v_mfma_f32_16x16x32_bf16 v[18:21], v[180:183], v[204:207], v[18:21]
	v_mfma_f32_16x16x32_bf16 v[10:13], v[172:175], v[208:211], v[10:13]
	v_mfma_f32_16x16x32_bf16 v[2:5], v[180:183], v[208:211], v[2:5]
	v_mfma_f32_16x16x32_bf16 v[58:61], v[176:179], v[196:199], v[58:61]
	v_mfma_f32_16x16x32_bf16 v[50:53], v[184:187], v[196:199], v[50:53]
	v_mfma_f32_16x16x32_bf16 v[42:45], v[176:179], v[200:203], v[42:45]
	v_mfma_f32_16x16x32_bf16 v[34:37], v[184:187], v[200:203], v[34:37]
	v_mfma_f32_16x16x32_bf16 v[26:29], v[176:179], v[212:215], v[26:29]
	v_mfma_f32_16x16x32_bf16 v[18:21], v[184:187], v[212:215], v[18:21]
	v_mfma_f32_16x16x32_bf16 v[10:13], v[176:179], v[216:219], v[10:13]
	v_mfma_f32_16x16x32_bf16 v[2:5], v[184:187], v[216:219], v[2:5]
	s_setprio 0
	s_barrier
	s_add_i32 s63, s63, 2
	s_add_u32 s22, s22, 0x100
	s_addc_u32 s23, s23, 0
	s_add_u32 s61, s61, 0x100
	s_addc_u32 s62, s62, 0
	s_cmp_gt_u32 s63, 13
	s_cbranch_scc1 .LBB0_1725

.Lpeel_5:
	s_mov_b32 s100, 0
	ds_read_b128 v[150:153], v245
	ds_read_b128 v[160:163], v246
	ds_read_b128 v[164:167], v245 offset:2048
	ds_read_b128 v[168:171], v246 offset:2048
	ds_read_b128 v[172:175], v245 offset:16384
	ds_read_b128 v[176:179], v246 offset:16384
	ds_read_b128 v[180:183], v245 offset:18432
	ds_read_b128 v[184:187], v246 offset:18432
	s_add_u32 s26, s22, 0xfffc0080
	s_addc_u32 s27, s23, -1
	s_and_b64 s[24:25], s[24:25], exec
	s_cselect_b32 s27, s13, s27
	s_cselect_b32 s26, s58, s26
	s_cselect_b32 s25, s5, s62
	s_cselect_b32 s24, s59, s61
	s_add_i32 m0, s38, 0xc000
	ds_read_b128 v[188:191], v157
	s_waitcnt lgkmcnt(0)
	ds_read_b128 v[192:195], v157 offset:2048
	ds_read_b128 v[196:199], v158
	ds_read_b128 v[200:203], v158 offset:2048
	ds_read_b128 v[204:207], v157 offset:4096
	ds_read_b128 v[208:211], v157 offset:6144
	ds_read_b128 v[212:215], v158 offset:4096
	ds_read_b128 v[216:219], v158 offset:6144
	global_load_lds_dwordx4 v140, s[22:23]
	s_add_i32 m0, s38, 0xe000
	s_nop 0
	global_load_lds_dwordx4 v142, s[22:23]
	s_waitcnt vmcnt(8)
	s_waitcnt lgkmcnt(0)
	s_barrier
	s_setprio 1
	v_mfma_f32_16x16x32_bf16 v[126:129], v[150:153], v[188:191], 0
	v_mfma_f32_16x16x32_bf16 v[118:121], v[164:167], v[188:191], 0
	s_waitcnt lgkmcnt(0)
	v_mfma_f32_16x16x32_bf16 v[110:113], v[150:153], v[192:195], 0
	v_mfma_f32_16x16x32_bf16 v[102:105], v[164:167], v[192:195], 0
	v_mfma_f32_16x16x32_bf16 v[94:97], v[150:153], v[204:207], 0
	v_mfma_f32_16x16x32_bf16 v[86:89], v[164:167], v[204:207], 0
	v_mfma_f32_16x16x32_bf16 v[78:81], v[150:153], v[208:211], 0
	v_mfma_f32_16x16x32_bf16 v[70:73], v[164:167], v[208:211], 0
	v_mfma_f32_16x16x32_bf16 v[126:129], v[160:163], v[196:199], v[126:129]
	v_mfma_f32_16x16x32_bf16 v[118:121], v[168:171], v[196:199], v[118:121]
	v_mfma_f32_16x16x32_bf16 v[110:113], v[160:163], v[200:203], v[110:113]
	v_mfma_f32_16x16x32_bf16 v[102:105], v[168:171], v[200:203], v[102:105]
	v_mfma_f32_16x16x32_bf16 v[94:97], v[160:163], v[212:215], v[94:97]
	v_mfma_f32_16x16x32_bf16 v[86:89], v[168:171], v[212:215], v[86:89]
	v_mfma_f32_16x16x32_bf16 v[78:81], v[160:163], v[216:219], v[78:81]
	v_mfma_f32_16x16x32_bf16 v[70:73], v[168:171], v[216:219], v[70:73]
	s_setprio 0
	s_setprio 1
	v_mfma_f32_16x16x32_bf16 v[122:125], v[172:175], v[188:191], 0
	v_mfma_f32_16x16x32_bf16 v[114:117], v[180:183], v[188:191], 0
	v_mfma_f32_16x16x32_bf16 v[106:109], v[172:175], v[192:195], 0
	v_mfma_f32_16x16x32_bf16 v[98:101], v[180:183], v[192:195], 0
	v_mfma_f32_16x16x32_bf16 v[90:93], v[172:175], v[204:207], 0
	v_mfma_f32_16x16x32_bf16 v[82:85], v[180:183], v[204:207], 0
	v_mfma_f32_16x16x32_bf16 v[74:77], v[172:175], v[208:211], 0
	v_mfma_f32_16x16x32_bf16 v[66:69], v[180:183], v[208:211], 0
	v_mfma_f32_16x16x32_bf16 v[122:125], v[176:179], v[196:199], v[122:125]
	v_mfma_f32_16x16x32_bf16 v[114:117], v[184:187], v[196:199], v[114:117]
	v_mfma_f32_16x16x32_bf16 v[106:109], v[176:179], v[200:203], v[106:109]
	v_mfma_f32_16x16x32_bf16 v[98:101], v[184:187], v[200:203], v[98:101]
	v_mfma_f32_16x16x32_bf16 v[90:93], v[176:179], v[212:215], v[90:93]
	v_mfma_f32_16x16x32_bf16 v[82:85], v[184:187], v[212:215], v[82:85]
	v_mfma_f32_16x16x32_bf16 v[74:77], v[176:179], v[216:219], v[74:77]
	v_mfma_f32_16x16x32_bf16 v[66:69], v[184:187], v[216:219], v[66:69]
	s_setprio 0
	s_barrier
	s_add_i32 s64, s49, s21
	s_mov_b32 m0, s64
	ds_read_b128 v[188:191], v157 offset:16384
	ds_read_b128 v[192:195], v157 offset:18432
	ds_read_b128 v[196:199], v158 offset:16384
	ds_read_b128 v[200:203], v158 offset:18432
	ds_read_b128 v[204:207], v157 offset:20480
	ds_read_b128 v[208:211], v157 offset:22528
	ds_read_b128 v[212:215], v158 offset:20480
	ds_read_b128 v[216:219], v158 offset:22528
	global_load_lds_dwordx4 v132, s[24:25]
	s_add_i32 m0, s64, 0x2000
	s_add_u32 s64, s24, 0x40000
	v_lshl_add_u64 v[222:223], s[24:25], 0, v[136:137]
	s_addc_u32 s65, s25, 0
	s_add_i32 s66, s51, s21
	global_load_lds_dwordx4 v136, s[24:25]
	s_mov_b32 m0, s66
	v_lshl_add_u64 v[226:227], s[26:27], 0, v[134:135]
	global_load_lds_dwordx4 v132, s[64:65]
	s_add_i32 m0, s66, 0x2000
	s_nop 0
	global_load_lds_dwordx4 v136, s[64:65]
	v_lshl_add_u64 v[224:225], s[26:27], 0, v[130:131]
	s_mov_b32 m0, s38
	s_nop 0
	global_load_lds_dwordx4 v130, s[26:27]
	s_mov_b32 m0, s39
	s_nop 0
	global_load_lds_dwordx4 v134, s[26:27]
	s_waitcnt vmcnt(8)
	s_waitcnt lgkmcnt(0)
	s_barrier
	s_setprio 1
	s_waitcnt lgkmcnt(0)
	v_mfma_f32_16x16x32_bf16 v[62:65], v[150:153], v[188:191], 0
	v_mfma_f32_16x16x32_bf16 v[54:57], v[164:167], v[188:191], 0
	v_mfma_f32_16x16x32_bf16 v[46:49], v[150:153], v[192:195], 0
	v_mfma_f32_16x16x32_bf16 v[38:41], v[164:167], v[192:195], 0
	v_mfma_f32_16x16x32_bf16 v[30:33], v[150:153], v[204:207], 0
	v_mfma_f32_16x16x32_bf16 v[22:25], v[164:167], v[204:207], 0
	v_mfma_f32_16x16x32_bf16 v[14:17], v[150:153], v[208:211], 0
	v_mfma_f32_16x16x32_bf16 v[6:9], v[164:167], v[208:211], 0
	v_mfma_f32_16x16x32_bf16 v[62:65], v[160:163], v[196:199], v[62:65]
	v_mfma_f32_16x16x32_bf16 v[54:57], v[168:171], v[196:199], v[54:57]
	v_mfma_f32_16x16x32_bf16 v[46:49], v[160:163], v[200:203], v[46:49]
	v_mfma_f32_16x16x32_bf16 v[38:41], v[168:171], v[200:203], v[38:41]
	v_mfma_f32_16x16x32_bf16 v[30:33], v[160:163], v[212:215], v[30:33]
	v_mfma_f32_16x16x32_bf16 v[22:25], v[168:171], v[212:215], v[22:25]
	v_mfma_f32_16x16x32_bf16 v[14:17], v[160:163], v[216:219], v[14:17]
	v_mfma_f32_16x16x32_bf16 v[6:9], v[168:171], v[216:219], v[6:9]
	s_setprio 0
	s_setprio 1
	v_mfma_f32_16x16x32_bf16 v[58:61], v[172:175], v[188:191], 0
	v_mfma_f32_16x16x32_bf16 v[50:53], v[180:183], v[188:191], 0
	v_mfma_f32_16x16x32_bf16 v[42:45], v[172:175], v[192:195], 0
	v_mfma_f32_16x16x32_bf16 v[34:37], v[180:183], v[192:195], 0
	v_mfma_f32_16x16x32_bf16 v[26:29], v[172:175], v[204:207], 0
	v_mfma_f32_16x16x32_bf16 v[18:21], v[180:183], v[204:207], 0
	v_mfma_f32_16x16x32_bf16 v[10:13], v[172:175], v[208:211], 0
	v_mfma_f32_16x16x32_bf16 v[2:5], v[180:183], v[208:211], 0
	v_mfma_f32_16x16x32_bf16 v[58:61], v[176:179], v[196:199], v[58:61]
	v_mfma_f32_16x16x32_bf16 v[50:53], v[184:187], v[196:199], v[50:53]
	v_mfma_f32_16x16x32_bf16 v[42:45], v[176:179], v[200:203], v[42:45]
	v_mfma_f32_16x16x32_bf16 v[34:37], v[184:187], v[200:203], v[34:37]
	v_mfma_f32_16x16x32_bf16 v[26:29], v[176:179], v[212:215], v[26:29]
	v_mfma_f32_16x16x32_bf16 v[18:21], v[184:187], v[212:215], v[18:21]
	v_mfma_f32_16x16x32_bf16 v[10:13], v[176:179], v[216:219], v[10:13]
	v_mfma_f32_16x16x32_bf16 v[2:5], v[184:187], v[216:219], v[2:5]
	s_setprio 0
	s_barrier
	s_add_i32 s64, 0, 0x18000
	s_add_i32 s65, 0, 0x1c000
	ds_read_b128 v[150:153], v245 offset:32768
	ds_read_b128 v[160:163], v246 offset:32768
	ds_read_b128 v[164:167], v245 offset:34816
	ds_read_b128 v[168:171], v246 offset:34816
	ds_read_b128 v[172:175], v245 offset:49152
	ds_read_b128 v[176:179], v246 offset:49152
	ds_read_b128 v[180:183], v245 offset:51200
	ds_read_b128 v[184:187], v246 offset:51200
	s_add_u32 s26, s26, 0x40000
	s_addc_u32 s27, s27, 0
	s_mov_b32 m0, s40
	ds_read_b128 v[188:191], v157 offset:32768
	ds_read_b128 v[192:195], v157 offset:34816
	ds_read_b128 v[196:199], v158 offset:32768
	ds_read_b128 v[200:203], v158 offset:34816
	ds_read_b128 v[204:207], v157 offset:36864
	ds_read_b128 v[208:211], v157 offset:38912
	ds_read_b128 v[212:215], v158 offset:36864
	ds_read_b128 v[216:219], v158 offset:38912
	global_load_lds_dwordx4 v130, s[26:27]
	s_mov_b32 m0, s41
	s_nop 0
	global_load_lds_dwordx4 v134, s[26:27]
	s_waitcnt vmcnt(8)
	s_waitcnt lgkmcnt(0)
	s_barrier
	s_setprio 1
	s_waitcnt lgkmcnt(0)
	v_mfma_f32_16x16x32_bf16 v[126:129], v[150:153], v[188:191], v[126:129]
	v_mfma_f32_16x16x32_bf16 v[118:121], v[164:167], v[188:191], v[118:121]
	v_mfma_f32_16x16x32_bf16 v[110:113], v[150:153], v[192:195], v[110:113]
	v_mfma_f32_16x16x32_bf16 v[102:105], v[164:167], v[192:195], v[102:105]
	v_mfma_f32_16x16x32_bf16 v[94:97], v[150:153], v[204:207], v[94:97]
	v_mfma_f32_16x16x32_bf16 v[86:89], v[164:167], v[204:207], v[86:89]
	v_mfma_f32_16x16x32_bf16 v[78:81], v[150:153], v[208:211], v[78:81]
	v_mfma_f32_16x16x32_bf16 v[70:73], v[164:167], v[208:211], v[70:73]
	v_mfma_f32_16x16x32_bf16 v[126:129], v[160:163], v[196:199], v[126:129]
	v_mfma_f32_16x16x32_bf16 v[118:121], v[168:171], v[196:199], v[118:121]
	v_mfma_f32_16x16x32_bf16 v[110:113], v[160:163], v[200:203], v[110:113]
	v_mfma_f32_16x16x32_bf16 v[102:105], v[168:171], v[200:203], v[102:105]
	v_mfma_f32_16x16x32_bf16 v[94:97], v[160:163], v[212:215], v[94:97]
	v_mfma_f32_16x16x32_bf16 v[86:89], v[168:171], v[212:215], v[86:89]
	v_mfma_f32_16x16x32_bf16 v[78:81], v[160:163], v[216:219], v[78:81]
	v_mfma_f32_16x16x32_bf16 v[70:73], v[168:171], v[216:219], v[70:73]
	s_setprio 0
	s_setprio 1
	v_mfma_f32_16x16x32_bf16 v[122:125], v[172:175], v[188:191], v[122:125]
	v_mfma_f32_16x16x32_bf16 v[114:117], v[180:183], v[188:191], v[114:117]
	v_mfma_f32_16x16x32_bf16 v[106:109], v[172:175], v[192:195], v[106:109]
	v_mfma_f32_16x16x32_bf16 v[98:101], v[180:183], v[192:195], v[98:101]
	v_mfma_f32_16x16x32_bf16 v[90:93], v[172:175], v[204:207], v[90:93]
	v_mfma_f32_16x16x32_bf16 v[82:85], v[180:183], v[204:207], v[82:85]
	v_mfma_f32_16x16x32_bf16 v[74:77], v[172:175], v[208:211], v[74:77]
	v_mfma_f32_16x16x32_bf16 v[66:69], v[180:183], v[208:211], v[66:69]
	v_mfma_f32_16x16x32_bf16 v[122:125], v[176:179], v[196:199], v[122:125]
	v_mfma_f32_16x16x32_bf16 v[114:117], v[184:187], v[196:199], v[114:117]
	v_mfma_f32_16x16x32_bf16 v[106:109], v[176:179], v[200:203], v[106:109]
	v_mfma_f32_16x16x32_bf16 v[98:101], v[184:187], v[200:203], v[98:101]
	v_mfma_f32_16x16x32_bf16 v[90:93], v[176:179], v[212:215], v[90:93]
	v_mfma_f32_16x16x32_bf16 v[82:85], v[184:187], v[212:215], v[82:85]
	v_mfma_f32_16x16x32_bf16 v[74:77], v[176:179], v[216:219], v[74:77]
	v_mfma_f32_16x16x32_bf16 v[66:69], v[184:187], v[216:219], v[66:69]
	s_setprio 0
	s_barrier
	s_add_i32 s26, s64, s21
	s_add_i32 m0, s26, 0xffffff80
	ds_read_b128 v[188:191], v157 offset:49152
	ds_read_b128 v[192:195], v157 offset:51200
	ds_read_b128 v[196:199], v158 offset:49152
	ds_read_b128 v[200:203], v158 offset:51200
	ds_read_b128 v[204:207], v157 offset:53248
	ds_read_b128 v[208:211], v157 offset:55296
	ds_read_b128 v[212:215], v158 offset:53248
	ds_read_b128 v[216:219], v158 offset:55296
	global_load_lds_dwordx4 v132, s[24:25] offset:128
	s_add_i32 m0, s26, 0x2000
	s_add_u32 s24, s24, 0x40080
	v_lshl_add_u64 v[220:221], v[222:223], 0, s[8:9]
	s_addc_u32 s25, s25, 0
	s_add_i32 s26, s65, s21
	global_load_lds_dwordx4 v[220:221], off
	s_mov_b32 m0, s26
	s_nop 0
	global_load_lds_dwordx4 v132, s[24:25]
	s_add_i32 m0, s26, 0x2000
	s_nop 0
	global_load_lds_dwordx4 v136, s[24:25]
	v_lshl_add_u64 v[220:221], v[224:225], 0, s[8:9]
	s_mov_b32 m0, s44
	s_nop 0
	global_load_lds_dwordx4 v[220:221], off
	v_lshl_add_u64 v[220:221], v[226:227], 0, s[8:9]
	s_mov_b32 m0, s45
	s_nop 0
	global_load_lds_dwordx4 v[220:221], off
	s_waitcnt vmcnt(8)
	s_waitcnt lgkmcnt(0)
	s_barrier
	s_setprio 1
	s_waitcnt lgkmcnt(0)
	v_mfma_f32_16x16x32_bf16 v[62:65], v[150:153], v[188:191], v[62:65]
	v_mfma_f32_16x16x32_bf16 v[54:57], v[164:167], v[188:191], v[54:57]
	v_mfma_f32_16x16x32_bf16 v[46:49], v[150:153], v[192:195], v[46:49]
	v_mfma_f32_16x16x32_bf16 v[38:41], v[164:167], v[192:195], v[38:41]
	v_mfma_f32_16x16x32_bf16 v[30:33], v[150:153], v[204:207], v[30:33]
	v_mfma_f32_16x16x32_bf16 v[22:25], v[164:167], v[204:207], v[22:25]
	v_mfma_f32_16x16x32_bf16 v[14:17], v[150:153], v[208:211], v[14:17]
	v_mfma_f32_16x16x32_bf16 v[6:9], v[164:167], v[208:211], v[6:9]
	v_mfma_f32_16x16x32_bf16 v[62:65], v[160:163], v[196:199], v[62:65]
	v_mfma_f32_16x16x32_bf16 v[54:57], v[168:171], v[196:199], v[54:57]
	v_mfma_f32_16x16x32_bf16 v[46:49], v[160:163], v[200:203], v[46:49]
	v_mfma_f32_16x16x32_bf16 v[38:41], v[168:171], v[200:203], v[38:41]
	v_mfma_f32_16x16x32_bf16 v[30:33], v[160:163], v[212:215], v[30:33]
	v_mfma_f32_16x16x32_bf16 v[22:25], v[168:171], v[212:215], v[22:25]
	v_mfma_f32_16x16x32_bf16 v[14:17], v[160:163], v[216:219], v[14:17]
	v_mfma_f32_16x16x32_bf16 v[6:9], v[168:171], v[216:219], v[6:9]
	s_setprio 0
	s_setprio 1
	v_mfma_f32_16x16x32_bf16 v[58:61], v[172:175], v[188:191], v[58:61]
	v_mfma_f32_16x16x32_bf16 v[50:53], v[180:183], v[188:191], v[50:53]
	v_mfma_f32_16x16x32_bf16 v[42:45], v[172:175], v[192:195], v[42:45]
	v_mfma_f32_16x16x32_bf16 v[34:37], v[180:183], v[192:195], v[34:37]
	v_mfma_f32_16x16x32_bf16 v[26:29], v[172:175], v[204:207], v[26:29]
	v_mfma_f32_16x16x32_bf16 v[18:21], v[180:183], v[204:207], v[18:21]
	v_mfma_f32_16x16x32_bf16 v[10:13], v[172:175], v[208:211], v[10:13]
	v_mfma_f32_16x16x32_bf16 v[2:5], v[180:183], v[208:211], v[2:5]
	v_mfma_f32_16x16x32_bf16 v[58:61], v[176:179], v[196:199], v[58:61]
	v_mfma_f32_16x16x32_bf16 v[50:53], v[184:187], v[196:199], v[50:53]
	v_mfma_f32_16x16x32_bf16 v[42:45], v[176:179], v[200:203], v[42:45]
	v_mfma_f32_16x16x32_bf16 v[34:37], v[184:187], v[200:203], v[34:37]
	v_mfma_f32_16x16x32_bf16 v[26:29], v[176:179], v[212:215], v[26:29]
	v_mfma_f32_16x16x32_bf16 v[18:21], v[184:187], v[212:215], v[18:21]
	v_mfma_f32_16x16x32_bf16 v[10:13], v[176:179], v[216:219], v[10:13]
	v_mfma_f32_16x16x32_bf16 v[2:5], v[184:187], v[216:219], v[2:5]
	s_setprio 0
	s_barrier
	s_add_i32 s63, s63, 2
	s_add_u32 s22, s22, 0x100
	s_addc_u32 s23, s23, 0
	s_add_u32 s61, s61, 0x100
	s_addc_u32 s62, s62, 0
	s_cmp_gt_u32 s63, 13
	s_cbranch_scc1 .LBB0_1725
	s_branch .LBB0_1722

.LBB0_1826:
	s_add_u32 s4, s42, 0xb0080
	s_addc_u32 s5, s43, 0
	s_add_u32 s64, s40, 0x100
	v_add_u32_e32 v245, 0x10000, v218
	v_add_u32_e32 v246, 0x10000, v219
	s_mov_b32 s100, 1
	s_addc_u32 s65, s41, 0
	s_mov_b32 s66, -2
	s_waitcnt lgkmcnt(0)
	s_waitcnt vmcnt(0)
.LBB0_1827:
	s_cmp_lg_u32 s100, 0
	s_cbranch_scc1 .Lpeel_6
	ds_read_b128 v[120:123], v220
	ds_read_b128 v[128:131], v221
	ds_read_b128 v[136:139], v222
	ds_read_b128 v[140:143], v223
	ds_read_b128 v[144:147], v224
	ds_read_b128 v[148:151], v225
	ds_read_b128 v[152:155], v226
	ds_read_b128 v[156:159], v227
	s_add_u32 s40, s4, 0xfff50080
	s_addc_u32 s41, s5, -1
	s_cmp_eq_u32 s66, 40
	s_cselect_b32 s43, s29, s41
	s_cselect_b32 s42, s28, s40
	s_cselect_b32 s41, s35, s65
	s_cselect_b32 s40, s34, s64
	s_add_i32 m0, s44, 0xc000
	ds_read_b128 v[160:163], v228
	ds_read_b128 v[164:167], v228 offset:2048
	ds_read_b128 v[168:171], v229
	ds_read_b128 v[172:175], v229 offset:2048
	ds_read_b128 v[176:179], v228 offset:4096
	ds_read_b128 v[180:183], v228 offset:6144
	ds_read_b128 v[184:187], v229 offset:4096
	ds_read_b128 v[188:191], v229 offset:6144
	global_load_lds_dwordx4 v202, s[4:5]
	s_add_i32 m0, s44, 0xe000
	s_nop 0
	global_load_lds_dwordx4 v204, s[4:5]
	s_waitcnt vmcnt(8)
	s_waitcnt lgkmcnt(0)
	s_barrier
	s_setprio 1
	s_waitcnt lgkmcnt(0)
	v_mfma_f32_16x16x32_bf16 v[132:135], v[120:123], v[160:163], v[132:135]
	v_mfma_f32_16x16x32_bf16 v[124:127], v[136:139], v[160:163], v[124:127]
	v_mfma_f32_16x16x32_bf16 v[108:111], v[120:123], v[164:167], v[108:111]
	v_mfma_f32_16x16x32_bf16 v[104:107], v[136:139], v[164:167], v[104:107]
	v_mfma_f32_16x16x32_bf16 v[92:95], v[120:123], v[176:179], v[92:95]
	v_mfma_f32_16x16x32_bf16 v[88:91], v[136:139], v[176:179], v[88:91]
	v_mfma_f32_16x16x32_bf16 v[76:79], v[120:123], v[180:183], v[76:79]
	v_mfma_f32_16x16x32_bf16 v[72:75], v[136:139], v[180:183], v[72:75]
	v_mfma_f32_16x16x32_bf16 v[132:135], v[128:131], v[168:171], v[132:135]
	v_mfma_f32_16x16x32_bf16 v[124:127], v[140:143], v[168:171], v[124:127]
	v_mfma_f32_16x16x32_bf16 v[108:111], v[128:131], v[172:175], v[108:111]
	v_mfma_f32_16x16x32_bf16 v[104:107], v[140:143], v[172:175], v[104:107]
	v_mfma_f32_16x16x32_bf16 v[92:95], v[128:131], v[184:187], v[92:95]
	v_mfma_f32_16x16x32_bf16 v[88:91], v[140:143], v[184:187], v[88:91]
	v_mfma_f32_16x16x32_bf16 v[76:79], v[128:131], v[188:191], v[76:79]
	v_mfma_f32_16x16x32_bf16 v[72:75], v[140:143], v[188:191], v[72:75]
	s_setprio 0
	s_setprio 1
	v_mfma_f32_16x16x32_bf16 v[116:119], v[144:147], v[160:163], v[116:119]
	v_mfma_f32_16x16x32_bf16 v[112:115], v[152:155], v[160:163], v[112:115]
	v_mfma_f32_16x16x32_bf16 v[100:103], v[144:147], v[164:167], v[100:103]
	v_mfma_f32_16x16x32_bf16 v[96:99], v[152:155], v[164:167], v[96:99]
	v_mfma_f32_16x16x32_bf16 v[84:87], v[144:147], v[176:179], v[84:87]
	v_mfma_f32_16x16x32_bf16 v[80:83], v[152:155], v[176:179], v[80:83]
	v_mfma_f32_16x16x32_bf16 v[68:71], v[144:147], v[180:183], v[68:71]
	v_mfma_f32_16x16x32_bf16 v[64:67], v[152:155], v[180:183], v[64:67]
	v_mfma_f32_16x16x32_bf16 v[116:119], v[148:151], v[168:171], v[116:119]
	v_mfma_f32_16x16x32_bf16 v[112:115], v[156:159], v[168:171], v[112:115]
	v_mfma_f32_16x16x32_bf16 v[100:103], v[148:151], v[172:175], v[100:103]
	v_mfma_f32_16x16x32_bf16 v[96:99], v[156:159], v[172:175], v[96:99]
	v_mfma_f32_16x16x32_bf16 v[84:87], v[148:151], v[184:187], v[84:87]
	v_mfma_f32_16x16x32_bf16 v[80:83], v[156:159], v[184:187], v[80:83]
	v_mfma_f32_16x16x32_bf16 v[68:71], v[148:151], v[188:191], v[68:71]
	v_mfma_f32_16x16x32_bf16 v[64:67], v[156:159], v[188:191], v[64:67]
	s_setprio 0
	s_barrier
	s_add_i32 s67, s58, s39
	s_mov_b32 m0, s67
	ds_read_b128 v[160:163], v228 offset:16384
	ds_read_b128 v[164:167], v228 offset:18432
	ds_read_b128 v[168:171], v229 offset:16384
	ds_read_b128 v[172:175], v229 offset:18432
	ds_read_b128 v[176:179], v228 offset:20480
	ds_read_b128 v[180:183], v228 offset:22528
	ds_read_b128 v[184:187], v229 offset:20480
	ds_read_b128 v[188:191], v229 offset:22528
	global_load_lds_dwordx4 v194, s[40:41]
	s_add_i32 m0, s67, 0x2000
	s_add_u32 s68, s40, 0xb0000
	v_lshl_add_u64 v[212:213], s[40:41], 0, v[198:199]
	s_addc_u32 s69, s41, 0
	s_add_i32 s67, s59, s39
	global_load_lds_dwordx4 v198, s[40:41]
	s_mov_b32 m0, s67
	v_lshl_add_u64 v[234:235], s[42:43], 0, v[196:197]
	global_load_lds_dwordx4 v194, s[68:69]
	s_add_i32 m0, s67, 0x2000
	s_nop 0
	global_load_lds_dwordx4 v198, s[68:69]
	v_lshl_add_u64 v[214:215], s[42:43], 0, v[192:193]
	s_mov_b32 m0, s44
	s_nop 0
	global_load_lds_dwordx4 v192, s[42:43]
	s_mov_b32 m0, s45
	s_nop 0
	global_load_lds_dwordx4 v196, s[42:43]
	s_waitcnt vmcnt(8)
	s_waitcnt lgkmcnt(0)
	s_barrier
	s_setprio 1
	s_waitcnt lgkmcnt(0)
	v_mfma_f32_16x16x32_bf16 v[60:63], v[120:123], v[160:163], v[60:63]
	v_mfma_f32_16x16x32_bf16 v[56:59], v[136:139], v[160:163], v[56:59]
	v_mfma_f32_16x16x32_bf16 v[44:47], v[120:123], v[164:167], v[44:47]
	v_mfma_f32_16x16x32_bf16 v[40:43], v[136:139], v[164:167], v[40:43]
	v_mfma_f32_16x16x32_bf16 v[28:31], v[120:123], v[176:179], v[28:31]
	v_mfma_f32_16x16x32_bf16 v[24:27], v[136:139], v[176:179], v[24:27]
	v_mfma_f32_16x16x32_bf16 v[12:15], v[120:123], v[180:183], v[12:15]
	v_mfma_f32_16x16x32_bf16 v[8:11], v[136:139], v[180:183], v[8:11]
	v_mfma_f32_16x16x32_bf16 v[60:63], v[128:131], v[168:171], v[60:63]
	v_mfma_f32_16x16x32_bf16 v[56:59], v[140:143], v[168:171], v[56:59]
	v_mfma_f32_16x16x32_bf16 v[44:47], v[128:131], v[172:175], v[44:47]
	v_mfma_f32_16x16x32_bf16 v[40:43], v[140:143], v[172:175], v[40:43]
	v_mfma_f32_16x16x32_bf16 v[28:31], v[128:131], v[184:187], v[28:31]
	v_mfma_f32_16x16x32_bf16 v[24:27], v[140:143], v[184:187], v[24:27]
	v_mfma_f32_16x16x32_bf16 v[12:15], v[128:131], v[188:191], v[12:15]
	v_mfma_f32_16x16x32_bf16 v[8:11], v[140:143], v[188:191], v[8:11]
	s_setprio 0
	s_setprio 1
	v_mfma_f32_16x16x32_bf16 v[52:55], v[144:147], v[160:163], v[52:55]
	v_mfma_f32_16x16x32_bf16 v[48:51], v[152:155], v[160:163], v[48:51]
	v_mfma_f32_16x16x32_bf16 v[36:39], v[144:147], v[164:167], v[36:39]
	v_mfma_f32_16x16x32_bf16 v[32:35], v[152:155], v[164:167], v[32:35]
	v_mfma_f32_16x16x32_bf16 v[20:23], v[144:147], v[176:179], v[20:23]
	v_mfma_f32_16x16x32_bf16 v[16:19], v[152:155], v[176:179], v[16:19]
	v_mfma_f32_16x16x32_bf16 v[4:7], v[144:147], v[180:183], v[4:7]
	v_mfma_f32_16x16x32_bf16 v[0:3], v[152:155], v[180:183], v[0:3]
	v_mfma_f32_16x16x32_bf16 v[52:55], v[148:151], v[168:171], v[52:55]
	v_mfma_f32_16x16x32_bf16 v[48:51], v[156:159], v[168:171], v[48:51]
	v_mfma_f32_16x16x32_bf16 v[36:39], v[148:151], v[172:175], v[36:39]
	v_mfma_f32_16x16x32_bf16 v[32:35], v[156:159], v[172:175], v[32:35]
	v_mfma_f32_16x16x32_bf16 v[20:23], v[148:151], v[184:187], v[20:23]
	v_mfma_f32_16x16x32_bf16 v[16:19], v[156:159], v[184:187], v[16:19]
	v_mfma_f32_16x16x32_bf16 v[4:7], v[148:151], v[188:191], v[4:7]
	v_mfma_f32_16x16x32_bf16 v[0:3], v[156:159], v[188:191], v[0:3]
	s_setprio 0
	s_barrier
	s_add_i32 s67, 0, 0x18000
	s_add_i32 s68, 0, 0x1c000
	ds_read_b128 v[120:123], v245 offset:32768
	ds_read_b128 v[128:131], v246 offset:32768
	ds_read_b128 v[136:139], v230
	ds_read_b128 v[140:143], v231
	ds_read_b128 v[144:147], v245 offset:49152
	ds_read_b128 v[148:151], v246 offset:49152
	ds_read_b128 v[152:155], v232
	ds_read_b128 v[156:159], v233
	s_add_u32 s42, s42, 0xb0000
	s_addc_u32 s43, s43, 0
	s_mov_b32 m0, s46
	ds_read_b128 v[160:163], v228 offset:32768
	ds_read_b128 v[164:167], v228 offset:34816
	ds_read_b128 v[168:171], v229 offset:32768
	ds_read_b128 v[172:175], v229 offset:34816
	ds_read_b128 v[176:179], v228 offset:36864
	ds_read_b128 v[180:183], v228 offset:38912
	ds_read_b128 v[184:187], v229 offset:36864
	ds_read_b128 v[188:191], v229 offset:38912
	global_load_lds_dwordx4 v192, s[42:43]
	s_mov_b32 m0, s47
	s_nop 0
	global_load_lds_dwordx4 v196, s[42:43]
	s_waitcnt vmcnt(8)
	s_waitcnt lgkmcnt(0)
	s_barrier
	s_setprio 1
	s_waitcnt lgkmcnt(0)
	v_mfma_f32_16x16x32_bf16 v[132:135], v[120:123], v[160:163], v[132:135]
	v_mfma_f32_16x16x32_bf16 v[124:127], v[136:139], v[160:163], v[124:127]
	v_mfma_f32_16x16x32_bf16 v[108:111], v[120:123], v[164:167], v[108:111]
	v_mfma_f32_16x16x32_bf16 v[104:107], v[136:139], v[164:167], v[104:107]
	v_mfma_f32_16x16x32_bf16 v[92:95], v[120:123], v[176:179], v[92:95]
	v_mfma_f32_16x16x32_bf16 v[88:91], v[136:139], v[176:179], v[88:91]
	v_mfma_f32_16x16x32_bf16 v[76:79], v[120:123], v[180:183], v[76:79]
	v_mfma_f32_16x16x32_bf16 v[72:75], v[136:139], v[180:183], v[72:75]
	v_mfma_f32_16x16x32_bf16 v[132:135], v[128:131], v[168:171], v[132:135]
	v_mfma_f32_16x16x32_bf16 v[124:127], v[140:143], v[168:171], v[124:127]
	v_mfma_f32_16x16x32_bf16 v[108:111], v[128:131], v[172:175], v[108:111]
	v_mfma_f32_16x16x32_bf16 v[104:107], v[140:143], v[172:175], v[104:107]
	v_mfma_f32_16x16x32_bf16 v[92:95], v[128:131], v[184:187], v[92:95]
	v_mfma_f32_16x16x32_bf16 v[88:91], v[140:143], v[184:187], v[88:91]
	v_mfma_f32_16x16x32_bf16 v[76:79], v[128:131], v[188:191], v[76:79]
	v_mfma_f32_16x16x32_bf16 v[72:75], v[140:143], v[188:191], v[72:75]
	s_setprio 0
	s_setprio 1
	v_mfma_f32_16x16x32_bf16 v[116:119], v[144:147], v[160:163], v[116:119]
	v_mfma_f32_16x16x32_bf16 v[112:115], v[152:155], v[160:163], v[112:115]
	v_mfma_f32_16x16x32_bf16 v[100:103], v[144:147], v[164:167], v[100:103]
	v_mfma_f32_16x16x32_bf16 v[96:99], v[152:155], v[164:167], v[96:99]
	v_mfma_f32_16x16x32_bf16 v[84:87], v[144:147], v[176:179], v[84:87]
	v_mfma_f32_16x16x32_bf16 v[80:83], v[152:155], v[176:179], v[80:83]
	v_mfma_f32_16x16x32_bf16 v[68:71], v[144:147], v[180:183], v[68:71]
	v_mfma_f32_16x16x32_bf16 v[64:67], v[152:155], v[180:183], v[64:67]
	v_mfma_f32_16x16x32_bf16 v[116:119], v[148:151], v[168:171], v[116:119]
	v_mfma_f32_16x16x32_bf16 v[112:115], v[156:159], v[168:171], v[112:115]
	v_mfma_f32_16x16x32_bf16 v[100:103], v[148:151], v[172:175], v[100:103]
	v_mfma_f32_16x16x32_bf16 v[96:99], v[156:159], v[172:175], v[96:99]
	v_mfma_f32_16x16x32_bf16 v[84:87], v[148:151], v[184:187], v[84:87]
	v_mfma_f32_16x16x32_bf16 v[80:83], v[156:159], v[184:187], v[80:83]
	v_mfma_f32_16x16x32_bf16 v[68:71], v[148:151], v[188:191], v[68:71]
	v_mfma_f32_16x16x32_bf16 v[64:67], v[156:159], v[188:191], v[64:67]
	s_setprio 0
	s_barrier
	s_add_i32 s42, s67, s39
	s_add_i32 m0, s42, 0xffffff80
	ds_read_b128 v[160:163], v228 offset:49152
	ds_read_b128 v[164:167], v228 offset:51200
	ds_read_b128 v[168:171], v229 offset:49152
	ds_read_b128 v[172:175], v229 offset:51200
	ds_read_b128 v[176:179], v228 offset:53248
	ds_read_b128 v[180:183], v228 offset:55296
	ds_read_b128 v[184:187], v229 offset:53248
	ds_read_b128 v[188:191], v229 offset:55296
	global_load_lds_dwordx4 v194, s[40:41] offset:128
	s_add_i32 m0, s42, 0x2000
	s_add_u32 s40, s40, 0xb0080
	v_lshl_add_u64 v[210:211], v[212:213], 0, s[8:9]
	s_addc_u32 s41, s41, 0
	s_add_i32 s42, s68, s39
	global_load_lds_dwordx4 v[210:211], off
	s_mov_b32 m0, s42
	s_nop 0
	global_load_lds_dwordx4 v194, s[40:41]
	s_add_i32 m0, s42, 0x2000
	s_nop 0
	global_load_lds_dwordx4 v198, s[40:41]
	v_lshl_add_u64 v[210:211], v[214:215], 0, s[8:9]
	s_mov_b32 m0, s51
	s_nop 0
	global_load_lds_dwordx4 v[210:211], off
	v_lshl_add_u64 v[210:211], v[234:235], 0, s[8:9]
	s_mov_b32 m0, s52
	s_nop 0
	global_load_lds_dwordx4 v[210:211], off
	s_waitcnt vmcnt(8)
	s_waitcnt lgkmcnt(0)
	s_barrier
	s_setprio 1
	s_waitcnt lgkmcnt(0)
	v_mfma_f32_16x16x32_bf16 v[60:63], v[120:123], v[160:163], v[60:63]
	v_mfma_f32_16x16x32_bf16 v[56:59], v[136:139], v[160:163], v[56:59]
	v_mfma_f32_16x16x32_bf16 v[44:47], v[120:123], v[164:167], v[44:47]
	v_mfma_f32_16x16x32_bf16 v[40:43], v[136:139], v[164:167], v[40:43]
	v_mfma_f32_16x16x32_bf16 v[28:31], v[120:123], v[176:179], v[28:31]
	v_mfma_f32_16x16x32_bf16 v[24:27], v[136:139], v[176:179], v[24:27]
	v_mfma_f32_16x16x32_bf16 v[12:15], v[120:123], v[180:183], v[12:15]
	v_mfma_f32_16x16x32_bf16 v[8:11], v[136:139], v[180:183], v[8:11]
	v_mfma_f32_16x16x32_bf16 v[60:63], v[128:131], v[168:171], v[60:63]
	v_mfma_f32_16x16x32_bf16 v[56:59], v[140:143], v[168:171], v[56:59]
	v_mfma_f32_16x16x32_bf16 v[44:47], v[128:131], v[172:175], v[44:47]
	v_mfma_f32_16x16x32_bf16 v[40:43], v[140:143], v[172:175], v[40:43]
	v_mfma_f32_16x16x32_bf16 v[28:31], v[128:131], v[184:187], v[28:31]
	v_mfma_f32_16x16x32_bf16 v[24:27], v[140:143], v[184:187], v[24:27]
	v_mfma_f32_16x16x32_bf16 v[12:15], v[128:131], v[188:191], v[12:15]
	v_mfma_f32_16x16x32_bf16 v[8:11], v[140:143], v[188:191], v[8:11]
	s_setprio 0
	s_setprio 1
	v_mfma_f32_16x16x32_bf16 v[52:55], v[144:147], v[160:163], v[52:55]
	v_mfma_f32_16x16x32_bf16 v[48:51], v[152:155], v[160:163], v[48:51]
	v_mfma_f32_16x16x32_bf16 v[36:39], v[144:147], v[164:167], v[36:39]
	v_mfma_f32_16x16x32_bf16 v[32:35], v[152:155], v[164:167], v[32:35]
	v_mfma_f32_16x16x32_bf16 v[20:23], v[144:147], v[176:179], v[20:23]
	v_mfma_f32_16x16x32_bf16 v[16:19], v[152:155], v[176:179], v[16:19]
	v_mfma_f32_16x16x32_bf16 v[4:7], v[144:147], v[180:183], v[4:7]
	v_mfma_f32_16x16x32_bf16 v[0:3], v[152:155], v[180:183], v[0:3]
	v_mfma_f32_16x16x32_bf16 v[52:55], v[148:151], v[168:171], v[52:55]
	v_mfma_f32_16x16x32_bf16 v[48:51], v[156:159], v[168:171], v[48:51]
	v_mfma_f32_16x16x32_bf16 v[36:39], v[148:151], v[172:175], v[36:39]
	v_mfma_f32_16x16x32_bf16 v[32:35], v[156:159], v[172:175], v[32:35]
	v_mfma_f32_16x16x32_bf16 v[20:23], v[148:151], v[184:187], v[20:23]
	v_mfma_f32_16x16x32_bf16 v[16:19], v[156:159], v[184:187], v[16:19]
	v_mfma_f32_16x16x32_bf16 v[4:7], v[148:151], v[188:191], v[4:7]
	v_mfma_f32_16x16x32_bf16 v[0:3], v[156:159], v[188:191], v[0:3]
	s_setprio 0
	s_barrier
	s_add_i32 s66, s66, 2
	s_add_u32 s4, s4, 0x100
	s_addc_u32 s5, s5, 0
	s_add_u32 s64, s64, 0x100
	s_addc_u32 s65, s65, 0
	s_cmp_gt_u32 s66, 41
	s_cbranch_scc0 .LBB0_1827
	s_branch .Lpx_6
.Lpeel_6:
	s_mov_b32 s100, 0
	ds_read_b128 v[120:123], v220
	ds_read_b128 v[128:131], v221
	ds_read_b128 v[136:139], v222
	ds_read_b128 v[140:143], v223
	ds_read_b128 v[144:147], v224
	ds_read_b128 v[148:151], v225
	ds_read_b128 v[152:155], v226
	ds_read_b128 v[156:159], v227
	s_add_u32 s40, s4, 0xfff50080
	s_addc_u32 s41, s5, -1
	s_cmp_eq_u32 s66, 40
	s_cselect_b32 s43, s29, s41
	s_cselect_b32 s42, s28, s40
	s_cselect_b32 s41, s35, s65
	s_cselect_b32 s40, s34, s64
	s_add_i32 m0, s44, 0xc000
	ds_read_b128 v[160:163], v228
	ds_read_b128 v[164:167], v228 offset:2048
	ds_read_b128 v[168:171], v229
	ds_read_b128 v[172:175], v229 offset:2048
	ds_read_b128 v[176:179], v228 offset:4096
	ds_read_b128 v[180:183], v228 offset:6144
	ds_read_b128 v[184:187], v229 offset:4096
	ds_read_b128 v[188:191], v229 offset:6144
	global_load_lds_dwordx4 v202, s[4:5]
	s_add_i32 m0, s44, 0xe000
	s_nop 0
	global_load_lds_dwordx4 v204, s[4:5]
	s_waitcnt vmcnt(8)
	s_waitcnt lgkmcnt(0)
	s_barrier
	s_setprio 1
	s_waitcnt lgkmcnt(0)
	v_mfma_f32_16x16x32_bf16 v[132:135], v[120:123], v[160:163], 0
	v_mfma_f32_16x16x32_bf16 v[124:127], v[136:139], v[160:163], 0
	v_mfma_f32_16x16x32_bf16 v[108:111], v[120:123], v[164:167], 0
	v_mfma_f32_16x16x32_bf16 v[104:107], v[136:139], v[164:167], 0
	v_mfma_f32_16x16x32_bf16 v[92:95], v[120:123], v[176:179], 0
	v_mfma_f32_16x16x32_bf16 v[88:91], v[136:139], v[176:179], 0
	v_mfma_f32_16x16x32_bf16 v[76:79], v[120:123], v[180:183], 0
	v_mfma_f32_16x16x32_bf16 v[72:75], v[136:139], v[180:183], 0
	v_mfma_f32_16x16x32_bf16 v[132:135], v[128:131], v[168:171], v[132:135]
	v_mfma_f32_16x16x32_bf16 v[124:127], v[140:143], v[168:171], v[124:127]
	v_mfma_f32_16x16x32_bf16 v[108:111], v[128:131], v[172:175], v[108:111]
	v_mfma_f32_16x16x32_bf16 v[104:107], v[140:143], v[172:175], v[104:107]
	v_mfma_f32_16x16x32_bf16 v[92:95], v[128:131], v[184:187], v[92:95]
	v_mfma_f32_16x16x32_bf16 v[88:91], v[140:143], v[184:187], v[88:91]
	v_mfma_f32_16x16x32_bf16 v[76:79], v[128:131], v[188:191], v[76:79]
	v_mfma_f32_16x16x32_bf16 v[72:75], v[140:143], v[188:191], v[72:75]
	s_setprio 0
	s_setprio 1
	v_mfma_f32_16x16x32_bf16 v[116:119], v[144:147], v[160:163], 0
	v_mfma_f32_16x16x32_bf16 v[112:115], v[152:155], v[160:163], 0
	v_mfma_f32_16x16x32_bf16 v[100:103], v[144:147], v[164:167], 0
	v_mfma_f32_16x16x32_bf16 v[96:99], v[152:155], v[164:167], 0
	v_mfma_f32_16x16x32_bf16 v[84:87], v[144:147], v[176:179], 0
	v_mfma_f32_16x16x32_bf16 v[80:83], v[152:155], v[176:179], 0
	v_mfma_f32_16x16x32_bf16 v[68:71], v[144:147], v[180:183], 0
	v_mfma_f32_16x16x32_bf16 v[64:67], v[152:155], v[180:183], 0
	v_mfma_f32_16x16x32_bf16 v[116:119], v[148:151], v[168:171], v[116:119]
	v_mfma_f32_16x16x32_bf16 v[112:115], v[156:159], v[168:171], v[112:115]
	v_mfma_f32_16x16x32_bf16 v[100:103], v[148:151], v[172:175], v[100:103]
	v_mfma_f32_16x16x32_bf16 v[96:99], v[156:159], v[172:175], v[96:99]
	v_mfma_f32_16x16x32_bf16 v[84:87], v[148:151], v[184:187], v[84:87]
	v_mfma_f32_16x16x32_bf16 v[80:83], v[156:159], v[184:187], v[80:83]
	v_mfma_f32_16x16x32_bf16 v[68:71], v[148:151], v[188:191], v[68:71]
	v_mfma_f32_16x16x32_bf16 v[64:67], v[156:159], v[188:191], v[64:67]
	s_setprio 0
	s_barrier
	s_add_i32 s67, s58, s39
	s_mov_b32 m0, s67
	ds_read_b128 v[160:163], v228 offset:16384
	ds_read_b128 v[164:167], v228 offset:18432
	ds_read_b128 v[168:171], v229 offset:16384
	ds_read_b128 v[172:175], v229 offset:18432
	ds_read_b128 v[176:179], v228 offset:20480
	ds_read_b128 v[180:183], v228 offset:22528
	ds_read_b128 v[184:187], v229 offset:20480
	ds_read_b128 v[188:191], v229 offset:22528
	global_load_lds_dwordx4 v194, s[40:41]
	s_add_i32 m0, s67, 0x2000
	s_add_u32 s68, s40, 0xb0000
	v_lshl_add_u64 v[212:213], s[40:41], 0, v[198:199]
	s_addc_u32 s69, s41, 0
	s_add_i32 s67, s59, s39
	global_load_lds_dwordx4 v198, s[40:41]
	s_mov_b32 m0, s67
	v_lshl_add_u64 v[234:235], s[42:43], 0, v[196:197]
	global_load_lds_dwordx4 v194, s[68:69]
	s_add_i32 m0, s67, 0x2000
	s_nop 0
	global_load_lds_dwordx4 v198, s[68:69]
	v_lshl_add_u64 v[214:215], s[42:43], 0, v[192:193]
	s_mov_b32 m0, s44
	s_nop 0
	global_load_lds_dwordx4 v192, s[42:43]
	s_mov_b32 m0, s45
	s_nop 0
	global_load_lds_dwordx4 v196, s[42:43]
	s_waitcnt vmcnt(8)
	s_waitcnt lgkmcnt(0)
	s_barrier
	s_setprio 1
	s_waitcnt lgkmcnt(0)
	v_mfma_f32_16x16x32_bf16 v[60:63], v[120:123], v[160:163], 0
	v_mfma_f32_16x16x32_bf16 v[56:59], v[136:139], v[160:163], 0
	v_mfma_f32_16x16x32_bf16 v[44:47], v[120:123], v[164:167], 0
	v_mfma_f32_16x16x32_bf16 v[40:43], v[136:139], v[164:167], 0
	v_mfma_f32_16x16x32_bf16 v[28:31], v[120:123], v[176:179], 0
	v_mfma_f32_16x16x32_bf16 v[24:27], v[136:139], v[176:179], 0
	v_mfma_f32_16x16x32_bf16 v[12:15], v[120:123], v[180:183], 0
	v_mfma_f32_16x16x32_bf16 v[8:11], v[136:139], v[180:183], 0
	v_mfma_f32_16x16x32_bf16 v[60:63], v[128:131], v[168:171], v[60:63]
	v_mfma_f32_16x16x32_bf16 v[56:59], v[140:143], v[168:171], v[56:59]
	v_mfma_f32_16x16x32_bf16 v[44:47], v[128:131], v[172:175], v[44:47]
	v_mfma_f32_16x16x32_bf16 v[40:43], v[140:143], v[172:175], v[40:43]
	v_mfma_f32_16x16x32_bf16 v[28:31], v[128:131], v[184:187], v[28:31]
	v_mfma_f32_16x16x32_bf16 v[24:27], v[140:143], v[184:187], v[24:27]
	v_mfma_f32_16x16x32_bf16 v[12:15], v[128:131], v[188:191], v[12:15]
	v_mfma_f32_16x16x32_bf16 v[8:11], v[140:143], v[188:191], v[8:11]
	s_setprio 0
	s_setprio 1
	v_mfma_f32_16x16x32_bf16 v[52:55], v[144:147], v[160:163], 0
	v_mfma_f32_16x16x32_bf16 v[48:51], v[152:155], v[160:163], 0
	v_mfma_f32_16x16x32_bf16 v[36:39], v[144:147], v[164:167], 0
	v_mfma_f32_16x16x32_bf16 v[32:35], v[152:155], v[164:167], 0
	v_mfma_f32_16x16x32_bf16 v[20:23], v[144:147], v[176:179], 0
	v_mfma_f32_16x16x32_bf16 v[16:19], v[152:155], v[176:179], 0
	v_mfma_f32_16x16x32_bf16 v[4:7], v[144:147], v[180:183], 0
	v_mfma_f32_16x16x32_bf16 v[0:3], v[152:155], v[180:183], 0
	v_mfma_f32_16x16x32_bf16 v[52:55], v[148:151], v[168:171], v[52:55]
	v_mfma_f32_16x16x32_bf16 v[48:51], v[156:159], v[168:171], v[48:51]
	v_mfma_f32_16x16x32_bf16 v[36:39], v[148:151], v[172:175], v[36:39]
	v_mfma_f32_16x16x32_bf16 v[32:35], v[156:159], v[172:175], v[32:35]
	v_mfma_f32_16x16x32_bf16 v[20:23], v[148:151], v[184:187], v[20:23]
	v_mfma_f32_16x16x32_bf16 v[16:19], v[156:159], v[184:187], v[16:19]
	v_mfma_f32_16x16x32_bf16 v[4:7], v[148:151], v[188:191], v[4:7]
	v_mfma_f32_16x16x32_bf16 v[0:3], v[156:159], v[188:191], v[0:3]
	s_setprio 0
	s_barrier
	s_add_i32 s67, 0, 0x18000
	s_add_i32 s68, 0, 0x1c000
	ds_read_b128 v[120:123], v245 offset:32768
	ds_read_b128 v[128:131], v246 offset:32768
	ds_read_b128 v[136:139], v230
	ds_read_b128 v[140:143], v231
	ds_read_b128 v[144:147], v245 offset:49152
	ds_read_b128 v[148:151], v246 offset:49152
	ds_read_b128 v[152:155], v232
	ds_read_b128 v[156:159], v233
	s_add_u32 s42, s42, 0xb0000
	s_addc_u32 s43, s43, 0
	s_mov_b32 m0, s46
	ds_read_b128 v[160:163], v228 offset:32768
	ds_read_b128 v[164:167], v228 offset:34816
	ds_read_b128 v[168:171], v229 offset:32768
	ds_read_b128 v[172:175], v229 offset:34816
	ds_read_b128 v[176:179], v228 offset:36864
	ds_read_b128 v[180:183], v228 offset:38912
	ds_read_b128 v[184:187], v229 offset:36864
	ds_read_b128 v[188:191], v229 offset:38912
	global_load_lds_dwordx4 v192, s[42:43]
	s_mov_b32 m0, s47
	s_nop 0
	global_load_lds_dwordx4 v196, s[42:43]
	s_waitcnt vmcnt(8)
	s_waitcnt lgkmcnt(0)
	s_barrier
	s_setprio 1
	s_waitcnt lgkmcnt(0)
	v_mfma_f32_16x16x32_bf16 v[132:135], v[120:123], v[160:163], v[132:135]
	v_mfma_f32_16x16x32_bf16 v[124:127], v[136:139], v[160:163], v[124:127]
	v_mfma_f32_16x16x32_bf16 v[108:111], v[120:123], v[164:167], v[108:111]
	v_mfma_f32_16x16x32_bf16 v[104:107], v[136:139], v[164:167], v[104:107]
	v_mfma_f32_16x16x32_bf16 v[92:95], v[120:123], v[176:179], v[92:95]
	v_mfma_f32_16x16x32_bf16 v[88:91], v[136:139], v[176:179], v[88:91]
	v_mfma_f32_16x16x32_bf16 v[76:79], v[120:123], v[180:183], v[76:79]
	v_mfma_f32_16x16x32_bf16 v[72:75], v[136:139], v[180:183], v[72:75]
	v_mfma_f32_16x16x32_bf16 v[132:135], v[128:131], v[168:171], v[132:135]
	v_mfma_f32_16x16x32_bf16 v[124:127], v[140:143], v[168:171], v[124:127]
	v_mfma_f32_16x16x32_bf16 v[108:111], v[128:131], v[172:175], v[108:111]
	v_mfma_f32_16x16x32_bf16 v[104:107], v[140:143], v[172:175], v[104:107]
	v_mfma_f32_16x16x32_bf16 v[92:95], v[128:131], v[184:187], v[92:95]
	v_mfma_f32_16x16x32_bf16 v[88:91], v[140:143], v[184:187], v[88:91]
	v_mfma_f32_16x16x32_bf16 v[76:79], v[128:131], v[188:191], v[76:79]
	v_mfma_f32_16x16x32_bf16 v[72:75], v[140:143], v[188:191], v[72:75]
	s_setprio 0
	s_setprio 1
	v_mfma_f32_16x16x32_bf16 v[116:119], v[144:147], v[160:163], v[116:119]
	v_mfma_f32_16x16x32_bf16 v[112:115], v[152:155], v[160:163], v[112:115]
	v_mfma_f32_16x16x32_bf16 v[100:103], v[144:147], v[164:167], v[100:103]
	v_mfma_f32_16x16x32_bf16 v[96:99], v[152:155], v[164:167], v[96:99]
	v_mfma_f32_16x16x32_bf16 v[84:87], v[144:147], v[176:179], v[84:87]
	v_mfma_f32_16x16x32_bf16 v[80:83], v[152:155], v[176:179], v[80:83]
	v_mfma_f32_16x16x32_bf16 v[68:71], v[144:147], v[180:183], v[68:71]
	v_mfma_f32_16x16x32_bf16 v[64:67], v[152:155], v[180:183], v[64:67]
	v_mfma_f32_16x16x32_bf16 v[116:119], v[148:151], v[168:171], v[116:119]
	v_mfma_f32_16x16x32_bf16 v[112:115], v[156:159], v[168:171], v[112:115]
	v_mfma_f32_16x16x32_bf16 v[100:103], v[148:151], v[172:175], v[100:103]
	v_mfma_f32_16x16x32_bf16 v[96:99], v[156:159], v[172:175], v[96:99]
	v_mfma_f32_16x16x32_bf16 v[84:87], v[148:151], v[184:187], v[84:87]
	v_mfma_f32_16x16x32_bf16 v[80:83], v[156:159], v[184:187], v[80:83]
	v_mfma_f32_16x16x32_bf16 v[68:71], v[148:151], v[188:191], v[68:71]
	v_mfma_f32_16x16x32_bf16 v[64:67], v[156:159], v[188:191], v[64:67]
	s_setprio 0
	s_barrier
	s_add_i32 s42, s67, s39
	s_add_i32 m0, s42, 0xffffff80
	ds_read_b128 v[160:163], v228 offset:49152
	ds_read_b128 v[164:167], v228 offset:51200
	ds_read_b128 v[168:171], v229 offset:49152
	ds_read_b128 v[172:175], v229 offset:51200
	ds_read_b128 v[176:179], v228 offset:53248
	ds_read_b128 v[180:183], v228 offset:55296
	ds_read_b128 v[184:187], v229 offset:53248
	ds_read_b128 v[188:191], v229 offset:55296
	global_load_lds_dwordx4 v194, s[40:41] offset:128
	s_add_i32 m0, s42, 0x2000
	s_add_u32 s40, s40, 0xb0080
	v_lshl_add_u64 v[210:211], v[212:213], 0, s[8:9]
	s_addc_u32 s41, s41, 0
	s_add_i32 s42, s68, s39
	global_load_lds_dwordx4 v[210:211], off
	s_mov_b32 m0, s42
	s_nop 0
	global_load_lds_dwordx4 v194, s[40:41]
	s_add_i32 m0, s42, 0x2000
	s_nop 0
	global_load_lds_dwordx4 v198, s[40:41]
	v_lshl_add_u64 v[210:211], v[214:215], 0, s[8:9]
	s_mov_b32 m0, s51
	s_nop 0
	global_load_lds_dwordx4 v[210:211], off
	v_lshl_add_u64 v[210:211], v[234:235], 0, s[8:9]
	s_mov_b32 m0, s52
	s_nop 0
	global_load_lds_dwordx4 v[210:211], off
	s_waitcnt vmcnt(8)
	s_waitcnt lgkmcnt(0)
	s_barrier
	s_setprio 1
	s_waitcnt lgkmcnt(0)
	v_mfma_f32_16x16x32_bf16 v[60:63], v[120:123], v[160:163], v[60:63]
	v_mfma_f32_16x16x32_bf16 v[56:59], v[136:139], v[160:163], v[56:59]
	v_mfma_f32_16x16x32_bf16 v[44:47], v[120:123], v[164:167], v[44:47]
	v_mfma_f32_16x16x32_bf16 v[40:43], v[136:139], v[164:167], v[40:43]
	v_mfma_f32_16x16x32_bf16 v[28:31], v[120:123], v[176:179], v[28:31]
	v_mfma_f32_16x16x32_bf16 v[24:27], v[136:139], v[176:179], v[24:27]
	v_mfma_f32_16x16x32_bf16 v[12:15], v[120:123], v[180:183], v[12:15]
	v_mfma_f32_16x16x32_bf16 v[8:11], v[136:139], v[180:183], v[8:11]
	v_mfma_f32_16x16x32_bf16 v[60:63], v[128:131], v[168:171], v[60:63]
	v_mfma_f32_16x16x32_bf16 v[56:59], v[140:143], v[168:171], v[56:59]
	v_mfma_f32_16x16x32_bf16 v[44:47], v[128:131], v[172:175], v[44:47]
	v_mfma_f32_16x16x32_bf16 v[40:43], v[140:143], v[172:175], v[40:43]
	v_mfma_f32_16x16x32_bf16 v[28:31], v[128:131], v[184:187], v[28:31]
	v_mfma_f32_16x16x32_bf16 v[24:27], v[140:143], v[184:187], v[24:27]
	v_mfma_f32_16x16x32_bf16 v[12:15], v[128:131], v[188:191], v[12:15]
	v_mfma_f32_16x16x32_bf16 v[8:11], v[140:143], v[188:191], v[8:11]
	s_setprio 0
	s_setprio 1
	v_mfma_f32_16x16x32_bf16 v[52:55], v[144:147], v[160:163], v[52:55]
	v_mfma_f32_16x16x32_bf16 v[48:51], v[152:155], v[160:163], v[48:51]
	v_mfma_f32_16x16x32_bf16 v[36:39], v[144:147], v[164:167], v[36:39]
	v_mfma_f32_16x16x32_bf16 v[32:35], v[152:155], v[164:167], v[32:35]
	v_mfma_f32_16x16x32_bf16 v[20:23], v[144:147], v[176:179], v[20:23]
	v_mfma_f32_16x16x32_bf16 v[16:19], v[152:155], v[176:179], v[16:19]
	v_mfma_f32_16x16x32_bf16 v[4:7], v[144:147], v[180:183], v[4:7]
	v_mfma_f32_16x16x32_bf16 v[0:3], v[152:155], v[180:183], v[0:3]
	v_mfma_f32_16x16x32_bf16 v[52:55], v[148:151], v[168:171], v[52:55]
	v_mfma_f32_16x16x32_bf16 v[48:51], v[156:159], v[168:171], v[48:51]
	v_mfma_f32_16x16x32_bf16 v[36:39], v[148:151], v[172:175], v[36:39]
	v_mfma_f32_16x16x32_bf16 v[32:35], v[156:159], v[172:175], v[32:35]
	v_mfma_f32_16x16x32_bf16 v[20:23], v[148:151], v[184:187], v[20:23]
	v_mfma_f32_16x16x32_bf16 v[16:19], v[156:159], v[184:187], v[16:19]
	v_mfma_f32_16x16x32_bf16 v[4:7], v[148:151], v[188:191], v[4:7]
	v_mfma_f32_16x16x32_bf16 v[0:3], v[156:159], v[188:191], v[0:3]
	s_setprio 0
	s_barrier
	s_add_i32 s66, s66, 2
	s_add_u32 s4, s4, 0x100
	s_addc_u32 s5, s5, 0
	s_add_u32 s64, s64, 0x100
	s_addc_u32 s65, s65, 0
	s_cmp_gt_u32 s66, 41
	s_cbranch_scc0 .LBB0_1827

	.amdhsa_kernel _Z6mk_fwd4Args
		.amdhsa_group_segment_fixed_size 0
		.amdhsa_private_segment_fixed_size 0
		.amdhsa_kernarg_size 472
		.amdhsa_user_sgpr_count 2
		.amdhsa_user_sgpr_dispatch_ptr 0
		.amdhsa_user_sgpr_queue_ptr 0
		.amdhsa_user_sgpr_kernarg_segment_ptr 1
		.amdhsa_user_sgpr_dispatch_id 0
		.amdhsa_user_sgpr_kernarg_preload_length 0
		.amdhsa_user_sgpr_kernarg_preload_offset 0
		.amdhsa_user_sgpr_private_segment_size 0
		.amdhsa_uses_dynamic_stack 0
		.amdhsa_enable_private_segment 0
		.amdhsa_system_sgpr_workgroup_id_x 1
		.amdhsa_system_sgpr_workgroup_id_y 0
		.amdhsa_system_sgpr_workgroup_id_z 0
		.amdhsa_system_sgpr_workgroup_info 0
		.amdhsa_system_vgpr_workitem_id 0
		.amdhsa_next_free_vgpr 247
		.amdhsa_next_free_sgpr 102
		.amdhsa_accum_offset 248
		.amdhsa_reserve_vcc 1
		.amdhsa_float_round_mode_32 0
		.amdhsa_float_round_mode_16_64 0
		.amdhsa_float_denorm_mode_32 3
		.amdhsa_float_denorm_mode_16_64 3
		.amdhsa_dx10_clamp 1
		.amdhsa_ieee_mode 1
		.amdhsa_fp16_overflow 0
		.amdhsa_tg_split 0
		.amdhsa_exception_fp_ieee_invalid_op 0
		.amdhsa_exception_fp_denorm_src 0
		.amdhsa_exception_fp_ieee_div_zero 0
		.amdhsa_exception_fp_ieee_overflow 0
		.amdhsa_exception_fp_ieee_underflow 0
		.amdhsa_exception_fp_ieee_inexact 0
		.amdhsa_exception_int_div_zero 0
	.end_amdhsa_kernel

amdhsa.kernels:
  - .agpr_count:     0
    .args:
      - .offset:         0
        .size:           216
        .value_kind:     by_value
      - .offset:         216
        .size:           4
        .value_kind:     hidden_block_count_x
      - .offset:         220
        .size:           4
        .value_kind:     hidden_block_count_y
      - .offset:         224
        .size:           4
        .value_kind:     hidden_block_count_z
      - .offset:         228
        .size:           2
        .value_kind:     hidden_group_size_x
      - .offset:         230
        .size:           2
        .value_kind:     hidden_group_size_y
      - .offset:         232
        .size:           2
        .value_kind:     hidden_group_size_z
      - .offset:         234
        .size:           2
        .value_kind:     hidden_remainder_x
      - .offset:         236
        .size:           2
        .value_kind:     hidden_remainder_y
      - .offset:         238
        .size:           2
        .value_kind:     hidden_remainder_z
      - .offset:         256
        .size:           8
        .value_kind:     hidden_global_offset_x
      - .offset:         264
        .size:           8
        .value_kind:     hidden_global_offset_y
      - .offset:         272
        .size:           8
        .value_kind:     hidden_global_offset_z
      - .offset:         280
        .size:           2
        .value_kind:     hidden_grid_dims
      - .offset:         336
        .size:           4
        .value_kind:     hidden_dynamic_lds_size
    .group_segment_fixed_size: 0
    .kernarg_segment_align: 8
    .kernarg_segment_size: 472
    .language:       OpenCL C
    .language_version:
      - 2
      - 0
    .max_flat_workgroup_size: 512
    .name:           _Z6mk_fwd4Args
    .private_segment_fixed_size: 0
    .sgpr_count:     108
    .sgpr_spill_count: 66
    .symbol:         _Z6mk_fwd4Args.kd
    .uniform_work_group_size: 1
    .uses_dynamic_stack: false
    .vgpr_count:     247
    .vgpr_spill_count: 0
    .wavefront_size: 64
